# phase-0 weight conversion: gain loads of an item prefetched together (v176-205) and W loads hoisted two elements ahead (3 in flight), exact counted waits
# speedup vs baseline: 1.0053x; 1.0003x over previous
.LBB0_117:
	s_movk_i32 s0, 0xaff
	v_cmp_lt_i32_e32 vcc, s0, v6
	s_and_saveexec_b64 s[0:1], vcc
	s_xor_b64 s[22:23], exec, s[0:1]
	s_cbranch_execz .LBB0_267
	s_movk_i32 s0, 0x15ff
	v_cmp_lt_u32_e32 vcc, s0, v6
	s_and_saveexec_b64 s[0:1], vcc
	s_xor_b64 s[24:25], exec, s[0:1]
	s_cbranch_execz .LBB0_200
	s_movk_i32 s0, 0x1b7f
	v_cmp_lt_u32_e32 vcc, s0, v6
	s_and_saveexec_b64 s[0:1], vcc
	s_xor_b64 s[26:27], exec, s[0:1]
	s_cbranch_execz .LBB0_197
	s_movk_i32 s0, 0x20ff
	v_cmp_lt_u32_e32 vcc, s0, v6
	s_and_saveexec_b64 s[0:1], vcc
	s_xor_b64 s[28:29], exec, s[0:1]
	s_cbranch_execz .LBB0_194
	s_movk_i32 s0, 0x283f
	v_cmp_lt_u32_e32 vcc, s0, v6
	s_and_saveexec_b64 s[0:1], vcc
	s_xor_b64 s[0:1], exec, s[0:1]
	s_cbranch_execz .LBB0_127
	s_movk_i32 s4, 0x2a3f
	v_and_b32_e32 v3, 0x3e0, v42
	v_cmp_lt_u32_e32 vcc, s4, v6
	v_lshlrev_b32_e32 v2, 2, v3
	v_or_b32_e32 v45, v3, v113
	v_or_b32_e32 v44, v3, v115
	v_or_b32_e32 v5, v3, v116
	v_or_b32_e32 v4, v3, v117
	s_and_saveexec_b64 s[4:5], vcc
	s_xor_b64 s[4:5], exec, s[4:5]
	s_cbranch_execz .LBB0_124
	v_and_b32_e32 v46, 0x1ffc0, v118
	v_mov_b32_e32 v3, v0
	v_or_b32_e32 v47, v46, v8
	v_lshl_add_u64 v[2:3], v[28:29], 0, v[2:3]
	v_lshlrev_b32_e32 v48, 12, v47
	v_mov_b32_e32 v49, v0
	v_lshl_add_u64 v[48:49], v[2:3], 0, v[48:49]
	global_load_dword v47, v[48:49], off
	v_or_b32_e32 v48, v46, v58
	v_lshlrev_b32_e32 v48, 12, v48
	v_mov_b32_e32 v49, v0
	v_lshl_add_u64 v[48:49], v[2:3], 0, v[48:49]
	global_load_dword v48, v[48:49], off
	v_add_u32_e32 v50, v7, v13
	v_mov_b32_e32 v49, v0
	v_lshlrev_b32_e32 v128, 11, v45
	v_mov_b32_e32 v129, v0
	v_lshlrev_b32_e32 v44, 11, v44
	v_lshlrev_b32_e32 v4, 11, v4
	v_or_b32_e32 v170, v46, v60
	v_lshlrev_b32_e32 v168, 12, v170
	v_mov_b32_e32 v169, v0
	v_lshl_add_u64 v[168:169], v[2:3], 0, v[168:169]
	global_load_dword v170, v[168:169], off
	v_or_b32_e32 v168, v46, v62
	v_lshlrev_b32_e32 v168, 12, v168
	v_mov_b32_e32 v169, v0
	v_lshl_add_u64 v[168:169], v[2:3], 0, v[168:169]
	global_load_dword v168, v[168:169], off
	v_or_b32_e32 v210, v46, v64
	v_lshlrev_b32_e32 v208, 12, v210
	v_mov_b32_e32 v209, v0
	v_lshl_add_u64 v[208:209], v[2:3], 0, v[208:209]
	global_load_dword v210, v[208:209], off
	v_or_b32_e32 v208, v46, v66
	v_lshlrev_b32_e32 v208, 12, v208
	v_mov_b32_e32 v209, v0
	v_lshl_add_u64 v[208:209], v[2:3], 0, v[208:209]
	global_load_dword v208, v[208:209], off
	s_waitcnt vmcnt(4)
	ds_write2_b32 v50, v47, v48 offset1:66
	v_mov_b32_e32 v49, v0
	v_or_b32_e32 v162, v46, v68
	v_lshlrev_b32_e32 v160, 12, v162
	v_mov_b32_e32 v161, v0
	v_lshl_add_u64 v[160:161], v[2:3], 0, v[160:161]
	global_load_dword v162, v[160:161], off
	v_or_b32_e32 v160, v46, v70
	v_lshlrev_b32_e32 v160, 12, v160
	v_mov_b32_e32 v161, v0
	v_lshl_add_u64 v[160:161], v[2:3], 0, v[160:161]
	global_load_dword v160, v[160:161], off
	s_waitcnt vmcnt(4)
	ds_write2_b32 v50, v170, v168 offset0:132 offset1:198
	v_add_u32_e32 v49, 0x400, v50
	v_add_u32_e32 v50, v7, v69
	v_or_b32_e32 v170, v46, v72
	v_lshlrev_b32_e32 v168, 12, v170
	v_mov_b32_e32 v169, v0
	v_lshl_add_u64 v[168:169], v[2:3], 0, v[168:169]
	global_load_dword v170, v[168:169], off
	v_or_b32_e32 v168, v46, v74
	v_lshlrev_b32_e32 v168, 12, v168
	v_mov_b32_e32 v169, v0
	v_lshl_add_u64 v[168:169], v[2:3], 0, v[168:169]
	global_load_dword v168, v[168:169], off
	s_waitcnt vmcnt(4)
	ds_write2_b32 v49, v210, v208 offset0:8 offset1:74
	v_mov_b32_e32 v49, v0
	v_or_b32_e32 v210, v46, v76
	v_lshlrev_b32_e32 v208, 12, v210
	v_mov_b32_e32 v209, v0
	v_lshl_add_u64 v[208:209], v[2:3], 0, v[208:209]
	global_load_dword v210, v[208:209], off
	v_or_b32_e32 v208, v46, v78
	v_lshlrev_b32_e32 v208, 12, v208
	v_mov_b32_e32 v209, v0
	v_lshl_add_u64 v[208:209], v[2:3], 0, v[208:209]
	global_load_dword v208, v[208:209], off
	s_waitcnt vmcnt(4)
	ds_write2_b32 v50, v162, v160 offset1:66
	v_mov_b32_e32 v49, v0
	v_or_b32_e32 v162, v46, v80
	v_lshlrev_b32_e32 v160, 12, v162
	v_mov_b32_e32 v161, v0
	v_lshl_add_u64 v[160:161], v[2:3], 0, v[160:161]
	global_load_dword v162, v[160:161], off
	v_or_b32_e32 v160, v46, v82
	v_lshlrev_b32_e32 v160, 12, v160
	v_mov_b32_e32 v161, v0
	v_lshl_add_u64 v[160:161], v[2:3], 0, v[160:161]
	global_load_dword v160, v[160:161], off
	s_waitcnt vmcnt(4)
	ds_write2_b32 v50, v170, v168 offset0:132 offset1:198
	v_add_u32_e32 v49, 0x400, v50
	v_add_u32_e32 v50, v7, v81
	v_or_b32_e32 v170, v46, v84
	v_lshlrev_b32_e32 v168, 12, v170
	v_mov_b32_e32 v169, v0
	v_lshl_add_u64 v[168:169], v[2:3], 0, v[168:169]
	global_load_dword v170, v[168:169], off
	v_or_b32_e32 v168, v46, v86
	v_lshlrev_b32_e32 v168, 12, v168
	v_mov_b32_e32 v169, v0
	v_lshl_add_u64 v[168:169], v[2:3], 0, v[168:169]
	global_load_dword v168, v[168:169], off
	s_waitcnt vmcnt(4)
	ds_write2_b32 v49, v210, v208 offset0:8 offset1:74
	v_mov_b32_e32 v49, v0
	v_or_b32_e32 v210, v46, v88
	v_lshlrev_b32_e32 v208, 12, v210
	v_mov_b32_e32 v209, v0
	v_lshl_add_u64 v[208:209], v[2:3], 0, v[208:209]
	global_load_dword v210, v[208:209], off
	v_or_b32_e32 v208, v46, v90
	v_lshlrev_b32_e32 v208, 12, v208
	v_mov_b32_e32 v209, v0
	v_lshl_add_u64 v[208:209], v[2:3], 0, v[208:209]
	global_load_dword v208, v[208:209], off
	s_waitcnt vmcnt(4)
	ds_write2_b32 v50, v162, v160 offset1:66
	v_mov_b32_e32 v49, v0
	v_or_b32_e32 v162, v46, v92
	v_lshlrev_b32_e32 v160, 12, v162
	v_mov_b32_e32 v161, v0
	v_lshl_add_u64 v[160:161], v[2:3], 0, v[160:161]
	global_load_dword v162, v[160:161], off
	v_or_b32_e32 v160, v46, v94
	v_lshlrev_b32_e32 v160, 12, v160
	v_mov_b32_e32 v161, v0
	v_lshl_add_u64 v[160:161], v[2:3], 0, v[160:161]
	global_load_dword v160, v[160:161], off
	s_waitcnt vmcnt(4)
	ds_write2_b32 v50, v170, v168 offset0:132 offset1:198
	v_add_u32_e32 v49, 0x400, v50
	v_add_u32_e32 v50, v7, v93
	v_or_b32_e32 v170, v46, v96
	v_lshlrev_b32_e32 v168, 12, v170
	v_mov_b32_e32 v169, v0
	v_lshl_add_u64 v[168:169], v[2:3], 0, v[168:169]
	global_load_dword v170, v[168:169], off
	v_or_b32_e32 v168, v46, v98
	v_lshlrev_b32_e32 v168, 12, v168
	v_mov_b32_e32 v169, v0
	v_lshl_add_u64 v[168:169], v[2:3], 0, v[168:169]
	global_load_dword v168, v[168:169], off
	s_waitcnt vmcnt(4)
	ds_write2_b32 v49, v210, v208 offset0:8 offset1:74
	v_mov_b32_e32 v49, v0
	v_or_b32_e32 v210, v46, v100
	v_lshlrev_b32_e32 v208, 12, v210
	v_mov_b32_e32 v209, v0
	v_lshl_add_u64 v[208:209], v[2:3], 0, v[208:209]
	global_load_dword v210, v[208:209], off
	v_or_b32_e32 v208, v46, v102
	v_lshlrev_b32_e32 v208, 12, v208
	v_mov_b32_e32 v209, v0
	v_lshl_add_u64 v[208:209], v[2:3], 0, v[208:209]
	global_load_dword v208, v[208:209], off
	s_waitcnt vmcnt(4)
	ds_write2_b32 v50, v162, v160 offset1:66
	v_mov_b32_e32 v49, v0
	v_or_b32_e32 v162, v46, v104
	v_lshlrev_b32_e32 v160, 12, v162
	v_mov_b32_e32 v161, v0
	v_lshl_add_u64 v[160:161], v[2:3], 0, v[160:161]
	global_load_dword v162, v[160:161], off
	v_or_b32_e32 v160, v46, v106
	v_lshlrev_b32_e32 v160, 12, v160
	v_mov_b32_e32 v161, v0
	v_lshl_add_u64 v[160:161], v[2:3], 0, v[160:161]
	global_load_dword v160, v[160:161], off
	s_waitcnt vmcnt(4)
	ds_write2_b32 v50, v170, v168 offset0:132 offset1:198
	v_add_u32_e32 v49, 0x400, v50
	v_add_u32_e32 v50, v7, v105
	v_or_b32_e32 v170, v46, v107
	v_lshlrev_b32_e32 v168, 12, v170
	v_mov_b32_e32 v169, v0
	v_lshl_add_u64 v[168:169], v[2:3], 0, v[168:169]
	global_load_dword v170, v[168:169], off
	v_or_b32_e32 v168, v46, v108
	v_lshlrev_b32_e32 v168, 12, v168
	v_mov_b32_e32 v169, v0
	v_lshl_add_u64 v[168:169], v[2:3], 0, v[168:169]
	global_load_dword v168, v[168:169], off
	s_waitcnt vmcnt(4)
	ds_write2_b32 v49, v210, v208 offset0:8 offset1:74
	v_mov_b32_e32 v49, v0
	v_or_b32_e32 v210, v46, v109
	v_lshlrev_b32_e32 v208, 12, v210
	v_mov_b32_e32 v209, v0
	v_lshl_add_u64 v[208:209], v[2:3], 0, v[208:209]
	global_load_dword v210, v[208:209], off
	v_or_b32_e32 v208, v46, v110
	v_lshlrev_b32_e32 v208, 12, v208
	v_mov_b32_e32 v209, v0
	v_lshl_add_u64 v[208:209], v[2:3], 0, v[208:209]
	global_load_dword v208, v[208:209], off
	s_waitcnt vmcnt(4)
	ds_write2_b32 v50, v162, v160 offset1:66
	v_mov_b32_e32 v49, v0
	v_or_b32_e32 v164, v46, v111
	v_lshlrev_b32_e32 v162, 12, v164
	v_mov_b32_e32 v163, v0
	v_lshl_add_u64 v[162:163], v[2:3], 0, v[162:163]
	global_load_dword v164, v[162:163], off
	v_or_b32_e32 v162, v46, v112
	v_lshlrev_b32_e32 v162, 12, v162
	v_mov_b32_e32 v163, v0
	v_lshl_add_u64 v[160:161], v[2:3], 0, v[162:163]
	global_load_dword v160, v[160:161], off
	s_waitcnt vmcnt(4)
	ds_write2_b32 v50, v170, v168 offset0:132 offset1:198
	v_add_u32_e32 v50, 0x400, v50
	v_mov_b32_e32 v49, v0
	s_waitcnt vmcnt(2)
	ds_write2_b32 v50, v210, v208 offset0:8 offset1:74
	v_mov_b32_e32 v3, v0
	s_waitcnt vmcnt(0)
	ds_write2_b32 v50, v164, v160 offset0:140 offset1:206
	s_waitcnt lgkmcnt(0)
	ds_read2_b32 v[50:51], v114 offset0:33 offset1:41
	ds_read2_b32 v[52:53], v114 offset1:8
	ds_read2_b32 v[54:55], v114 offset0:66 offset1:74
	ds_read2_b32 v[56:57], v114 offset0:99 offset1:107
	v_lshlrev_b32_e32 v2, 1, v46
	ds_read2_b32 v[120:121], v114 offset0:132 offset1:140
	ds_read2_b32 v[122:123], v114 offset0:165 offset1:173
	s_waitcnt lgkmcnt(5)
	v_bfe_u32 v47, v50, 16, 1
	s_waitcnt lgkmcnt(4)
	v_bfe_u32 v46, v52, 16, 1
	v_add3_u32 v46, v52, v46, s51
	v_lshrrev_b32_e32 v46, 16, v46
	v_add3_u32 v47, v50, v47, s51
	v_and_or_b32 v46, v47, s33, v46
	s_waitcnt lgkmcnt(3)
	v_bfe_u32 v47, v54, 16, 1
	v_add3_u32 v47, v54, v47, s51
	s_waitcnt lgkmcnt(2)
	v_bfe_u32 v48, v56, 16, 1
	v_lshrrev_b32_e32 v47, 16, v47
	v_add3_u32 v48, v56, v48, s51
	ds_read2_b32 v[124:125], v114 offset0:198 offset1:206
	ds_read2_b32 v[126:127], v114 offset0:231 offset1:239
	v_and_or_b32 v47, v48, s33, v47
	s_waitcnt lgkmcnt(3)
	v_bfe_u32 v48, v120, 16, 1
	v_add3_u32 v48, v120, v48, s51
	s_waitcnt lgkmcnt(2)
	v_bfe_u32 v49, v122, 16, 1
	v_lshrrev_b32_e32 v48, 16, v48
	v_add3_u32 v49, v122, v49, s51
	v_and_or_b32 v48, v49, s33, v48
	s_waitcnt lgkmcnt(1)
	v_bfe_u32 v49, v124, 16, 1
	v_add3_u32 v49, v124, v49, s51
	s_waitcnt lgkmcnt(0)
	v_bfe_u32 v50, v126, 16, 1
	v_lshl_add_u64 v[2:3], v[14:15], 0, v[2:3]
	v_lshrrev_b32_e32 v49, 16, v49
	v_add3_u32 v50, v126, v50, s51
	v_and_or_b32 v49, v50, s33, v49
	v_lshl_add_u64 v[128:129], v[2:3], 0, v[128:129]
	v_bfe_u32 v45, v53, 16, 1
	global_store_dwordx4 v[128:129], v[46:49], off
	v_add3_u32 v45, v53, v45, s51
	v_lshrrev_b32_e32 v45, 16, v45
	v_bfe_u32 v46, v51, 16, 1
	v_add3_u32 v46, v51, v46, s51
	v_and_or_b32 v46, v46, s33, v45
	v_bfe_u32 v45, v55, 16, 1
	v_add3_u32 v45, v55, v45, s51
	v_bfe_u32 v47, v57, 16, 1
	v_lshrrev_b32_e32 v45, 16, v45
	v_add3_u32 v47, v57, v47, s51
	v_and_or_b32 v47, v47, s33, v45
	v_bfe_u32 v45, v121, 16, 1
	v_add3_u32 v45, v121, v45, s51
	v_bfe_u32 v48, v123, 16, 1
	v_lshrrev_b32_e32 v45, 16, v45
	v_add3_u32 v48, v123, v48, s51
	v_and_or_b32 v48, v48, s33, v45
	v_bfe_u32 v45, v125, 16, 1
	v_add3_u32 v45, v125, v45, s51
	v_bfe_u32 v49, v127, 16, 1
	v_lshrrev_b32_e32 v45, 16, v45
	v_add3_u32 v49, v127, v49, s51
	v_and_or_b32 v49, v49, s33, v45
	v_mov_b32_e32 v45, v0
	v_lshl_add_u64 v[44:45], v[2:3], 0, v[44:45]
	global_store_dwordx4 v[44:45], v[46:49], off
	ds_read2_b32 v[48:49], v114 offset0:49 offset1:57
	ds_read2_b32 v[50:51], v114 offset0:16 offset1:24
	ds_read2_b32 v[52:53], v114 offset0:82 offset1:90
	ds_read2_b32 v[54:55], v114 offset0:115 offset1:123
	ds_read2_b32 v[56:57], v114 offset0:148 offset1:156
	ds_read2_b32 v[120:121], v114 offset0:181 offset1:189
	ds_read2_b32 v[122:123], v114 offset0:214 offset1:222
	ds_read2_b32 v[124:125], v114 offset0:247 offset1:255
	s_waitcnt lgkmcnt(7)
	v_bfe_u32 v45, v48, 16, 1
	s_waitcnt lgkmcnt(6)
	v_bfe_u32 v44, v50, 16, 1
	v_add3_u32 v44, v50, v44, s51
	v_lshrrev_b32_e32 v44, 16, v44
	v_add3_u32 v45, v48, v45, s51
	v_and_or_b32 v44, v45, s33, v44
	s_waitcnt lgkmcnt(5)
	v_bfe_u32 v45, v52, 16, 1
	v_add3_u32 v45, v52, v45, s51
	s_waitcnt lgkmcnt(4)
	v_bfe_u32 v46, v54, 16, 1
	v_lshrrev_b32_e32 v45, 16, v45
	v_add3_u32 v46, v54, v46, s51
	v_and_or_b32 v45, v46, s33, v45
	s_waitcnt lgkmcnt(3)
	v_bfe_u32 v46, v56, 16, 1
	v_add3_u32 v46, v56, v46, s51
	s_waitcnt lgkmcnt(2)
	v_bfe_u32 v47, v120, 16, 1
	v_lshrrev_b32_e32 v46, 16, v46
	v_add3_u32 v47, v120, v47, s51
	v_and_or_b32 v46, v47, s33, v46
	s_waitcnt lgkmcnt(1)
	v_bfe_u32 v47, v122, 16, 1
	v_add3_u32 v47, v122, v47, s51
	s_waitcnt lgkmcnt(0)
	v_bfe_u32 v48, v124, 16, 1
	v_lshrrev_b32_e32 v47, 16, v47
	v_add3_u32 v48, v124, v48, s51
	v_lshlrev_b32_e32 v126, 11, v5
	v_mov_b32_e32 v127, v0
	v_and_or_b32 v47, v48, s33, v47
	v_lshl_add_u64 v[126:127], v[2:3], 0, v[126:127]
	v_bfe_u32 v5, v51, 16, 1
	global_store_dwordx4 v[126:127], v[44:47], off
	v_add3_u32 v5, v51, v5, s51
	v_lshrrev_b32_e32 v5, 16, v5
	v_bfe_u32 v44, v49, 16, 1
	v_add3_u32 v44, v49, v44, s51
	v_and_or_b32 v44, v44, s33, v5
	v_bfe_u32 v5, v53, 16, 1
	v_add3_u32 v5, v53, v5, s51
	v_bfe_u32 v45, v55, 16, 1
	v_lshrrev_b32_e32 v5, 16, v5
	v_add3_u32 v45, v55, v45, s51
	v_and_or_b32 v45, v45, s33, v5
	v_bfe_u32 v5, v57, 16, 1
	v_add3_u32 v5, v57, v5, s51
	v_bfe_u32 v46, v121, 16, 1
	v_lshrrev_b32_e32 v5, 16, v5
	v_add3_u32 v46, v121, v46, s51
	v_and_or_b32 v46, v46, s33, v5
	v_bfe_u32 v5, v123, 16, 1
	v_add3_u32 v5, v123, v5, s51
	v_bfe_u32 v47, v125, 16, 1
	v_lshrrev_b32_e32 v5, 16, v5
	v_add3_u32 v47, v125, v47, s51
	v_and_or_b32 v47, v47, s33, v5
	v_mov_b32_e32 v5, v0
	v_lshl_add_u64 v[2:3], v[2:3], 0, v[4:5]
	global_store_dwordx4 v[2:3], v[44:47], off
	s_waitcnt lgkmcnt(0)
.LBB0_124:
	s_andn2_saveexec_b64 s[4:5], s[4:5]
	s_cbranch_execz .LBB0_126
	v_add_u32_e32 v3, 0x400, v118
	v_and_b32_e32 v46, 0x1ffc0, v3
	v_mov_b32_e32 v3, v0
	v_or_b32_e32 v47, v46, v8
	v_lshl_add_u64 v[2:3], v[30:31], 0, v[2:3]
	v_lshlrev_b32_e32 v48, 12, v47
	v_mov_b32_e32 v49, v0
	v_lshl_add_u64 v[48:49], v[2:3], 0, v[48:49]
	global_load_dword v47, v[48:49], off
	v_or_b32_e32 v48, v46, v58
	v_lshlrev_b32_e32 v48, 12, v48
	v_mov_b32_e32 v49, v0
	v_lshl_add_u64 v[48:49], v[2:3], 0, v[48:49]
	global_load_dword v48, v[48:49], off
	v_add_u32_e32 v50, v7, v13
	v_mov_b32_e32 v49, v0
	v_lshlrev_b32_e32 v128, 11, v45
	v_mov_b32_e32 v129, v0
	v_lshlrev_b32_e32 v44, 11, v44
	v_lshlrev_b32_e32 v4, 11, v4
	v_or_b32_e32 v210, v46, v60
	v_lshlrev_b32_e32 v208, 12, v210
	v_mov_b32_e32 v209, v0
	v_lshl_add_u64 v[208:209], v[2:3], 0, v[208:209]
	global_load_dword v210, v[208:209], off
	v_or_b32_e32 v208, v46, v62
	v_lshlrev_b32_e32 v208, 12, v208
	v_mov_b32_e32 v209, v0
	v_lshl_add_u64 v[208:209], v[2:3], 0, v[208:209]
	global_load_dword v208, v[208:209], off
	v_or_b32_e32 v162, v46, v64
	v_lshlrev_b32_e32 v160, 12, v162
	v_mov_b32_e32 v161, v0
	v_lshl_add_u64 v[160:161], v[2:3], 0, v[160:161]
	global_load_dword v162, v[160:161], off
	v_or_b32_e32 v160, v46, v66
	v_lshlrev_b32_e32 v160, 12, v160
	v_mov_b32_e32 v161, v0
	v_lshl_add_u64 v[160:161], v[2:3], 0, v[160:161]
	global_load_dword v160, v[160:161], off
	s_waitcnt vmcnt(4)
	ds_write2_b32 v50, v47, v48 offset1:66
	v_mov_b32_e32 v49, v0
	v_or_b32_e32 v170, v46, v68
	v_lshlrev_b32_e32 v168, 12, v170
	v_mov_b32_e32 v169, v0
	v_lshl_add_u64 v[168:169], v[2:3], 0, v[168:169]
	global_load_dword v170, v[168:169], off
	v_or_b32_e32 v168, v46, v70
	v_lshlrev_b32_e32 v168, 12, v168
	v_mov_b32_e32 v169, v0
	v_lshl_add_u64 v[168:169], v[2:3], 0, v[168:169]
	global_load_dword v168, v[168:169], off
	s_waitcnt vmcnt(4)
	ds_write2_b32 v50, v210, v208 offset0:132 offset1:198
	v_add_u32_e32 v49, 0x400, v50
	v_add_u32_e32 v50, v7, v69
	v_or_b32_e32 v210, v46, v72
	v_lshlrev_b32_e32 v208, 12, v210
	v_mov_b32_e32 v209, v0
	v_lshl_add_u64 v[208:209], v[2:3], 0, v[208:209]
	global_load_dword v210, v[208:209], off
	v_or_b32_e32 v208, v46, v74
	v_lshlrev_b32_e32 v208, 12, v208
	v_mov_b32_e32 v209, v0
	v_lshl_add_u64 v[208:209], v[2:3], 0, v[208:209]
	global_load_dword v208, v[208:209], off
	s_waitcnt vmcnt(4)
	ds_write2_b32 v49, v162, v160 offset0:8 offset1:74
	v_mov_b32_e32 v49, v0
	v_or_b32_e32 v162, v46, v76
	v_lshlrev_b32_e32 v160, 12, v162
	v_mov_b32_e32 v161, v0
	v_lshl_add_u64 v[160:161], v[2:3], 0, v[160:161]
	global_load_dword v162, v[160:161], off
	v_or_b32_e32 v160, v46, v78
	v_lshlrev_b32_e32 v160, 12, v160
	v_mov_b32_e32 v161, v0
	v_lshl_add_u64 v[160:161], v[2:3], 0, v[160:161]
	global_load_dword v160, v[160:161], off
	s_waitcnt vmcnt(4)
	ds_write2_b32 v50, v170, v168 offset1:66
	v_mov_b32_e32 v49, v0
	v_or_b32_e32 v170, v46, v80
	v_lshlrev_b32_e32 v168, 12, v170
	v_mov_b32_e32 v169, v0
	v_lshl_add_u64 v[168:169], v[2:3], 0, v[168:169]
	global_load_dword v170, v[168:169], off
	v_or_b32_e32 v168, v46, v82
	v_lshlrev_b32_e32 v168, 12, v168
	v_mov_b32_e32 v169, v0
	v_lshl_add_u64 v[168:169], v[2:3], 0, v[168:169]
	global_load_dword v168, v[168:169], off
	s_waitcnt vmcnt(4)
	ds_write2_b32 v50, v210, v208 offset0:132 offset1:198
	v_add_u32_e32 v49, 0x400, v50
	v_add_u32_e32 v50, v7, v81
	v_or_b32_e32 v210, v46, v84
	v_lshlrev_b32_e32 v208, 12, v210
	v_mov_b32_e32 v209, v0
	v_lshl_add_u64 v[208:209], v[2:3], 0, v[208:209]
	global_load_dword v210, v[208:209], off
	v_or_b32_e32 v208, v46, v86
	v_lshlrev_b32_e32 v208, 12, v208
	v_mov_b32_e32 v209, v0
	v_lshl_add_u64 v[208:209], v[2:3], 0, v[208:209]
	global_load_dword v208, v[208:209], off
	s_waitcnt vmcnt(4)
	ds_write2_b32 v49, v162, v160 offset0:8 offset1:74
	v_mov_b32_e32 v49, v0
	v_or_b32_e32 v162, v46, v88
	v_lshlrev_b32_e32 v160, 12, v162
	v_mov_b32_e32 v161, v0
	v_lshl_add_u64 v[160:161], v[2:3], 0, v[160:161]
	global_load_dword v162, v[160:161], off
	v_or_b32_e32 v160, v46, v90
	v_lshlrev_b32_e32 v160, 12, v160
	v_mov_b32_e32 v161, v0
	v_lshl_add_u64 v[160:161], v[2:3], 0, v[160:161]
	global_load_dword v160, v[160:161], off
	s_waitcnt vmcnt(4)
	ds_write2_b32 v50, v170, v168 offset1:66
	v_mov_b32_e32 v49, v0
	v_or_b32_e32 v170, v46, v92
	v_lshlrev_b32_e32 v168, 12, v170
	v_mov_b32_e32 v169, v0
	v_lshl_add_u64 v[168:169], v[2:3], 0, v[168:169]
	global_load_dword v170, v[168:169], off
	v_or_b32_e32 v168, v46, v94
	v_lshlrev_b32_e32 v168, 12, v168
	v_mov_b32_e32 v169, v0
	v_lshl_add_u64 v[168:169], v[2:3], 0, v[168:169]
	global_load_dword v168, v[168:169], off
	s_waitcnt vmcnt(4)
	ds_write2_b32 v50, v210, v208 offset0:132 offset1:198
	v_add_u32_e32 v49, 0x400, v50
	v_add_u32_e32 v50, v7, v93
	v_or_b32_e32 v210, v46, v96
	v_lshlrev_b32_e32 v208, 12, v210
	v_mov_b32_e32 v209, v0
	v_lshl_add_u64 v[208:209], v[2:3], 0, v[208:209]
	global_load_dword v210, v[208:209], off
	v_or_b32_e32 v208, v46, v98
	v_lshlrev_b32_e32 v208, 12, v208
	v_mov_b32_e32 v209, v0
	v_lshl_add_u64 v[208:209], v[2:3], 0, v[208:209]
	global_load_dword v208, v[208:209], off
	s_waitcnt vmcnt(4)
	ds_write2_b32 v49, v162, v160 offset0:8 offset1:74
	v_mov_b32_e32 v49, v0
	v_or_b32_e32 v162, v46, v100
	v_lshlrev_b32_e32 v160, 12, v162
	v_mov_b32_e32 v161, v0
	v_lshl_add_u64 v[160:161], v[2:3], 0, v[160:161]
	global_load_dword v162, v[160:161], off
	v_or_b32_e32 v160, v46, v102
	v_lshlrev_b32_e32 v160, 12, v160
	v_mov_b32_e32 v161, v0
	v_lshl_add_u64 v[160:161], v[2:3], 0, v[160:161]
	global_load_dword v160, v[160:161], off
	s_waitcnt vmcnt(4)
	ds_write2_b32 v50, v170, v168 offset1:66
	v_mov_b32_e32 v49, v0
	v_or_b32_e32 v170, v46, v104
	v_lshlrev_b32_e32 v168, 12, v170
	v_mov_b32_e32 v169, v0
	v_lshl_add_u64 v[168:169], v[2:3], 0, v[168:169]
	global_load_dword v170, v[168:169], off
	v_or_b32_e32 v168, v46, v106
	v_lshlrev_b32_e32 v168, 12, v168
	v_mov_b32_e32 v169, v0
	v_lshl_add_u64 v[168:169], v[2:3], 0, v[168:169]
	global_load_dword v168, v[168:169], off
	s_waitcnt vmcnt(4)
	ds_write2_b32 v50, v210, v208 offset0:132 offset1:198
	v_add_u32_e32 v49, 0x400, v50
	v_add_u32_e32 v50, v7, v105
	v_or_b32_e32 v210, v46, v107
	v_lshlrev_b32_e32 v208, 12, v210
	v_mov_b32_e32 v209, v0
	v_lshl_add_u64 v[208:209], v[2:3], 0, v[208:209]
	global_load_dword v210, v[208:209], off
	v_or_b32_e32 v208, v46, v108
	v_lshlrev_b32_e32 v208, 12, v208
	v_mov_b32_e32 v209, v0
	v_lshl_add_u64 v[208:209], v[2:3], 0, v[208:209]
	global_load_dword v208, v[208:209], off
	s_waitcnt vmcnt(4)
	ds_write2_b32 v49, v162, v160 offset0:8 offset1:74
	v_mov_b32_e32 v49, v0
	v_or_b32_e32 v162, v46, v109
	v_lshlrev_b32_e32 v160, 12, v162
	v_mov_b32_e32 v161, v0
	v_lshl_add_u64 v[160:161], v[2:3], 0, v[160:161]
	global_load_dword v162, v[160:161], off
	v_or_b32_e32 v160, v46, v110
	v_lshlrev_b32_e32 v160, 12, v160
	v_mov_b32_e32 v161, v0
	v_lshl_add_u64 v[160:161], v[2:3], 0, v[160:161]
	global_load_dword v160, v[160:161], off
	s_waitcnt vmcnt(4)
	ds_write2_b32 v50, v170, v168 offset1:66
	v_mov_b32_e32 v49, v0
	v_or_b32_e32 v172, v46, v111
	v_lshlrev_b32_e32 v170, 12, v172
	v_mov_b32_e32 v171, v0
	v_lshl_add_u64 v[170:171], v[2:3], 0, v[170:171]
	global_load_dword v172, v[170:171], off
	v_or_b32_e32 v170, v46, v112
	v_lshlrev_b32_e32 v170, 12, v170
	v_mov_b32_e32 v171, v0
	v_lshl_add_u64 v[168:169], v[2:3], 0, v[170:171]
	global_load_dword v168, v[168:169], off
	s_waitcnt vmcnt(4)
	ds_write2_b32 v50, v210, v208 offset0:132 offset1:198
	v_add_u32_e32 v50, 0x400, v50
	v_mov_b32_e32 v49, v0
	s_waitcnt vmcnt(2)
	ds_write2_b32 v50, v162, v160 offset0:8 offset1:74
	v_mov_b32_e32 v3, v0
	s_waitcnt vmcnt(0)
	ds_write2_b32 v50, v172, v168 offset0:140 offset1:206
	s_waitcnt lgkmcnt(0)
	ds_read2_b32 v[50:51], v114 offset0:33 offset1:41
	ds_read2_b32 v[52:53], v114 offset1:8
	ds_read2_b32 v[54:55], v114 offset0:66 offset1:74
	ds_read2_b32 v[56:57], v114 offset0:99 offset1:107
	v_lshlrev_b32_e32 v2, 1, v46
	ds_read2_b32 v[120:121], v114 offset0:132 offset1:140
	ds_read2_b32 v[122:123], v114 offset0:165 offset1:173
	s_waitcnt lgkmcnt(5)
	v_bfe_u32 v47, v50, 16, 1
	s_waitcnt lgkmcnt(4)
	v_bfe_u32 v46, v52, 16, 1
	v_add3_u32 v46, v52, v46, s51
	v_lshrrev_b32_e32 v46, 16, v46
	v_add3_u32 v47, v50, v47, s51
	v_and_or_b32 v46, v47, s33, v46
	s_waitcnt lgkmcnt(3)
	v_bfe_u32 v47, v54, 16, 1
	v_add3_u32 v47, v54, v47, s51
	s_waitcnt lgkmcnt(2)
	v_bfe_u32 v48, v56, 16, 1
	v_lshrrev_b32_e32 v47, 16, v47
	v_add3_u32 v48, v56, v48, s51
	ds_read2_b32 v[124:125], v114 offset0:198 offset1:206
	ds_read2_b32 v[126:127], v114 offset0:231 offset1:239
	v_and_or_b32 v47, v48, s33, v47
	s_waitcnt lgkmcnt(3)
	v_bfe_u32 v48, v120, 16, 1
	v_add3_u32 v48, v120, v48, s51
	s_waitcnt lgkmcnt(2)
	v_bfe_u32 v49, v122, 16, 1
	v_lshrrev_b32_e32 v48, 16, v48
	v_add3_u32 v49, v122, v49, s51
	v_and_or_b32 v48, v49, s33, v48
	s_waitcnt lgkmcnt(1)
	v_bfe_u32 v49, v124, 16, 1
	v_add3_u32 v49, v124, v49, s51
	s_waitcnt lgkmcnt(0)
	v_bfe_u32 v50, v126, 16, 1
	v_lshl_add_u64 v[2:3], v[16:17], 0, v[2:3]
	v_lshrrev_b32_e32 v49, 16, v49
	v_add3_u32 v50, v126, v50, s51
	v_and_or_b32 v49, v50, s33, v49
	v_lshl_add_u64 v[128:129], v[2:3], 0, v[128:129]
	v_bfe_u32 v45, v53, 16, 1
	global_store_dwordx4 v[128:129], v[46:49], off
	v_add3_u32 v45, v53, v45, s51
	v_lshrrev_b32_e32 v45, 16, v45
	v_bfe_u32 v46, v51, 16, 1
	v_add3_u32 v46, v51, v46, s51
	v_and_or_b32 v46, v46, s33, v45
	v_bfe_u32 v45, v55, 16, 1
	v_add3_u32 v45, v55, v45, s51
	v_bfe_u32 v47, v57, 16, 1
	v_lshrrev_b32_e32 v45, 16, v45
	v_add3_u32 v47, v57, v47, s51
	v_and_or_b32 v47, v47, s33, v45
	v_bfe_u32 v45, v121, 16, 1
	v_add3_u32 v45, v121, v45, s51
	v_bfe_u32 v48, v123, 16, 1
	v_lshrrev_b32_e32 v45, 16, v45
	v_add3_u32 v48, v123, v48, s51
	v_and_or_b32 v48, v48, s33, v45
	v_bfe_u32 v45, v125, 16, 1
	v_add3_u32 v45, v125, v45, s51
	v_bfe_u32 v49, v127, 16, 1
	v_lshrrev_b32_e32 v45, 16, v45
	v_add3_u32 v49, v127, v49, s51
	v_and_or_b32 v49, v49, s33, v45
	v_mov_b32_e32 v45, v0
	v_lshl_add_u64 v[44:45], v[2:3], 0, v[44:45]
	global_store_dwordx4 v[44:45], v[46:49], off
	ds_read2_b32 v[48:49], v114 offset0:49 offset1:57
	ds_read2_b32 v[50:51], v114 offset0:16 offset1:24
	ds_read2_b32 v[52:53], v114 offset0:82 offset1:90
	ds_read2_b32 v[54:55], v114 offset0:115 offset1:123
	ds_read2_b32 v[56:57], v114 offset0:148 offset1:156
	ds_read2_b32 v[120:121], v114 offset0:181 offset1:189
	ds_read2_b32 v[122:123], v114 offset0:214 offset1:222
	ds_read2_b32 v[124:125], v114 offset0:247 offset1:255
	s_waitcnt lgkmcnt(7)
	v_bfe_u32 v45, v48, 16, 1
	s_waitcnt lgkmcnt(6)
	v_bfe_u32 v44, v50, 16, 1
	v_add3_u32 v44, v50, v44, s51
	v_lshrrev_b32_e32 v44, 16, v44
	v_add3_u32 v45, v48, v45, s51
	v_and_or_b32 v44, v45, s33, v44
	s_waitcnt lgkmcnt(5)
	v_bfe_u32 v45, v52, 16, 1
	v_add3_u32 v45, v52, v45, s51
	s_waitcnt lgkmcnt(4)
	v_bfe_u32 v46, v54, 16, 1
	v_lshrrev_b32_e32 v45, 16, v45
	v_add3_u32 v46, v54, v46, s51
	v_and_or_b32 v45, v46, s33, v45
	s_waitcnt lgkmcnt(3)
	v_bfe_u32 v46, v56, 16, 1
	v_add3_u32 v46, v56, v46, s51
	s_waitcnt lgkmcnt(2)
	v_bfe_u32 v47, v120, 16, 1
	v_lshrrev_b32_e32 v46, 16, v46
	v_add3_u32 v47, v120, v47, s51
	v_and_or_b32 v46, v47, s33, v46
	s_waitcnt lgkmcnt(1)
	v_bfe_u32 v47, v122, 16, 1
	v_add3_u32 v47, v122, v47, s51
	s_waitcnt lgkmcnt(0)
	v_bfe_u32 v48, v124, 16, 1
	v_lshrrev_b32_e32 v47, 16, v47
	v_add3_u32 v48, v124, v48, s51
	v_lshlrev_b32_e32 v126, 11, v5
	v_mov_b32_e32 v127, v0
	v_and_or_b32 v47, v48, s33, v47
	v_lshl_add_u64 v[126:127], v[2:3], 0, v[126:127]
	v_bfe_u32 v5, v51, 16, 1
	global_store_dwordx4 v[126:127], v[44:47], off
	v_add3_u32 v5, v51, v5, s51
	v_lshrrev_b32_e32 v5, 16, v5
	v_bfe_u32 v44, v49, 16, 1
	v_add3_u32 v44, v49, v44, s51
	v_and_or_b32 v44, v44, s33, v5
	v_bfe_u32 v5, v53, 16, 1
	v_add3_u32 v5, v53, v5, s51
	v_bfe_u32 v45, v55, 16, 1
	v_lshrrev_b32_e32 v5, 16, v5
	v_add3_u32 v45, v55, v45, s51
	v_and_or_b32 v45, v45, s33, v5
	v_bfe_u32 v5, v57, 16, 1
	v_add3_u32 v5, v57, v5, s51
	v_bfe_u32 v46, v121, 16, 1
	v_lshrrev_b32_e32 v5, 16, v5
	v_add3_u32 v46, v121, v46, s51
	v_and_or_b32 v46, v46, s33, v5
	v_bfe_u32 v5, v123, 16, 1
	v_add3_u32 v5, v123, v5, s51
	v_bfe_u32 v47, v125, 16, 1
	v_lshrrev_b32_e32 v5, 16, v5
	v_add3_u32 v47, v125, v47, s51
	v_and_or_b32 v47, v47, s33, v5
	v_mov_b32_e32 v5, v0
	v_lshl_add_u64 v[2:3], v[2:3], 0, v[4:5]
	global_store_dwordx4 v[2:3], v[44:47], off
	s_waitcnt lgkmcnt(0)

.LBB0_130:
	v_mul_lo_u16_e32 v3, 0x74, v3
	v_sub_u16_e32 v2, v2, v3
	v_lshlrev_b16_e32 v119, 5, v2
	v_lshlrev_b32_e32 v2, 2, v119
	v_mov_b32_e32 v3, v0
	v_lshl_add_u64 v[2:3], v[32:33], 0, v[2:3]
	s_movk_i32 s8, 0x3a00
	v_mad_u64_u32 v[46:47], s[8:9], v5, s8, v[2:3]
	global_load_dword v5, v[46:47], off
	v_add_u32_e32 v46, v7, v13
	s_and_b64 vcc, exec, s[0:1]
	v_or_b32_e32 v162, v58, v4
	s_movk_i32 s8, 0x3a00
	v_mad_u64_u32 v[160:161], s[8:9], v162, s8, v[2:3]
	global_load_dword v160, v[160:161], off
	v_or_b32_e32 v168, v60, v4
	s_movk_i32 s8, 0x3a00
	v_mad_u64_u32 v[168:169], s[8:9], v168, s8, v[2:3]
	global_load_dword v168, v[168:169], off
	s_waitcnt vmcnt(2)
	v_mul_f32_e32 v5, v45, v5
	ds_write_b32 v46, v5
	v_add_lshl_u32 v5, v8, v4, 2
	s_cbranch_vccnz .LBB0_132
	v_readlane_b32 s52, v252, 14
	v_readlane_b32 s62, v252, 24
	v_readlane_b32 s63, v252, 25
	v_readlane_b32 s53, v252, 15
	v_readlane_b32 s54, v252, 16
	v_readlane_b32 s55, v252, 17
	v_readlane_b32 s56, v252, 18
	v_readlane_b32 s57, v252, 19
	global_load_dword v176, v5, s[62:63] offset:16
	global_load_dword v177, v5, s[62:63] offset:24
	global_load_dword v178, v5, s[62:63] offset:32
	global_load_dword v179, v5, s[62:63] offset:40
	global_load_dword v180, v5, s[62:63] offset:48
	global_load_dword v181, v5, s[62:63] offset:56
	global_load_dword v182, v5, s[62:63] offset:64
	global_load_dword v183, v5, s[62:63] offset:72
	global_load_dword v184, v5, s[62:63] offset:80
	global_load_dword v185, v5, s[62:63] offset:88
	global_load_dword v186, v5, s[62:63] offset:96
	global_load_dword v187, v5, s[62:63] offset:104
	global_load_dword v188, v5, s[62:63] offset:112
	global_load_dword v189, v5, s[62:63] offset:120
	global_load_dword v190, v5, s[62:63] offset:128
	global_load_dword v191, v5, s[62:63] offset:136
	global_load_dword v192, v5, s[62:63] offset:144
	global_load_dword v193, v5, s[62:63] offset:152
	global_load_dword v194, v5, s[62:63] offset:160
	global_load_dword v195, v5, s[62:63] offset:168
	global_load_dword v196, v5, s[62:63] offset:176
	global_load_dword v197, v5, s[62:63] offset:184
	global_load_dword v198, v5, s[62:63] offset:192
	global_load_dword v199, v5, s[62:63] offset:200
	global_load_dword v200, v5, s[62:63] offset:208
	global_load_dword v201, v5, s[62:63] offset:216
	global_load_dword v202, v5, s[62:63] offset:224
	global_load_dword v203, v5, s[62:63] offset:232
	global_load_dword v204, v5, s[62:63] offset:240
	global_load_dword v205, v5, s[62:63] offset:248
	global_load_dword v44, v5, s[62:63] offset:8
	v_readlane_b32 s58, v252, 20
	v_readlane_b32 s59, v252, 21
	v_readlane_b32 s60, v252, 22
	v_readlane_b32 s61, v252, 23
	v_readlane_b32 s64, v252, 26
	v_readlane_b32 s65, v252, 27
	v_readlane_b32 s66, v252, 28
	v_readlane_b32 s67, v252, 29
.LBB0_132:
	v_add_u32_e32 v47, v7, v59
	v_mov_b32_e32 v45, 1.0
	s_and_b64 vcc, exec, s[0:1]
	v_or_b32_e32 v210, v62, v4
	s_movk_i32 s8, 0x3a00
	v_mad_u64_u32 v[208:209], s[8:9], v210, s8, v[2:3]
	global_load_dword v208, v[208:209], off
	s_waitcnt vmcnt(1)
	v_mul_f32_e32 v44, v44, v160
	ds_write_b32 v47, v44
	v_mov_b32_e32 v44, 1.0
	s_cbranch_vccnz .LBB0_134
	v_readlane_b32 s52, v252, 14
	v_readlane_b32 s62, v252, 24
	v_readlane_b32 s63, v252, 25
	v_readlane_b32 s53, v252, 15
	v_readlane_b32 s54, v252, 16
	v_readlane_b32 s55, v252, 17
	v_readlane_b32 s56, v252, 18
	v_readlane_b32 s57, v252, 19
	v_mov_b32_e32 v44, v176
	v_readlane_b32 s58, v252, 20
	v_readlane_b32 s59, v252, 21
	v_readlane_b32 s60, v252, 22
	v_readlane_b32 s61, v252, 23
	v_readlane_b32 s64, v252, 26
	v_readlane_b32 s65, v252, 27
	v_readlane_b32 s66, v252, 28
	v_readlane_b32 s67, v252, 29
.LBB0_134:
	v_add_u32_e32 v47, v7, v61
	s_and_b64 vcc, exec, s[0:1]
	v_or_b32_e32 v160, v64, v4
	s_movk_i32 s8, 0x3a00
	v_mad_u64_u32 v[160:161], s[8:9], v160, s8, v[2:3]
	global_load_dword v160, v[160:161], off
	s_waitcnt vmcnt(2)
	v_mul_f32_e32 v44, v44, v168
	ds_write_b32 v47, v44
	s_cbranch_vccnz .LBB0_136
	v_readlane_b32 s52, v252, 14
	v_readlane_b32 s62, v252, 24
	v_readlane_b32 s63, v252, 25
	v_readlane_b32 s53, v252, 15
	v_readlane_b32 s54, v252, 16
	v_readlane_b32 s55, v252, 17
	v_readlane_b32 s56, v252, 18
	v_readlane_b32 s57, v252, 19
	v_mov_b32_e32 v45, v177
	v_readlane_b32 s58, v252, 20
	v_readlane_b32 s59, v252, 21
	v_readlane_b32 s60, v252, 22
	v_readlane_b32 s61, v252, 23
	v_readlane_b32 s64, v252, 26
	v_readlane_b32 s65, v252, 27
	v_readlane_b32 s66, v252, 28
	v_readlane_b32 s67, v252, 29
.LBB0_136:
	v_add_u32_e32 v47, v7, v63
	v_mov_b32_e32 v44, 1.0
	s_and_b64 vcc, exec, s[0:1]
	v_or_b32_e32 v170, v66, v4
	s_movk_i32 s8, 0x3a00
	v_mad_u64_u32 v[168:169], s[8:9], v170, s8, v[2:3]
	global_load_dword v168, v[168:169], off
	s_waitcnt vmcnt(2)
	v_mul_f32_e32 v45, v45, v208
	ds_write_b32 v47, v45
	v_mov_b32_e32 v45, 1.0
	s_cbranch_vccnz .LBB0_138
	v_readlane_b32 s52, v252, 14
	v_readlane_b32 s62, v252, 24
	v_readlane_b32 s63, v252, 25
	v_readlane_b32 s53, v252, 15
	v_readlane_b32 s54, v252, 16
	v_readlane_b32 s55, v252, 17
	v_readlane_b32 s56, v252, 18
	v_readlane_b32 s57, v252, 19
	v_mov_b32_e32 v45, v178
	v_readlane_b32 s58, v252, 20
	v_readlane_b32 s59, v252, 21
	v_readlane_b32 s60, v252, 22
	v_readlane_b32 s61, v252, 23
	v_readlane_b32 s64, v252, 26
	v_readlane_b32 s65, v252, 27
	v_readlane_b32 s66, v252, 28
	v_readlane_b32 s67, v252, 29
.LBB0_138:
	v_add_u32_e32 v47, v7, v65
	s_and_b64 vcc, exec, s[0:1]
	v_or_b32_e32 v208, v68, v4
	s_movk_i32 s8, 0x3a00
	v_mad_u64_u32 v[208:209], s[8:9], v208, s8, v[2:3]
	global_load_dword v208, v[208:209], off
	s_waitcnt vmcnt(2)
	v_mul_f32_e32 v45, v45, v160
	ds_write_b32 v47, v45
	s_cbranch_vccnz .LBB0_140
	v_readlane_b32 s52, v252, 14
	v_readlane_b32 s62, v252, 24
	v_readlane_b32 s63, v252, 25
	v_readlane_b32 s53, v252, 15
	v_readlane_b32 s54, v252, 16
	v_readlane_b32 s55, v252, 17
	v_readlane_b32 s56, v252, 18
	v_readlane_b32 s57, v252, 19
	v_mov_b32_e32 v44, v179
	v_readlane_b32 s58, v252, 20
	v_readlane_b32 s59, v252, 21
	v_readlane_b32 s60, v252, 22
	v_readlane_b32 s61, v252, 23
	v_readlane_b32 s64, v252, 26
	v_readlane_b32 s65, v252, 27
	v_readlane_b32 s66, v252, 28
	v_readlane_b32 s67, v252, 29
.LBB0_140:
	v_add_u32_e32 v47, v7, v67
	v_mov_b32_e32 v45, 1.0
	s_and_b64 vcc, exec, s[0:1]
	v_or_b32_e32 v162, v70, v4
	s_movk_i32 s8, 0x3a00
	v_mad_u64_u32 v[160:161], s[8:9], v162, s8, v[2:3]
	global_load_dword v160, v[160:161], off
	s_waitcnt vmcnt(2)
	v_mul_f32_e32 v44, v44, v168
	ds_write_b32 v47, v44
	v_mov_b32_e32 v44, 1.0
	s_cbranch_vccnz .LBB0_142
	v_readlane_b32 s52, v252, 14
	v_readlane_b32 s62, v252, 24
	v_readlane_b32 s63, v252, 25
	v_readlane_b32 s53, v252, 15
	v_readlane_b32 s54, v252, 16
	v_readlane_b32 s55, v252, 17
	v_readlane_b32 s56, v252, 18
	v_readlane_b32 s57, v252, 19
	v_mov_b32_e32 v44, v180
	v_readlane_b32 s58, v252, 20
	v_readlane_b32 s59, v252, 21
	v_readlane_b32 s60, v252, 22
	v_readlane_b32 s61, v252, 23
	v_readlane_b32 s64, v252, 26
	v_readlane_b32 s65, v252, 27
	v_readlane_b32 s66, v252, 28
	v_readlane_b32 s67, v252, 29
.LBB0_142:
	v_add_u32_e32 v47, v7, v69
	s_and_b64 vcc, exec, s[0:1]
	v_or_b32_e32 v168, v72, v4
	s_movk_i32 s8, 0x3a00
	v_mad_u64_u32 v[168:169], s[8:9], v168, s8, v[2:3]
	global_load_dword v168, v[168:169], off
	s_waitcnt vmcnt(2)
	v_mul_f32_e32 v44, v44, v208
	ds_write_b32 v47, v44
	s_cbranch_vccnz .LBB0_144
	v_readlane_b32 s52, v252, 14
	v_readlane_b32 s62, v252, 24
	v_readlane_b32 s63, v252, 25
	v_readlane_b32 s53, v252, 15
	v_readlane_b32 s54, v252, 16
	v_readlane_b32 s55, v252, 17
	v_readlane_b32 s56, v252, 18
	v_readlane_b32 s57, v252, 19
	v_mov_b32_e32 v45, v181
	v_readlane_b32 s58, v252, 20
	v_readlane_b32 s59, v252, 21
	v_readlane_b32 s60, v252, 22
	v_readlane_b32 s61, v252, 23
	v_readlane_b32 s64, v252, 26
	v_readlane_b32 s65, v252, 27
	v_readlane_b32 s66, v252, 28
	v_readlane_b32 s67, v252, 29
.LBB0_144:
	v_add_u32_e32 v47, v7, v71
	v_mov_b32_e32 v44, 1.0
	s_and_b64 vcc, exec, s[0:1]
	v_or_b32_e32 v210, v74, v4
	s_movk_i32 s8, 0x3a00
	v_mad_u64_u32 v[208:209], s[8:9], v210, s8, v[2:3]
	global_load_dword v208, v[208:209], off
	s_waitcnt vmcnt(2)
	v_mul_f32_e32 v45, v45, v160
	ds_write_b32 v47, v45
	v_mov_b32_e32 v45, 1.0
	s_cbranch_vccnz .LBB0_146
	v_readlane_b32 s52, v252, 14
	v_readlane_b32 s62, v252, 24
	v_readlane_b32 s63, v252, 25
	v_readlane_b32 s53, v252, 15
	v_readlane_b32 s54, v252, 16
	v_readlane_b32 s55, v252, 17
	v_readlane_b32 s56, v252, 18
	v_readlane_b32 s57, v252, 19
	v_mov_b32_e32 v45, v182
	v_readlane_b32 s58, v252, 20
	v_readlane_b32 s59, v252, 21
	v_readlane_b32 s60, v252, 22
	v_readlane_b32 s61, v252, 23
	v_readlane_b32 s64, v252, 26
	v_readlane_b32 s65, v252, 27
	v_readlane_b32 s66, v252, 28
	v_readlane_b32 s67, v252, 29
.LBB0_146:
	v_add_u32_e32 v47, v7, v73
	s_and_b64 vcc, exec, s[0:1]
	v_or_b32_e32 v160, v76, v4
	s_movk_i32 s8, 0x3a00
	v_mad_u64_u32 v[160:161], s[8:9], v160, s8, v[2:3]
	global_load_dword v160, v[160:161], off
	s_waitcnt vmcnt(2)
	v_mul_f32_e32 v45, v45, v168
	ds_write_b32 v47, v45
	s_cbranch_vccnz .LBB0_148
	v_readlane_b32 s52, v252, 14
	v_readlane_b32 s62, v252, 24
	v_readlane_b32 s63, v252, 25
	v_readlane_b32 s53, v252, 15
	v_readlane_b32 s54, v252, 16
	v_readlane_b32 s55, v252, 17
	v_readlane_b32 s56, v252, 18
	v_readlane_b32 s57, v252, 19
	v_mov_b32_e32 v44, v183
	v_readlane_b32 s58, v252, 20
	v_readlane_b32 s59, v252, 21
	v_readlane_b32 s60, v252, 22
	v_readlane_b32 s61, v252, 23
	v_readlane_b32 s64, v252, 26
	v_readlane_b32 s65, v252, 27
	v_readlane_b32 s66, v252, 28
	v_readlane_b32 s67, v252, 29
.LBB0_148:
	v_add_u32_e32 v47, v7, v75
	v_mov_b32_e32 v45, 1.0
	s_and_b64 vcc, exec, s[0:1]
	v_or_b32_e32 v170, v78, v4
	s_movk_i32 s8, 0x3a00
	v_mad_u64_u32 v[168:169], s[8:9], v170, s8, v[2:3]
	global_load_dword v168, v[168:169], off
	s_waitcnt vmcnt(2)
	v_mul_f32_e32 v44, v44, v208
	ds_write_b32 v47, v44
	v_mov_b32_e32 v44, 1.0
	s_cbranch_vccnz .LBB0_150
	v_readlane_b32 s52, v252, 14
	v_readlane_b32 s62, v252, 24
	v_readlane_b32 s63, v252, 25
	v_readlane_b32 s53, v252, 15
	v_readlane_b32 s54, v252, 16
	v_readlane_b32 s55, v252, 17
	v_readlane_b32 s56, v252, 18
	v_readlane_b32 s57, v252, 19
	v_mov_b32_e32 v44, v184
	v_readlane_b32 s58, v252, 20
	v_readlane_b32 s59, v252, 21
	v_readlane_b32 s60, v252, 22
	v_readlane_b32 s61, v252, 23
	v_readlane_b32 s64, v252, 26
	v_readlane_b32 s65, v252, 27
	v_readlane_b32 s66, v252, 28
	v_readlane_b32 s67, v252, 29
.LBB0_150:
	v_add_u32_e32 v47, v7, v77
	s_and_b64 vcc, exec, s[0:1]
	v_or_b32_e32 v208, v80, v4
	s_movk_i32 s8, 0x3a00
	v_mad_u64_u32 v[208:209], s[8:9], v208, s8, v[2:3]
	global_load_dword v208, v[208:209], off
	s_waitcnt vmcnt(2)
	v_mul_f32_e32 v44, v44, v160
	ds_write_b32 v47, v44
	s_cbranch_vccnz .LBB0_152
	v_readlane_b32 s52, v252, 14
	v_readlane_b32 s62, v252, 24
	v_readlane_b32 s63, v252, 25
	v_readlane_b32 s53, v252, 15
	v_readlane_b32 s54, v252, 16
	v_readlane_b32 s55, v252, 17
	v_readlane_b32 s56, v252, 18
	v_readlane_b32 s57, v252, 19
	v_mov_b32_e32 v45, v185
	v_readlane_b32 s58, v252, 20
	v_readlane_b32 s59, v252, 21
	v_readlane_b32 s60, v252, 22
	v_readlane_b32 s61, v252, 23
	v_readlane_b32 s64, v252, 26
	v_readlane_b32 s65, v252, 27
	v_readlane_b32 s66, v252, 28
	v_readlane_b32 s67, v252, 29
.LBB0_152:
	v_add_u32_e32 v47, v7, v79
	v_mov_b32_e32 v44, 1.0
	s_and_b64 vcc, exec, s[0:1]
	v_or_b32_e32 v162, v82, v4
	s_movk_i32 s8, 0x3a00
	v_mad_u64_u32 v[160:161], s[8:9], v162, s8, v[2:3]
	global_load_dword v160, v[160:161], off
	s_waitcnt vmcnt(2)
	v_mul_f32_e32 v45, v45, v168
	ds_write_b32 v47, v45
	v_mov_b32_e32 v45, 1.0
	s_cbranch_vccnz .LBB0_154
	v_readlane_b32 s52, v252, 14
	v_readlane_b32 s62, v252, 24
	v_readlane_b32 s63, v252, 25
	v_readlane_b32 s53, v252, 15
	v_readlane_b32 s54, v252, 16
	v_readlane_b32 s55, v252, 17
	v_readlane_b32 s56, v252, 18
	v_readlane_b32 s57, v252, 19
	v_mov_b32_e32 v45, v186
	v_readlane_b32 s58, v252, 20
	v_readlane_b32 s59, v252, 21
	v_readlane_b32 s60, v252, 22
	v_readlane_b32 s61, v252, 23
	v_readlane_b32 s64, v252, 26
	v_readlane_b32 s65, v252, 27
	v_readlane_b32 s66, v252, 28
	v_readlane_b32 s67, v252, 29
.LBB0_154:
	v_add_u32_e32 v47, v7, v81
	s_and_b64 vcc, exec, s[0:1]
	v_or_b32_e32 v168, v84, v4
	s_movk_i32 s8, 0x3a00
	v_mad_u64_u32 v[168:169], s[8:9], v168, s8, v[2:3]
	global_load_dword v168, v[168:169], off
	s_waitcnt vmcnt(2)
	v_mul_f32_e32 v45, v45, v208
	ds_write_b32 v47, v45
	s_cbranch_vccnz .LBB0_156
	v_readlane_b32 s52, v252, 14
	v_readlane_b32 s62, v252, 24
	v_readlane_b32 s63, v252, 25
	v_readlane_b32 s53, v252, 15
	v_readlane_b32 s54, v252, 16
	v_readlane_b32 s55, v252, 17
	v_readlane_b32 s56, v252, 18
	v_readlane_b32 s57, v252, 19
	v_mov_b32_e32 v44, v187
	v_readlane_b32 s58, v252, 20
	v_readlane_b32 s59, v252, 21
	v_readlane_b32 s60, v252, 22
	v_readlane_b32 s61, v252, 23
	v_readlane_b32 s64, v252, 26
	v_readlane_b32 s65, v252, 27
	v_readlane_b32 s66, v252, 28
	v_readlane_b32 s67, v252, 29
.LBB0_156:
	v_add_u32_e32 v47, v7, v83
	v_mov_b32_e32 v45, 1.0
	s_and_b64 vcc, exec, s[0:1]
	v_or_b32_e32 v210, v86, v4
	s_movk_i32 s8, 0x3a00
	v_mad_u64_u32 v[208:209], s[8:9], v210, s8, v[2:3]
	global_load_dword v208, v[208:209], off
	s_waitcnt vmcnt(2)
	v_mul_f32_e32 v44, v44, v160
	ds_write_b32 v47, v44
	v_mov_b32_e32 v44, 1.0
	s_cbranch_vccnz .LBB0_158
	v_readlane_b32 s52, v252, 14
	v_readlane_b32 s62, v252, 24
	v_readlane_b32 s63, v252, 25
	v_readlane_b32 s53, v252, 15
	v_readlane_b32 s54, v252, 16
	v_readlane_b32 s55, v252, 17
	v_readlane_b32 s56, v252, 18
	v_readlane_b32 s57, v252, 19
	v_mov_b32_e32 v44, v188
	v_readlane_b32 s58, v252, 20
	v_readlane_b32 s59, v252, 21
	v_readlane_b32 s60, v252, 22
	v_readlane_b32 s61, v252, 23
	v_readlane_b32 s64, v252, 26
	v_readlane_b32 s65, v252, 27
	v_readlane_b32 s66, v252, 28
	v_readlane_b32 s67, v252, 29
.LBB0_158:
	v_add_u32_e32 v47, v7, v85
	s_and_b64 vcc, exec, s[0:1]
	v_or_b32_e32 v160, v88, v4
	s_movk_i32 s8, 0x3a00
	v_mad_u64_u32 v[160:161], s[8:9], v160, s8, v[2:3]
	global_load_dword v160, v[160:161], off
	s_waitcnt vmcnt(2)
	v_mul_f32_e32 v44, v44, v168
	ds_write_b32 v47, v44
	s_cbranch_vccnz .LBB0_160
	v_readlane_b32 s52, v252, 14
	v_readlane_b32 s62, v252, 24
	v_readlane_b32 s63, v252, 25
	v_readlane_b32 s53, v252, 15
	v_readlane_b32 s54, v252, 16
	v_readlane_b32 s55, v252, 17
	v_readlane_b32 s56, v252, 18
	v_readlane_b32 s57, v252, 19
	v_mov_b32_e32 v45, v189
	v_readlane_b32 s58, v252, 20
	v_readlane_b32 s59, v252, 21
	v_readlane_b32 s60, v252, 22
	v_readlane_b32 s61, v252, 23
	v_readlane_b32 s64, v252, 26
	v_readlane_b32 s65, v252, 27
	v_readlane_b32 s66, v252, 28
	v_readlane_b32 s67, v252, 29
.LBB0_160:
	v_add_u32_e32 v47, v7, v87
	v_mov_b32_e32 v44, 1.0
	s_and_b64 vcc, exec, s[0:1]
	v_or_b32_e32 v170, v90, v4
	s_movk_i32 s8, 0x3a00
	v_mad_u64_u32 v[168:169], s[8:9], v170, s8, v[2:3]
	global_load_dword v168, v[168:169], off
	s_waitcnt vmcnt(2)
	v_mul_f32_e32 v45, v45, v208
	ds_write_b32 v47, v45
	v_mov_b32_e32 v45, 1.0
	s_cbranch_vccnz .LBB0_162
	v_readlane_b32 s52, v252, 14
	v_readlane_b32 s62, v252, 24
	v_readlane_b32 s63, v252, 25
	v_readlane_b32 s53, v252, 15
	v_readlane_b32 s54, v252, 16
	v_readlane_b32 s55, v252, 17
	v_readlane_b32 s56, v252, 18
	v_readlane_b32 s57, v252, 19
	v_mov_b32_e32 v45, v190
	v_readlane_b32 s58, v252, 20
	v_readlane_b32 s59, v252, 21
	v_readlane_b32 s60, v252, 22
	v_readlane_b32 s61, v252, 23
	v_readlane_b32 s64, v252, 26
	v_readlane_b32 s65, v252, 27
	v_readlane_b32 s66, v252, 28
	v_readlane_b32 s67, v252, 29
.LBB0_162:
	v_add_u32_e32 v47, v7, v89
	s_and_b64 vcc, exec, s[0:1]
	v_or_b32_e32 v208, v92, v4
	s_movk_i32 s8, 0x3a00
	v_mad_u64_u32 v[208:209], s[8:9], v208, s8, v[2:3]
	global_load_dword v208, v[208:209], off
	s_waitcnt vmcnt(2)
	v_mul_f32_e32 v45, v45, v160
	ds_write_b32 v47, v45
	s_cbranch_vccnz .LBB0_164
	v_readlane_b32 s52, v252, 14
	v_readlane_b32 s62, v252, 24
	v_readlane_b32 s63, v252, 25
	v_readlane_b32 s53, v252, 15
	v_readlane_b32 s54, v252, 16
	v_readlane_b32 s55, v252, 17
	v_readlane_b32 s56, v252, 18
	v_readlane_b32 s57, v252, 19
	v_mov_b32_e32 v44, v191
	v_readlane_b32 s58, v252, 20
	v_readlane_b32 s59, v252, 21
	v_readlane_b32 s60, v252, 22
	v_readlane_b32 s61, v252, 23
	v_readlane_b32 s64, v252, 26
	v_readlane_b32 s65, v252, 27
	v_readlane_b32 s66, v252, 28
	v_readlane_b32 s67, v252, 29
.LBB0_164:
	v_add_u32_e32 v47, v7, v91
	v_mov_b32_e32 v45, 1.0
	s_and_b64 vcc, exec, s[0:1]
	v_or_b32_e32 v162, v94, v4
	s_movk_i32 s8, 0x3a00
	v_mad_u64_u32 v[160:161], s[8:9], v162, s8, v[2:3]
	global_load_dword v160, v[160:161], off
	s_waitcnt vmcnt(2)
	v_mul_f32_e32 v44, v44, v168
	ds_write_b32 v47, v44
	v_mov_b32_e32 v44, 1.0
	s_cbranch_vccnz .LBB0_166
	v_readlane_b32 s52, v252, 14
	v_readlane_b32 s62, v252, 24
	v_readlane_b32 s63, v252, 25
	v_readlane_b32 s53, v252, 15
	v_readlane_b32 s54, v252, 16
	v_readlane_b32 s55, v252, 17
	v_readlane_b32 s56, v252, 18
	v_readlane_b32 s57, v252, 19
	v_mov_b32_e32 v44, v192
	v_readlane_b32 s58, v252, 20
	v_readlane_b32 s59, v252, 21
	v_readlane_b32 s60, v252, 22
	v_readlane_b32 s61, v252, 23
	v_readlane_b32 s64, v252, 26
	v_readlane_b32 s65, v252, 27
	v_readlane_b32 s66, v252, 28
	v_readlane_b32 s67, v252, 29
.LBB0_166:
	v_add_u32_e32 v47, v7, v93
	s_and_b64 vcc, exec, s[0:1]
	v_or_b32_e32 v168, v96, v4
	s_movk_i32 s8, 0x3a00
	v_mad_u64_u32 v[168:169], s[8:9], v168, s8, v[2:3]
	global_load_dword v168, v[168:169], off
	s_waitcnt vmcnt(2)
	v_mul_f32_e32 v44, v44, v208
	ds_write_b32 v47, v44
	s_cbranch_vccnz .LBB0_168
	v_readlane_b32 s52, v252, 14
	v_readlane_b32 s62, v252, 24
	v_readlane_b32 s63, v252, 25
	v_readlane_b32 s53, v252, 15
	v_readlane_b32 s54, v252, 16
	v_readlane_b32 s55, v252, 17
	v_readlane_b32 s56, v252, 18
	v_readlane_b32 s57, v252, 19
	v_mov_b32_e32 v45, v193
	v_readlane_b32 s58, v252, 20
	v_readlane_b32 s59, v252, 21
	v_readlane_b32 s60, v252, 22
	v_readlane_b32 s61, v252, 23
	v_readlane_b32 s64, v252, 26
	v_readlane_b32 s65, v252, 27
	v_readlane_b32 s66, v252, 28
	v_readlane_b32 s67, v252, 29
.LBB0_168:
	v_add_u32_e32 v47, v7, v95
	v_mov_b32_e32 v44, 1.0
	s_and_b64 vcc, exec, s[0:1]
	v_or_b32_e32 v210, v98, v4
	s_movk_i32 s8, 0x3a00
	v_mad_u64_u32 v[208:209], s[8:9], v210, s8, v[2:3]
	global_load_dword v208, v[208:209], off
	s_waitcnt vmcnt(2)
	v_mul_f32_e32 v45, v45, v160
	ds_write_b32 v47, v45
	v_mov_b32_e32 v45, 1.0
	s_cbranch_vccnz .LBB0_170
	v_readlane_b32 s52, v252, 14
	v_readlane_b32 s62, v252, 24
	v_readlane_b32 s63, v252, 25
	v_readlane_b32 s53, v252, 15
	v_readlane_b32 s54, v252, 16
	v_readlane_b32 s55, v252, 17
	v_readlane_b32 s56, v252, 18
	v_readlane_b32 s57, v252, 19
	v_mov_b32_e32 v45, v194
	v_readlane_b32 s58, v252, 20
	v_readlane_b32 s59, v252, 21
	v_readlane_b32 s60, v252, 22
	v_readlane_b32 s61, v252, 23
	v_readlane_b32 s64, v252, 26
	v_readlane_b32 s65, v252, 27
	v_readlane_b32 s66, v252, 28
	v_readlane_b32 s67, v252, 29
.LBB0_170:
	v_add_u32_e32 v47, v7, v97
	s_and_b64 vcc, exec, s[0:1]
	v_or_b32_e32 v160, v100, v4
	s_movk_i32 s8, 0x3a00
	v_mad_u64_u32 v[160:161], s[8:9], v160, s8, v[2:3]
	global_load_dword v160, v[160:161], off
	s_waitcnt vmcnt(2)
	v_mul_f32_e32 v45, v45, v168
	ds_write_b32 v47, v45
	s_cbranch_vccnz .LBB0_172
	v_readlane_b32 s52, v252, 14
	v_readlane_b32 s62, v252, 24
	v_readlane_b32 s63, v252, 25
	v_readlane_b32 s53, v252, 15
	v_readlane_b32 s54, v252, 16
	v_readlane_b32 s55, v252, 17
	v_readlane_b32 s56, v252, 18
	v_readlane_b32 s57, v252, 19
	v_mov_b32_e32 v44, v195
	v_readlane_b32 s58, v252, 20
	v_readlane_b32 s59, v252, 21
	v_readlane_b32 s60, v252, 22
	v_readlane_b32 s61, v252, 23
	v_readlane_b32 s64, v252, 26
	v_readlane_b32 s65, v252, 27
	v_readlane_b32 s66, v252, 28
	v_readlane_b32 s67, v252, 29
.LBB0_172:
	v_add_u32_e32 v47, v7, v99
	v_mov_b32_e32 v45, 1.0
	s_and_b64 vcc, exec, s[0:1]
	v_or_b32_e32 v170, v102, v4
	s_movk_i32 s8, 0x3a00
	v_mad_u64_u32 v[168:169], s[8:9], v170, s8, v[2:3]
	global_load_dword v170, v[168:169], off
	s_waitcnt vmcnt(2)
	v_mul_f32_e32 v44, v44, v208
	ds_write_b32 v47, v44
	v_mov_b32_e32 v44, 1.0
	s_cbranch_vccnz .LBB0_174
	v_readlane_b32 s52, v252, 14
	v_readlane_b32 s62, v252, 24
	v_readlane_b32 s63, v252, 25
	v_readlane_b32 s53, v252, 15
	v_readlane_b32 s54, v252, 16
	v_readlane_b32 s55, v252, 17
	v_readlane_b32 s56, v252, 18
	v_readlane_b32 s57, v252, 19
	v_mov_b32_e32 v44, v196
	v_readlane_b32 s58, v252, 20
	v_readlane_b32 s59, v252, 21
	v_readlane_b32 s60, v252, 22
	v_readlane_b32 s61, v252, 23
	v_readlane_b32 s64, v252, 26
	v_readlane_b32 s65, v252, 27
	v_readlane_b32 s66, v252, 28
	v_readlane_b32 s67, v252, 29
.LBB0_174:
	v_add_u32_e32 v47, v7, v101
	s_and_b64 vcc, exec, s[0:1]
	v_or_b32_e32 v210, v104, v4
	s_movk_i32 s8, 0x3a00
	v_mad_u64_u32 v[208:209], s[8:9], v210, s8, v[2:3]
	global_load_dword v211, v[208:209], off
	s_waitcnt vmcnt(2)
	v_mul_f32_e32 v44, v44, v160
	ds_write_b32 v47, v44
	s_cbranch_vccnz .LBB0_176
	v_readlane_b32 s52, v252, 14
	v_readlane_b32 s62, v252, 24
	v_readlane_b32 s63, v252, 25
	v_readlane_b32 s53, v252, 15
	v_readlane_b32 s54, v252, 16
	v_readlane_b32 s55, v252, 17
	v_readlane_b32 s56, v252, 18
	v_readlane_b32 s57, v252, 19
	v_mov_b32_e32 v45, v197
	v_readlane_b32 s58, v252, 20
	v_readlane_b32 s59, v252, 21
	v_readlane_b32 s60, v252, 22
	v_readlane_b32 s61, v252, 23
	v_readlane_b32 s64, v252, 26
	v_readlane_b32 s65, v252, 27
	v_readlane_b32 s66, v252, 28
	v_readlane_b32 s67, v252, 29
.LBB0_176:
	v_add_u32_e32 v47, v7, v103
	v_mov_b32_e32 v46, 1.0
	s_and_b64 vcc, exec, s[0:1]
	v_or_b32_e32 v162, v106, v4
	s_movk_i32 s8, 0x3a00
	v_mad_u64_u32 v[160:161], s[8:9], v162, s8, v[2:3]
	global_load_dword v163, v[160:161], off
	s_waitcnt vmcnt(2)
	v_mul_f32_e32 v44, v45, v170
	v_mov_b32_e32 v45, 1.0
	ds_write_b32 v47, v44
	s_cbranch_vccnz .LBB0_178
	v_readlane_b32 s52, v252, 14
	v_readlane_b32 s62, v252, 24
	v_readlane_b32 s63, v252, 25
	v_readlane_b32 s53, v252, 15
	v_readlane_b32 s54, v252, 16
	v_readlane_b32 s55, v252, 17
	v_readlane_b32 s56, v252, 18
	v_readlane_b32 s57, v252, 19
	v_mov_b32_e32 v45, v198
	v_readlane_b32 s58, v252, 20
	v_readlane_b32 s59, v252, 21
	v_readlane_b32 s60, v252, 22
	v_readlane_b32 s61, v252, 23
	v_readlane_b32 s64, v252, 26
	v_readlane_b32 s65, v252, 27
	v_readlane_b32 s66, v252, 28
	v_readlane_b32 s67, v252, 29
.LBB0_178:
	v_add_u32_e32 v44, v7, v105
	s_and_b64 vcc, exec, s[0:1]
	v_or_b32_e32 v170, v107, v4
	s_movk_i32 s8, 0x3a00
	v_mad_u64_u32 v[168:169], s[8:9], v170, s8, v[2:3]
	global_load_dword v170, v[168:169], off
	s_waitcnt vmcnt(2)
	v_mul_f32_e32 v45, v45, v211
	ds_write_b32 v44, v45
	s_cbranch_vccnz .LBB0_180
	v_readlane_b32 s52, v252, 14
	v_readlane_b32 s62, v252, 24
	v_readlane_b32 s63, v252, 25
	v_readlane_b32 s53, v252, 15
	v_readlane_b32 s54, v252, 16
	v_readlane_b32 s55, v252, 17
	v_readlane_b32 s56, v252, 18
	v_readlane_b32 s57, v252, 19
	v_mov_b32_e32 v46, v199
	v_readlane_b32 s58, v252, 20
	v_readlane_b32 s59, v252, 21
	v_readlane_b32 s60, v252, 22
	v_readlane_b32 s61, v252, 23
	v_readlane_b32 s64, v252, 26
	v_readlane_b32 s65, v252, 27
	v_readlane_b32 s66, v252, 28
	v_readlane_b32 s67, v252, 29
.LBB0_180:
	v_mov_b32_e32 v45, 1.0
	s_and_b64 vcc, exec, s[0:1]
	v_or_b32_e32 v208, v108, v4
	s_movk_i32 s8, 0x3a00
	v_mad_u64_u32 v[208:209], s[8:9], v208, s8, v[2:3]
	global_load_dword v209, v[208:209], off
	s_waitcnt vmcnt(2)
	v_mul_f32_e32 v46, v46, v163
	ds_write_b32 v44, v46 offset:264
	v_mov_b32_e32 v46, 1.0
	s_cbranch_vccnz .LBB0_182
	v_readlane_b32 s52, v252, 14
	v_readlane_b32 s62, v252, 24
	v_readlane_b32 s63, v252, 25
	v_readlane_b32 s53, v252, 15
	v_readlane_b32 s54, v252, 16
	v_readlane_b32 s55, v252, 17
	v_readlane_b32 s56, v252, 18
	v_readlane_b32 s57, v252, 19
	v_mov_b32_e32 v46, v200
	v_readlane_b32 s58, v252, 20
	v_readlane_b32 s59, v252, 21
	v_readlane_b32 s60, v252, 22
	v_readlane_b32 s61, v252, 23
	v_readlane_b32 s64, v252, 26
	v_readlane_b32 s65, v252, 27
	v_readlane_b32 s66, v252, 28
	v_readlane_b32 s67, v252, 29
.LBB0_182:
	s_and_b64 vcc, exec, s[0:1]
	v_or_b32_e32 v162, v109, v4
	s_movk_i32 s8, 0x3a00
	v_mad_u64_u32 v[160:161], s[8:9], v162, s8, v[2:3]
	global_load_dword v162, v[160:161], off
	s_waitcnt vmcnt(2)
	v_mul_f32_e32 v46, v46, v170
	ds_write_b32 v44, v46 offset:528
	s_cbranch_vccnz .LBB0_184
	v_readlane_b32 s52, v252, 14
	v_readlane_b32 s62, v252, 24
	v_readlane_b32 s63, v252, 25
	v_readlane_b32 s53, v252, 15
	v_readlane_b32 s54, v252, 16
	v_readlane_b32 s55, v252, 17
	v_readlane_b32 s56, v252, 18
	v_readlane_b32 s57, v252, 19
	v_mov_b32_e32 v45, v201
	v_readlane_b32 s58, v252, 20
	v_readlane_b32 s59, v252, 21
	v_readlane_b32 s60, v252, 22
	v_readlane_b32 s61, v252, 23
	v_readlane_b32 s64, v252, 26
	v_readlane_b32 s65, v252, 27
	v_readlane_b32 s66, v252, 28
	v_readlane_b32 s67, v252, 29
.LBB0_184:
	v_mov_b32_e32 v46, 1.0
	s_and_b64 vcc, exec, s[0:1]
	v_or_b32_e32 v170, v110, v4
	s_movk_i32 s8, 0x3a00
	v_mad_u64_u32 v[168:169], s[8:9], v170, s8, v[2:3]
	global_load_dword v171, v[168:169], off
	s_waitcnt vmcnt(2)
	v_mul_f32_e32 v45, v45, v209
	ds_write_b32 v44, v45 offset:792
	v_mov_b32_e32 v45, 1.0
	s_cbranch_vccnz .LBB0_186
	v_readlane_b32 s52, v252, 14
	v_readlane_b32 s62, v252, 24
	v_readlane_b32 s63, v252, 25
	v_readlane_b32 s53, v252, 15
	v_readlane_b32 s54, v252, 16
	v_readlane_b32 s55, v252, 17
	v_readlane_b32 s56, v252, 18
	v_readlane_b32 s57, v252, 19
	v_mov_b32_e32 v45, v202
	v_readlane_b32 s58, v252, 20
	v_readlane_b32 s59, v252, 21
	v_readlane_b32 s60, v252, 22
	v_readlane_b32 s61, v252, 23
	v_readlane_b32 s64, v252, 26
	v_readlane_b32 s65, v252, 27
	v_readlane_b32 s66, v252, 28
	v_readlane_b32 s67, v252, 29
.LBB0_186:
	s_and_b64 vcc, exec, s[0:1]
	v_or_b32_e32 v210, v111, v4
	s_movk_i32 s8, 0x3a00
	v_mad_u64_u32 v[208:209], s[8:9], v210, s8, v[2:3]
	global_load_dword v210, v[208:209], off
	s_waitcnt vmcnt(2)
	v_mul_f32_e32 v45, v45, v162
	ds_write_b32 v44, v45 offset:1056
	s_cbranch_vccnz .LBB0_188
	v_readlane_b32 s52, v252, 14
	v_readlane_b32 s62, v252, 24
	v_readlane_b32 s63, v252, 25
	v_readlane_b32 s53, v252, 15
	v_readlane_b32 s54, v252, 16
	v_readlane_b32 s55, v252, 17
	v_readlane_b32 s56, v252, 18
	v_readlane_b32 s57, v252, 19
	v_mov_b32_e32 v46, v203
	v_readlane_b32 s58, v252, 20
	v_readlane_b32 s59, v252, 21
	v_readlane_b32 s60, v252, 22
	v_readlane_b32 s61, v252, 23
	v_readlane_b32 s64, v252, 26
	v_readlane_b32 s65, v252, 27
	v_readlane_b32 s66, v252, 28
	v_readlane_b32 s67, v252, 29
.LBB0_188:
	v_mov_b32_e32 v45, 1.0
	s_and_b64 vcc, exec, s[0:1]
	s_waitcnt vmcnt(1)
	v_mul_f32_e32 v46, v46, v171
	ds_write_b32 v44, v46 offset:1320
	v_mov_b32_e32 v46, 1.0
	s_cbranch_vccnz .LBB0_190
	v_readlane_b32 s52, v252, 14
	v_readlane_b32 s62, v252, 24
	v_readlane_b32 s63, v252, 25
	v_readlane_b32 s53, v252, 15
	v_readlane_b32 s54, v252, 16
	v_readlane_b32 s55, v252, 17
	v_readlane_b32 s56, v252, 18
	v_readlane_b32 s57, v252, 19
	v_mov_b32_e32 v46, v204
	v_readlane_b32 s58, v252, 20
	v_readlane_b32 s59, v252, 21
	v_readlane_b32 s60, v252, 22
	v_readlane_b32 s61, v252, 23
	v_readlane_b32 s64, v252, 26
	v_readlane_b32 s65, v252, 27
	v_readlane_b32 s66, v252, 28
	v_readlane_b32 s67, v252, 29
.LBB0_190:
	s_and_b64 vcc, exec, s[0:1]
	v_or_b32_e32 v162, v112, v4
	s_movk_i32 s0, 0x3a00
	v_mad_u64_u32 v[160:161], s[0:1], v162, s0, v[2:3]
	global_load_dword v160, v[160:161], off
	s_waitcnt vmcnt(1)
	v_mul_f32_e32 v46, v46, v210
	ds_write_b32 v44, v46 offset:1584
	s_cbranch_vccnz .LBB0_192
	v_readlane_b32 s52, v252, 14
	v_readlane_b32 s62, v252, 24
	v_readlane_b32 s63, v252, 25
	v_readlane_b32 s53, v252, 15
	v_readlane_b32 s54, v252, 16
	v_readlane_b32 s55, v252, 17
	v_readlane_b32 s56, v252, 18
	v_readlane_b32 s57, v252, 19
	v_mov_b32_e32 v45, v205
	v_readlane_b32 s58, v252, 20
	v_readlane_b32 s59, v252, 21
	v_readlane_b32 s60, v252, 22
	v_readlane_b32 s61, v252, 23
	v_readlane_b32 s64, v252, 26
	v_readlane_b32 s65, v252, 27
	v_readlane_b32 s66, v252, 28
	v_readlane_b32 s67, v252, 29
.LBB0_192:
	v_mov_b32_e32 v3, v0
	v_mov_b32_e32 v125, v0
	s_waitcnt vmcnt(0)
	v_mul_f32_e32 v2, v45, v160
	ds_write_b32 v44, v2 offset:1848
	s_waitcnt lgkmcnt(0)
	ds_read2_b32 v[46:47], v114 offset0:33 offset1:41
	ds_read2_b32 v[48:49], v114 offset1:8
	v_lshlrev_b32_e32 v2, 1, v4
	ds_read2_b32 v[50:51], v114 offset0:66 offset1:74
	ds_read2_b32 v[52:53], v114 offset0:99 offset1:107
	v_lshl_add_u64 v[44:45], v[18:19], 0, v[2:3]
	s_waitcnt lgkmcnt(3)
	v_bfe_u32 v3, v46, 16, 1
	s_waitcnt lgkmcnt(2)
	v_bfe_u32 v2, v48, 16, 1
	v_add3_u32 v2, v48, v2, s51
	v_lshrrev_b32_e32 v2, 16, v2
	v_add3_u32 v3, v46, v3, s51
	ds_read2_b32 v[54:55], v114 offset0:132 offset1:140
	ds_read2_b32 v[56:57], v114 offset0:165 offset1:173
	v_and_or_b32 v2, v3, s33, v2
	s_waitcnt lgkmcnt(3)
	v_bfe_u32 v3, v50, 16, 1
	v_add3_u32 v3, v50, v3, s51
	s_waitcnt lgkmcnt(2)
	v_bfe_u32 v4, v52, 16, 1
	v_lshrrev_b32_e32 v3, 16, v3
	v_add3_u32 v4, v52, v4, s51
	ds_read2_b32 v[120:121], v114 offset0:198 offset1:206
	ds_read2_b32 v[122:123], v114 offset0:231 offset1:239
	v_and_or_b32 v3, v4, s33, v3
	s_waitcnt lgkmcnt(3)
	v_bfe_u32 v4, v54, 16, 1
	v_add3_u32 v4, v54, v4, s51
	s_waitcnt lgkmcnt(2)
	v_bfe_u32 v5, v56, 16, 1
	v_lshrrev_b32_e32 v4, 16, v4
	v_add3_u32 v5, v56, v5, s51
	v_and_or_b32 v4, v5, s33, v4
	s_waitcnt lgkmcnt(1)
	v_bfe_u32 v5, v120, 16, 1
	v_add3_u32 v5, v120, v5, s51
	s_waitcnt lgkmcnt(0)
	v_bfe_u32 v46, v122, 16, 1
	v_lshrrev_b32_e32 v5, 16, v5
	v_add3_u32 v46, v122, v46, s51
	v_and_or_b32 v5, v46, s33, v5
	v_or_b32_e32 v46, v113, v119
	v_lshlrev_b32_e32 v124, 11, v46
	v_lshl_add_u64 v[124:125], v[44:45], 0, v[124:125]
	global_store_dwordx4 v[124:125], v[2:5], off
	v_bfe_u32 v46, v123, 16, 1
	v_add3_u32 v46, v123, v46, s51
	v_bfe_u32 v2, v49, 16, 1
	v_add3_u32 v2, v49, v2, s51
	v_bfe_u32 v3, v47, 16, 1
	v_lshrrev_b32_e32 v2, 16, v2
	v_add3_u32 v3, v47, v3, s51
	v_and_or_b32 v2, v3, s33, v2
	v_bfe_u32 v3, v51, 16, 1
	v_add3_u32 v3, v51, v3, s51
	v_bfe_u32 v4, v53, 16, 1
	v_lshrrev_b32_e32 v3, 16, v3
	v_add3_u32 v4, v53, v4, s51
	v_and_or_b32 v3, v4, s33, v3
	v_bfe_u32 v4, v55, 16, 1
	v_add3_u32 v4, v55, v4, s51
	v_bfe_u32 v5, v57, 16, 1
	v_lshrrev_b32_e32 v4, 16, v4
	v_add3_u32 v5, v57, v5, s51
	v_and_or_b32 v4, v5, s33, v4
	v_bfe_u32 v5, v121, 16, 1
	v_add3_u32 v5, v121, v5, s51
	v_lshrrev_b32_e32 v5, 16, v5
	v_and_or_b32 v5, v46, s33, v5
	v_or_b32_e32 v46, v115, v119
	v_lshlrev_b32_e32 v46, 11, v46
	v_mov_b32_e32 v47, v0
	v_lshl_add_u64 v[46:47], v[44:45], 0, v[46:47]
	global_store_dwordx4 v[46:47], v[2:5], off
	ds_read2_b32 v[46:47], v114 offset0:49 offset1:57
	ds_read2_b32 v[48:49], v114 offset0:16 offset1:24
	ds_read2_b32 v[52:53], v114 offset0:82 offset1:90
	ds_read2_b32 v[50:51], v114 offset0:115 offset1:123
	ds_read2_b32 v[56:57], v114 offset0:148 offset1:156
	ds_read2_b32 v[54:55], v114 offset0:181 offset1:189
	ds_read2_b32 v[120:121], v114 offset0:214 offset1:222
	ds_read2_b32 v[122:123], v114 offset0:247 offset1:255
	s_waitcnt lgkmcnt(7)
	v_bfe_u32 v3, v46, 16, 1
	s_waitcnt lgkmcnt(6)
	v_bfe_u32 v2, v48, 16, 1
	v_add3_u32 v2, v48, v2, s51
	v_lshrrev_b32_e32 v2, 16, v2
	v_add3_u32 v3, v46, v3, s51
	v_and_or_b32 v2, v3, s33, v2
	s_waitcnt lgkmcnt(5)
	v_bfe_u32 v3, v52, 16, 1
	v_add3_u32 v3, v52, v3, s51
	s_waitcnt lgkmcnt(4)
	v_bfe_u32 v4, v50, 16, 1
	v_lshrrev_b32_e32 v3, 16, v3
	v_add3_u32 v4, v50, v4, s51
	v_and_or_b32 v3, v4, s33, v3
	s_waitcnt lgkmcnt(3)
	v_bfe_u32 v4, v56, 16, 1
	v_add3_u32 v4, v56, v4, s51
	s_waitcnt lgkmcnt(2)
	v_bfe_u32 v5, v54, 16, 1
	v_lshrrev_b32_e32 v4, 16, v4
	v_add3_u32 v5, v54, v5, s51
	v_and_or_b32 v4, v5, s33, v4
	s_waitcnt lgkmcnt(1)
	v_bfe_u32 v5, v120, 16, 1
	v_add3_u32 v5, v120, v5, s51
	s_waitcnt lgkmcnt(0)
	v_bfe_u32 v46, v122, 16, 1
	v_lshrrev_b32_e32 v5, 16, v5
	v_add3_u32 v46, v122, v46, s51
	v_and_or_b32 v5, v46, s33, v5
	v_or_b32_e32 v46, v116, v119
	v_lshlrev_b32_e32 v124, 11, v46
	v_mov_b32_e32 v125, v0
	v_lshl_add_u64 v[124:125], v[44:45], 0, v[124:125]
	global_store_dwordx4 v[124:125], v[2:5], off
	v_bfe_u32 v46, v123, 16, 1
	v_add3_u32 v46, v123, v46, s51
	v_bfe_u32 v2, v49, 16, 1
	v_add3_u32 v2, v49, v2, s51
	v_bfe_u32 v3, v47, 16, 1
	v_lshrrev_b32_e32 v2, 16, v2
	v_add3_u32 v3, v47, v3, s51
	v_and_or_b32 v2, v3, s33, v2
	v_bfe_u32 v3, v53, 16, 1
	v_add3_u32 v3, v53, v3, s51
	v_bfe_u32 v4, v51, 16, 1
	v_lshrrev_b32_e32 v3, 16, v3
	v_add3_u32 v4, v51, v4, s51
	v_and_or_b32 v3, v4, s33, v3
	v_bfe_u32 v4, v57, 16, 1
	v_add3_u32 v4, v57, v4, s51
	v_bfe_u32 v5, v55, 16, 1
	v_lshrrev_b32_e32 v4, 16, v4
	v_add3_u32 v5, v55, v5, s51
	v_and_or_b32 v4, v5, s33, v4
	v_bfe_u32 v5, v121, 16, 1
	v_add3_u32 v5, v121, v5, s51
	v_lshrrev_b32_e32 v5, 16, v5
	v_and_or_b32 v5, v46, s33, v5
	v_or_b32_e32 v46, v117, v119
	v_lshlrev_b32_e32 v46, 11, v46
	v_mov_b32_e32 v47, v0
	v_lshl_add_u64 v[44:45], v[44:45], 0, v[46:47]
	global_store_dwordx4 v[44:45], v[2:5], off
	s_waitcnt lgkmcnt(0)

.LBB0_194:
	s_andn2_saveexec_b64 s[0:1], s[28:29]
	s_cbranch_execz .LBB0_196
	v_add_u32_e32 v2, 0x1d80, v118
	v_and_b32_e32 v4, 0x3e0, v42
	v_and_b32_e32 v5, 0x1ffc0, v2
	v_lshlrev_b32_e32 v2, 2, v4
	v_mov_b32_e32 v3, v0
	v_or_b32_e32 v44, v5, v8
	v_lshl_add_u64 v[2:3], v[34:35], 0, v[2:3]
	v_lshlrev_b32_e32 v44, 12, v44
	v_mov_b32_e32 v45, v0
	v_lshl_add_u64 v[44:45], v[2:3], 0, v[44:45]
	global_load_dword v46, v[44:45], off
	v_or_b32_e32 v44, v5, v58
	v_lshlrev_b32_e32 v44, 12, v44
	v_mov_b32_e32 v45, v0
	v_lshl_add_u64 v[44:45], v[2:3], 0, v[44:45]
	global_load_dword v44, v[44:45], off
	v_add_u32_e32 v47, v7, v13
	v_mov_b32_e32 v45, v0
	v_mov_b32_e32 v127, v0
	v_or_b32_e32 v208, v5, v60
	v_lshlrev_b32_e32 v208, 12, v208
	v_mov_b32_e32 v209, v0
	v_lshl_add_u64 v[208:209], v[2:3], 0, v[208:209]
	global_load_dword v210, v[208:209], off
	v_or_b32_e32 v208, v5, v62
	v_lshlrev_b32_e32 v208, 12, v208
	v_mov_b32_e32 v209, v0
	v_lshl_add_u64 v[208:209], v[2:3], 0, v[208:209]
	global_load_dword v208, v[208:209], off
	v_or_b32_e32 v160, v5, v64
	v_lshlrev_b32_e32 v160, 12, v160
	v_mov_b32_e32 v161, v0
	v_lshl_add_u64 v[160:161], v[2:3], 0, v[160:161]
	global_load_dword v162, v[160:161], off
	v_or_b32_e32 v160, v5, v66
	v_lshlrev_b32_e32 v160, 12, v160
	v_mov_b32_e32 v161, v0
	v_lshl_add_u64 v[160:161], v[2:3], 0, v[160:161]
	global_load_dword v160, v[160:161], off
	s_waitcnt vmcnt(4)
	ds_write2_b32 v47, v46, v44 offset1:66
	v_mov_b32_e32 v45, v0
	v_or_b32_e32 v168, v5, v68
	v_lshlrev_b32_e32 v168, 12, v168
	v_mov_b32_e32 v169, v0
	v_lshl_add_u64 v[168:169], v[2:3], 0, v[168:169]
	global_load_dword v170, v[168:169], off
	v_or_b32_e32 v168, v5, v70
	v_lshlrev_b32_e32 v168, 12, v168
	v_mov_b32_e32 v169, v0
	v_lshl_add_u64 v[168:169], v[2:3], 0, v[168:169]
	global_load_dword v168, v[168:169], off
	s_waitcnt vmcnt(4)
	ds_write2_b32 v47, v210, v208 offset0:132 offset1:198
	v_add_u32_e32 v45, 0x400, v47
	v_add_u32_e32 v47, v7, v69
	v_or_b32_e32 v208, v5, v72
	v_lshlrev_b32_e32 v208, 12, v208
	v_mov_b32_e32 v209, v0
	v_lshl_add_u64 v[208:209], v[2:3], 0, v[208:209]
	global_load_dword v210, v[208:209], off
	v_or_b32_e32 v208, v5, v74
	v_lshlrev_b32_e32 v208, 12, v208
	v_mov_b32_e32 v209, v0
	v_lshl_add_u64 v[208:209], v[2:3], 0, v[208:209]
	global_load_dword v208, v[208:209], off
	s_waitcnt vmcnt(4)
	ds_write2_b32 v45, v162, v160 offset0:8 offset1:74
	v_mov_b32_e32 v45, v0
	v_or_b32_e32 v160, v5, v76
	v_lshlrev_b32_e32 v160, 12, v160
	v_mov_b32_e32 v161, v0
	v_lshl_add_u64 v[160:161], v[2:3], 0, v[160:161]
	global_load_dword v162, v[160:161], off
	v_or_b32_e32 v160, v5, v78
	v_lshlrev_b32_e32 v160, 12, v160
	v_mov_b32_e32 v161, v0
	v_lshl_add_u64 v[160:161], v[2:3], 0, v[160:161]
	global_load_dword v160, v[160:161], off
	s_waitcnt vmcnt(4)
	ds_write2_b32 v47, v170, v168 offset1:66
	v_mov_b32_e32 v45, v0
	v_or_b32_e32 v168, v5, v80
	v_lshlrev_b32_e32 v168, 12, v168
	v_mov_b32_e32 v169, v0
	v_lshl_add_u64 v[168:169], v[2:3], 0, v[168:169]
	global_load_dword v170, v[168:169], off
	v_or_b32_e32 v168, v5, v82
	v_lshlrev_b32_e32 v168, 12, v168
	v_mov_b32_e32 v169, v0
	v_lshl_add_u64 v[168:169], v[2:3], 0, v[168:169]
	global_load_dword v168, v[168:169], off
	s_waitcnt vmcnt(4)
	ds_write2_b32 v47, v210, v208 offset0:132 offset1:198
	v_add_u32_e32 v45, 0x400, v47
	v_add_u32_e32 v47, v7, v81
	v_or_b32_e32 v208, v5, v84
	v_lshlrev_b32_e32 v208, 12, v208
	v_mov_b32_e32 v209, v0
	v_lshl_add_u64 v[208:209], v[2:3], 0, v[208:209]
	global_load_dword v210, v[208:209], off
	v_or_b32_e32 v208, v5, v86
	v_lshlrev_b32_e32 v208, 12, v208
	v_mov_b32_e32 v209, v0
	v_lshl_add_u64 v[208:209], v[2:3], 0, v[208:209]
	global_load_dword v208, v[208:209], off
	s_waitcnt vmcnt(4)
	ds_write2_b32 v45, v162, v160 offset0:8 offset1:74
	v_mov_b32_e32 v45, v0
	v_or_b32_e32 v160, v5, v88
	v_lshlrev_b32_e32 v160, 12, v160
	v_mov_b32_e32 v161, v0
	v_lshl_add_u64 v[160:161], v[2:3], 0, v[160:161]
	global_load_dword v162, v[160:161], off
	v_or_b32_e32 v160, v5, v90
	v_lshlrev_b32_e32 v160, 12, v160
	v_mov_b32_e32 v161, v0
	v_lshl_add_u64 v[160:161], v[2:3], 0, v[160:161]
	global_load_dword v160, v[160:161], off
	s_waitcnt vmcnt(4)
	ds_write2_b32 v47, v170, v168 offset1:66
	v_mov_b32_e32 v45, v0
	v_or_b32_e32 v168, v5, v92
	v_lshlrev_b32_e32 v168, 12, v168
	v_mov_b32_e32 v169, v0
	v_lshl_add_u64 v[168:169], v[2:3], 0, v[168:169]
	global_load_dword v170, v[168:169], off
	v_or_b32_e32 v168, v5, v94
	v_lshlrev_b32_e32 v168, 12, v168
	v_mov_b32_e32 v169, v0
	v_lshl_add_u64 v[168:169], v[2:3], 0, v[168:169]
	global_load_dword v168, v[168:169], off
	s_waitcnt vmcnt(4)
	ds_write2_b32 v47, v210, v208 offset0:132 offset1:198
	v_add_u32_e32 v45, 0x400, v47
	v_add_u32_e32 v47, v7, v93
	v_or_b32_e32 v208, v5, v96
	v_lshlrev_b32_e32 v208, 12, v208
	v_mov_b32_e32 v209, v0
	v_lshl_add_u64 v[208:209], v[2:3], 0, v[208:209]
	global_load_dword v210, v[208:209], off
	v_or_b32_e32 v208, v5, v98
	v_lshlrev_b32_e32 v208, 12, v208
	v_mov_b32_e32 v209, v0
	v_lshl_add_u64 v[208:209], v[2:3], 0, v[208:209]
	global_load_dword v208, v[208:209], off
	s_waitcnt vmcnt(4)
	ds_write2_b32 v45, v162, v160 offset0:8 offset1:74
	v_mov_b32_e32 v45, v0
	v_or_b32_e32 v160, v5, v100
	v_lshlrev_b32_e32 v160, 12, v160
	v_mov_b32_e32 v161, v0
	v_lshl_add_u64 v[160:161], v[2:3], 0, v[160:161]
	global_load_dword v162, v[160:161], off
	v_or_b32_e32 v160, v5, v102
	v_lshlrev_b32_e32 v160, 12, v160
	v_mov_b32_e32 v161, v0
	v_lshl_add_u64 v[160:161], v[2:3], 0, v[160:161]
	global_load_dword v160, v[160:161], off
	s_waitcnt vmcnt(4)
	ds_write2_b32 v47, v170, v168 offset1:66
	v_mov_b32_e32 v45, v0
	v_or_b32_e32 v168, v5, v104
	v_lshlrev_b32_e32 v168, 12, v168
	v_mov_b32_e32 v169, v0
	v_lshl_add_u64 v[168:169], v[2:3], 0, v[168:169]
	global_load_dword v170, v[168:169], off
	v_or_b32_e32 v168, v5, v106
	v_lshlrev_b32_e32 v168, 12, v168
	v_mov_b32_e32 v169, v0
	v_lshl_add_u64 v[168:169], v[2:3], 0, v[168:169]
	global_load_dword v168, v[168:169], off
	s_waitcnt vmcnt(4)
	ds_write2_b32 v47, v210, v208 offset0:132 offset1:198
	v_add_u32_e32 v45, 0x400, v47
	v_add_u32_e32 v47, v7, v105
	v_or_b32_e32 v208, v5, v107
	v_lshlrev_b32_e32 v208, 12, v208
	v_mov_b32_e32 v209, v0
	v_lshl_add_u64 v[208:209], v[2:3], 0, v[208:209]
	global_load_dword v210, v[208:209], off
	v_or_b32_e32 v208, v5, v108
	v_lshlrev_b32_e32 v208, 12, v208
	v_mov_b32_e32 v209, v0
	v_lshl_add_u64 v[208:209], v[2:3], 0, v[208:209]
	global_load_dword v208, v[208:209], off
	s_waitcnt vmcnt(4)
	ds_write2_b32 v45, v162, v160 offset0:8 offset1:74
	v_mov_b32_e32 v45, v0
	v_or_b32_e32 v160, v5, v109
	v_lshlrev_b32_e32 v160, 12, v160
	v_mov_b32_e32 v161, v0
	v_lshl_add_u64 v[160:161], v[2:3], 0, v[160:161]
	global_load_dword v162, v[160:161], off
	v_or_b32_e32 v160, v5, v110
	v_lshlrev_b32_e32 v160, 12, v160
	v_mov_b32_e32 v161, v0
	v_lshl_add_u64 v[160:161], v[2:3], 0, v[160:161]
	global_load_dword v160, v[160:161], off
	s_waitcnt vmcnt(4)
	ds_write2_b32 v47, v170, v168 offset1:66
	v_mov_b32_e32 v45, v0
	v_or_b32_e32 v170, v5, v111
	v_lshlrev_b32_e32 v170, 12, v170
	v_mov_b32_e32 v171, v0
	v_lshl_add_u64 v[170:171], v[2:3], 0, v[170:171]
	global_load_dword v172, v[170:171], off
	v_or_b32_e32 v170, v5, v112
	v_lshlrev_b32_e32 v170, 12, v170
	v_mov_b32_e32 v171, v0
	v_lshl_add_u64 v[168:169], v[2:3], 0, v[170:171]
	global_load_dword v168, v[168:169], off
	s_waitcnt vmcnt(4)
	ds_write2_b32 v47, v210, v208 offset0:132 offset1:198
	v_add_u32_e32 v47, 0x400, v47
	v_mov_b32_e32 v45, v0
	s_waitcnt vmcnt(2)
	ds_write2_b32 v47, v162, v160 offset0:8 offset1:74
	v_mov_b32_e32 v3, v0
	s_waitcnt vmcnt(0)
	ds_write2_b32 v47, v172, v168 offset0:140 offset1:206
	s_waitcnt lgkmcnt(0)
	ds_read2_b32 v[48:49], v114 offset0:33 offset1:41
	ds_read2_b32 v[50:51], v114 offset1:8
	ds_read2_b32 v[52:53], v114 offset0:66 offset1:74
	ds_read2_b32 v[54:55], v114 offset0:99 offset1:107
	v_lshlrev_b32_e32 v2, 1, v5
	ds_read2_b32 v[56:57], v114 offset0:132 offset1:140
	ds_read2_b32 v[120:121], v114 offset0:165 offset1:173
	s_waitcnt lgkmcnt(5)
	v_bfe_u32 v44, v48, 16, 1
	s_waitcnt lgkmcnt(4)
	v_bfe_u32 v5, v50, 16, 1
	v_add3_u32 v5, v50, v5, s51
	v_lshrrev_b32_e32 v5, 16, v5
	v_add3_u32 v44, v48, v44, s51
	v_and_or_b32 v44, v44, s33, v5
	s_waitcnt lgkmcnt(3)
	v_bfe_u32 v5, v52, 16, 1
	v_add3_u32 v5, v52, v5, s51
	s_waitcnt lgkmcnt(2)
	v_bfe_u32 v45, v54, 16, 1
	v_lshrrev_b32_e32 v5, 16, v5
	v_add3_u32 v45, v54, v45, s51
	ds_read2_b32 v[122:123], v114 offset0:198 offset1:206
	ds_read2_b32 v[124:125], v114 offset0:231 offset1:239
	v_and_or_b32 v45, v45, s33, v5
	s_waitcnt lgkmcnt(3)
	v_bfe_u32 v5, v56, 16, 1
	v_add3_u32 v5, v56, v5, s51
	s_waitcnt lgkmcnt(2)
	v_bfe_u32 v46, v120, 16, 1
	v_lshrrev_b32_e32 v5, 16, v5
	v_add3_u32 v46, v120, v46, s51
	v_and_or_b32 v46, v46, s33, v5
	s_waitcnt lgkmcnt(1)
	v_bfe_u32 v5, v122, 16, 1
	v_add3_u32 v5, v122, v5, s51
	s_waitcnt lgkmcnt(0)
	v_bfe_u32 v47, v124, 16, 1
	v_lshrrev_b32_e32 v5, 16, v5
	v_add3_u32 v47, v124, v47, s51
	v_and_or_b32 v47, v47, s33, v5
	v_or_b32_e32 v5, v4, v113
	v_mul_u32_u24_e32 v5, 0xb00, v5
	v_lshl_add_u64 v[2:3], v[20:21], 0, v[2:3]
	v_lshlrev_b32_e32 v126, 1, v5
	v_lshl_add_u64 v[126:127], v[2:3], 0, v[126:127]
	v_bfe_u32 v5, v51, 16, 1
	global_store_dwordx4 v[126:127], v[44:47], off
	v_add3_u32 v5, v51, v5, s51
	v_lshrrev_b32_e32 v5, 16, v5
	v_bfe_u32 v44, v49, 16, 1
	v_add3_u32 v44, v49, v44, s51
	v_and_or_b32 v44, v44, s33, v5
	v_bfe_u32 v5, v53, 16, 1
	v_add3_u32 v5, v53, v5, s51
	v_bfe_u32 v45, v55, 16, 1
	v_lshrrev_b32_e32 v5, 16, v5
	v_add3_u32 v45, v55, v45, s51
	v_and_or_b32 v45, v45, s33, v5
	v_bfe_u32 v5, v57, 16, 1
	v_add3_u32 v5, v57, v5, s51
	v_bfe_u32 v46, v121, 16, 1
	v_lshrrev_b32_e32 v5, 16, v5
	v_add3_u32 v46, v121, v46, s51
	v_and_or_b32 v46, v46, s33, v5
	v_bfe_u32 v5, v123, 16, 1
	v_add3_u32 v5, v123, v5, s51
	v_bfe_u32 v47, v125, 16, 1
	v_lshrrev_b32_e32 v5, 16, v5
	v_add3_u32 v47, v125, v47, s51
	v_and_or_b32 v47, v47, s33, v5
	v_or_b32_e32 v5, v4, v115
	v_mul_u32_u24_e32 v5, 0xb00, v5
	v_lshlrev_b32_e32 v48, 1, v5
	v_mov_b32_e32 v49, v0
	v_lshl_add_u64 v[48:49], v[2:3], 0, v[48:49]
	global_store_dwordx4 v[48:49], v[44:47], off
	ds_read2_b32 v[48:49], v114 offset0:16 offset1:24
	ds_read2_b32 v[50:51], v114 offset0:49 offset1:57
	ds_read2_b32 v[52:53], v114 offset0:82 offset1:90
	ds_read2_b32 v[54:55], v114 offset0:115 offset1:123
	ds_read2_b32 v[56:57], v114 offset0:148 offset1:156
	ds_read2_b32 v[120:121], v114 offset0:181 offset1:189
	ds_read2_b32 v[122:123], v114 offset0:214 offset1:222
	ds_read2_b32 v[124:125], v114 offset0:247 offset1:255
	s_waitcnt lgkmcnt(7)
	v_bfe_u32 v5, v48, 16, 1
	v_add3_u32 v5, v48, v5, s51
	s_waitcnt lgkmcnt(6)
	v_bfe_u32 v44, v50, 16, 1
	v_lshrrev_b32_e32 v5, 16, v5
	v_add3_u32 v44, v50, v44, s51
	v_and_or_b32 v44, v44, s33, v5
	s_waitcnt lgkmcnt(5)
	v_bfe_u32 v5, v52, 16, 1
	v_add3_u32 v5, v52, v5, s51
	s_waitcnt lgkmcnt(4)
	v_bfe_u32 v45, v54, 16, 1
	v_lshrrev_b32_e32 v5, 16, v5
	v_add3_u32 v45, v54, v45, s51
	v_and_or_b32 v45, v45, s33, v5
	s_waitcnt lgkmcnt(3)
	v_bfe_u32 v5, v56, 16, 1
	v_add3_u32 v5, v56, v5, s51
	s_waitcnt lgkmcnt(2)
	v_bfe_u32 v46, v120, 16, 1
	v_lshrrev_b32_e32 v5, 16, v5
	v_add3_u32 v46, v120, v46, s51
	v_and_or_b32 v46, v46, s33, v5
	s_waitcnt lgkmcnt(1)
	v_bfe_u32 v5, v122, 16, 1
	v_add3_u32 v5, v122, v5, s51
	s_waitcnt lgkmcnt(0)
	v_bfe_u32 v47, v124, 16, 1
	v_lshrrev_b32_e32 v5, 16, v5
	v_add3_u32 v47, v124, v47, s51
	v_and_or_b32 v47, v47, s33, v5
	v_or_b32_e32 v5, v4, v116
	v_mul_u32_u24_e32 v5, 0xb00, v5
	v_lshlrev_b32_e32 v126, 1, v5
	v_mov_b32_e32 v127, v0
	v_lshl_add_u64 v[126:127], v[2:3], 0, v[126:127]
	v_bfe_u32 v5, v49, 16, 1
	global_store_dwordx4 v[126:127], v[44:47], off
	v_add3_u32 v5, v49, v5, s51
	v_lshrrev_b32_e32 v5, 16, v5
	v_bfe_u32 v44, v51, 16, 1
	v_add3_u32 v44, v51, v44, s51
	v_and_or_b32 v44, v44, s33, v5
	v_bfe_u32 v5, v53, 16, 1
	v_add3_u32 v5, v53, v5, s51
	v_bfe_u32 v45, v55, 16, 1
	v_lshrrev_b32_e32 v5, 16, v5
	v_add3_u32 v45, v55, v45, s51
	v_and_or_b32 v45, v45, s33, v5
	v_bfe_u32 v5, v57, 16, 1
	v_add3_u32 v5, v57, v5, s51
	v_bfe_u32 v46, v121, 16, 1
	v_lshrrev_b32_e32 v5, 16, v5
	v_add3_u32 v46, v121, v46, s51
	v_and_or_b32 v46, v46, s33, v5
	v_bfe_u32 v5, v123, 16, 1
	v_add3_u32 v5, v123, v5, s51
	v_bfe_u32 v47, v125, 16, 1
	v_or_b32_e32 v4, v4, v117
	v_lshrrev_b32_e32 v5, 16, v5
	v_add3_u32 v47, v125, v47, s51
	v_mul_u32_u24_e32 v4, 0xb00, v4
	v_and_or_b32 v47, v47, s33, v5
	v_lshlrev_b32_e32 v4, 1, v4
	v_mov_b32_e32 v5, v0
	v_lshl_add_u64 v[2:3], v[2:3], 0, v[4:5]
	global_store_dwordx4 v[2:3], v[44:47], off
	s_waitcnt lgkmcnt(0)

.LBB0_197:
	s_andn2_saveexec_b64 s[0:1], s[26:27]
	s_cbranch_execz .LBB0_199
	v_add_u32_e32 v2, 0x2880, v118
	v_and_b32_e32 v4, 0x3e0, v42
	v_and_b32_e32 v5, 0x1ffc0, v2
	v_lshlrev_b32_e32 v2, 2, v4
	v_mov_b32_e32 v3, v0
	v_or_b32_e32 v44, v5, v8
	v_lshl_add_u64 v[2:3], v[36:37], 0, v[2:3]
	v_lshlrev_b32_e32 v44, 12, v44
	v_mov_b32_e32 v45, v0
	v_lshl_add_u64 v[44:45], v[2:3], 0, v[44:45]
	global_load_dword v46, v[44:45], off
	v_or_b32_e32 v44, v5, v58
	v_lshlrev_b32_e32 v44, 12, v44
	v_mov_b32_e32 v45, v0
	v_lshl_add_u64 v[44:45], v[2:3], 0, v[44:45]
	global_load_dword v44, v[44:45], off
	v_add_u32_e32 v47, v7, v13
	v_mov_b32_e32 v45, v0
	v_mov_b32_e32 v127, v0
	v_or_b32_e32 v160, v5, v60
	v_lshlrev_b32_e32 v160, 12, v160
	v_mov_b32_e32 v161, v0
	v_lshl_add_u64 v[160:161], v[2:3], 0, v[160:161]
	global_load_dword v162, v[160:161], off
	v_or_b32_e32 v160, v5, v62
	v_lshlrev_b32_e32 v160, 12, v160
	v_mov_b32_e32 v161, v0
	v_lshl_add_u64 v[160:161], v[2:3], 0, v[160:161]
	global_load_dword v160, v[160:161], off
	v_or_b32_e32 v168, v5, v64
	v_lshlrev_b32_e32 v168, 12, v168
	v_mov_b32_e32 v169, v0
	v_lshl_add_u64 v[168:169], v[2:3], 0, v[168:169]
	global_load_dword v170, v[168:169], off
	v_or_b32_e32 v168, v5, v66
	v_lshlrev_b32_e32 v168, 12, v168
	v_mov_b32_e32 v169, v0
	v_lshl_add_u64 v[168:169], v[2:3], 0, v[168:169]
	global_load_dword v168, v[168:169], off
	s_waitcnt vmcnt(4)
	ds_write2_b32 v47, v46, v44 offset1:66
	v_mov_b32_e32 v45, v0
	v_or_b32_e32 v208, v5, v68
	v_lshlrev_b32_e32 v208, 12, v208
	v_mov_b32_e32 v209, v0
	v_lshl_add_u64 v[208:209], v[2:3], 0, v[208:209]
	global_load_dword v210, v[208:209], off
	v_or_b32_e32 v208, v5, v70
	v_lshlrev_b32_e32 v208, 12, v208
	v_mov_b32_e32 v209, v0
	v_lshl_add_u64 v[208:209], v[2:3], 0, v[208:209]
	global_load_dword v208, v[208:209], off
	s_waitcnt vmcnt(4)
	ds_write2_b32 v47, v162, v160 offset0:132 offset1:198
	v_add_u32_e32 v45, 0x400, v47
	v_add_u32_e32 v47, v7, v69
	v_or_b32_e32 v160, v5, v72
	v_lshlrev_b32_e32 v160, 12, v160
	v_mov_b32_e32 v161, v0
	v_lshl_add_u64 v[160:161], v[2:3], 0, v[160:161]
	global_load_dword v162, v[160:161], off
	v_or_b32_e32 v160, v5, v74
	v_lshlrev_b32_e32 v160, 12, v160
	v_mov_b32_e32 v161, v0
	v_lshl_add_u64 v[160:161], v[2:3], 0, v[160:161]
	global_load_dword v160, v[160:161], off
	s_waitcnt vmcnt(4)
	ds_write2_b32 v45, v170, v168 offset0:8 offset1:74
	v_mov_b32_e32 v45, v0
	v_or_b32_e32 v168, v5, v76
	v_lshlrev_b32_e32 v168, 12, v168
	v_mov_b32_e32 v169, v0
	v_lshl_add_u64 v[168:169], v[2:3], 0, v[168:169]
	global_load_dword v170, v[168:169], off
	v_or_b32_e32 v168, v5, v78
	v_lshlrev_b32_e32 v168, 12, v168
	v_mov_b32_e32 v169, v0
	v_lshl_add_u64 v[168:169], v[2:3], 0, v[168:169]
	global_load_dword v168, v[168:169], off
	s_waitcnt vmcnt(4)
	ds_write2_b32 v47, v210, v208 offset1:66
	v_mov_b32_e32 v45, v0
	v_or_b32_e32 v208, v5, v80
	v_lshlrev_b32_e32 v208, 12, v208
	v_mov_b32_e32 v209, v0
	v_lshl_add_u64 v[208:209], v[2:3], 0, v[208:209]
	global_load_dword v210, v[208:209], off
	v_or_b32_e32 v208, v5, v82
	v_lshlrev_b32_e32 v208, 12, v208
	v_mov_b32_e32 v209, v0
	v_lshl_add_u64 v[208:209], v[2:3], 0, v[208:209]
	global_load_dword v208, v[208:209], off
	s_waitcnt vmcnt(4)
	ds_write2_b32 v47, v162, v160 offset0:132 offset1:198
	v_add_u32_e32 v45, 0x400, v47
	v_add_u32_e32 v47, v7, v81
	v_or_b32_e32 v160, v5, v84
	v_lshlrev_b32_e32 v160, 12, v160
	v_mov_b32_e32 v161, v0
	v_lshl_add_u64 v[160:161], v[2:3], 0, v[160:161]
	global_load_dword v162, v[160:161], off
	v_or_b32_e32 v160, v5, v86
	v_lshlrev_b32_e32 v160, 12, v160
	v_mov_b32_e32 v161, v0
	v_lshl_add_u64 v[160:161], v[2:3], 0, v[160:161]
	global_load_dword v160, v[160:161], off
	s_waitcnt vmcnt(4)
	ds_write2_b32 v45, v170, v168 offset0:8 offset1:74
	v_mov_b32_e32 v45, v0
	v_or_b32_e32 v168, v5, v88
	v_lshlrev_b32_e32 v168, 12, v168
	v_mov_b32_e32 v169, v0
	v_lshl_add_u64 v[168:169], v[2:3], 0, v[168:169]
	global_load_dword v170, v[168:169], off
	v_or_b32_e32 v168, v5, v90
	v_lshlrev_b32_e32 v168, 12, v168
	v_mov_b32_e32 v169, v0
	v_lshl_add_u64 v[168:169], v[2:3], 0, v[168:169]
	global_load_dword v168, v[168:169], off
	s_waitcnt vmcnt(4)
	ds_write2_b32 v47, v210, v208 offset1:66
	v_mov_b32_e32 v45, v0
	v_or_b32_e32 v208, v5, v92
	v_lshlrev_b32_e32 v208, 12, v208
	v_mov_b32_e32 v209, v0
	v_lshl_add_u64 v[208:209], v[2:3], 0, v[208:209]
	global_load_dword v210, v[208:209], off
	v_or_b32_e32 v208, v5, v94
	v_lshlrev_b32_e32 v208, 12, v208
	v_mov_b32_e32 v209, v0
	v_lshl_add_u64 v[208:209], v[2:3], 0, v[208:209]
	global_load_dword v208, v[208:209], off
	s_waitcnt vmcnt(4)
	ds_write2_b32 v47, v162, v160 offset0:132 offset1:198
	v_add_u32_e32 v45, 0x400, v47
	v_add_u32_e32 v47, v7, v93
	v_or_b32_e32 v160, v5, v96
	v_lshlrev_b32_e32 v160, 12, v160
	v_mov_b32_e32 v161, v0
	v_lshl_add_u64 v[160:161], v[2:3], 0, v[160:161]
	global_load_dword v162, v[160:161], off
	v_or_b32_e32 v160, v5, v98
	v_lshlrev_b32_e32 v160, 12, v160
	v_mov_b32_e32 v161, v0
	v_lshl_add_u64 v[160:161], v[2:3], 0, v[160:161]
	global_load_dword v160, v[160:161], off
	s_waitcnt vmcnt(4)
	ds_write2_b32 v45, v170, v168 offset0:8 offset1:74
	v_mov_b32_e32 v45, v0
	v_or_b32_e32 v168, v5, v100
	v_lshlrev_b32_e32 v168, 12, v168
	v_mov_b32_e32 v169, v0
	v_lshl_add_u64 v[168:169], v[2:3], 0, v[168:169]
	global_load_dword v170, v[168:169], off
	v_or_b32_e32 v168, v5, v102
	v_lshlrev_b32_e32 v168, 12, v168
	v_mov_b32_e32 v169, v0
	v_lshl_add_u64 v[168:169], v[2:3], 0, v[168:169]
	global_load_dword v168, v[168:169], off
	s_waitcnt vmcnt(4)
	ds_write2_b32 v47, v210, v208 offset1:66
	v_mov_b32_e32 v45, v0
	v_or_b32_e32 v208, v5, v104
	v_lshlrev_b32_e32 v208, 12, v208
	v_mov_b32_e32 v209, v0
	v_lshl_add_u64 v[208:209], v[2:3], 0, v[208:209]
	global_load_dword v210, v[208:209], off
	v_or_b32_e32 v208, v5, v106
	v_lshlrev_b32_e32 v208, 12, v208
	v_mov_b32_e32 v209, v0
	v_lshl_add_u64 v[208:209], v[2:3], 0, v[208:209]
	global_load_dword v208, v[208:209], off
	s_waitcnt vmcnt(4)
	ds_write2_b32 v47, v162, v160 offset0:132 offset1:198
	v_add_u32_e32 v45, 0x400, v47
	v_add_u32_e32 v47, v7, v105
	v_or_b32_e32 v160, v5, v107
	v_lshlrev_b32_e32 v160, 12, v160
	v_mov_b32_e32 v161, v0
	v_lshl_add_u64 v[160:161], v[2:3], 0, v[160:161]
	global_load_dword v162, v[160:161], off
	v_or_b32_e32 v160, v5, v108
	v_lshlrev_b32_e32 v160, 12, v160
	v_mov_b32_e32 v161, v0
	v_lshl_add_u64 v[160:161], v[2:3], 0, v[160:161]
	global_load_dword v160, v[160:161], off
	s_waitcnt vmcnt(4)
	ds_write2_b32 v45, v170, v168 offset0:8 offset1:74
	v_mov_b32_e32 v45, v0
	v_or_b32_e32 v168, v5, v109
	v_lshlrev_b32_e32 v168, 12, v168
	v_mov_b32_e32 v169, v0
	v_lshl_add_u64 v[168:169], v[2:3], 0, v[168:169]
	global_load_dword v170, v[168:169], off
	v_or_b32_e32 v168, v5, v110
	v_lshlrev_b32_e32 v168, 12, v168
	v_mov_b32_e32 v169, v0
	v_lshl_add_u64 v[168:169], v[2:3], 0, v[168:169]
	global_load_dword v168, v[168:169], off
	s_waitcnt vmcnt(4)
	ds_write2_b32 v47, v210, v208 offset1:66
	v_mov_b32_e32 v45, v0
	v_or_b32_e32 v210, v5, v111
	v_lshlrev_b32_e32 v210, 12, v210
	v_mov_b32_e32 v211, v0
	v_lshl_add_u64 v[210:211], v[2:3], 0, v[210:211]
	global_load_dword v212, v[210:211], off
	v_or_b32_e32 v210, v5, v112
	v_lshlrev_b32_e32 v210, 12, v210
	v_mov_b32_e32 v211, v0
	v_lshl_add_u64 v[208:209], v[2:3], 0, v[210:211]
	global_load_dword v208, v[208:209], off
	s_waitcnt vmcnt(4)
	ds_write2_b32 v47, v162, v160 offset0:132 offset1:198
	v_add_u32_e32 v47, 0x400, v47
	v_mov_b32_e32 v45, v0
	s_waitcnt vmcnt(2)
	ds_write2_b32 v47, v170, v168 offset0:8 offset1:74
	v_mov_b32_e32 v3, v0
	s_waitcnt vmcnt(0)
	ds_write2_b32 v47, v212, v208 offset0:140 offset1:206
	s_waitcnt lgkmcnt(0)
	ds_read2_b32 v[48:49], v114 offset0:33 offset1:41
	ds_read2_b32 v[50:51], v114 offset1:8
	ds_read2_b32 v[52:53], v114 offset0:66 offset1:74
	ds_read2_b32 v[54:55], v114 offset0:99 offset1:107
	v_lshlrev_b32_e32 v2, 1, v5
	ds_read2_b32 v[56:57], v114 offset0:132 offset1:140
	ds_read2_b32 v[120:121], v114 offset0:165 offset1:173
	s_waitcnt lgkmcnt(5)
	v_bfe_u32 v44, v48, 16, 1
	s_waitcnt lgkmcnt(4)
	v_bfe_u32 v5, v50, 16, 1
	v_add3_u32 v5, v50, v5, s51
	v_lshrrev_b32_e32 v5, 16, v5
	v_add3_u32 v44, v48, v44, s51
	v_and_or_b32 v44, v44, s33, v5
	s_waitcnt lgkmcnt(3)
	v_bfe_u32 v5, v52, 16, 1
	v_add3_u32 v5, v52, v5, s51
	s_waitcnt lgkmcnt(2)
	v_bfe_u32 v45, v54, 16, 1
	v_lshrrev_b32_e32 v5, 16, v5
	v_add3_u32 v45, v54, v45, s51
	ds_read2_b32 v[122:123], v114 offset0:198 offset1:206
	ds_read2_b32 v[124:125], v114 offset0:231 offset1:239
	v_and_or_b32 v45, v45, s33, v5
	s_waitcnt lgkmcnt(3)
	v_bfe_u32 v5, v56, 16, 1
	v_add3_u32 v5, v56, v5, s51
	s_waitcnt lgkmcnt(2)
	v_bfe_u32 v46, v120, 16, 1
	v_lshrrev_b32_e32 v5, 16, v5
	v_add3_u32 v46, v120, v46, s51
	v_and_or_b32 v46, v46, s33, v5
	s_waitcnt lgkmcnt(1)
	v_bfe_u32 v5, v122, 16, 1
	v_add3_u32 v5, v122, v5, s51
	s_waitcnt lgkmcnt(0)
	v_bfe_u32 v47, v124, 16, 1
	v_lshrrev_b32_e32 v5, 16, v5
	v_add3_u32 v47, v124, v47, s51
	v_and_or_b32 v47, v47, s33, v5
	v_or_b32_e32 v5, v4, v113
	v_mul_u32_u24_e32 v5, 0xb00, v5
	v_lshl_add_u64 v[2:3], v[22:23], 0, v[2:3]
	v_lshlrev_b32_e32 v126, 1, v5
	v_lshl_add_u64 v[126:127], v[2:3], 0, v[126:127]
	v_bfe_u32 v5, v51, 16, 1
	global_store_dwordx4 v[126:127], v[44:47], off
	v_add3_u32 v5, v51, v5, s51
	v_lshrrev_b32_e32 v5, 16, v5
	v_bfe_u32 v44, v49, 16, 1
	v_add3_u32 v44, v49, v44, s51
	v_and_or_b32 v44, v44, s33, v5
	v_bfe_u32 v5, v53, 16, 1
	v_add3_u32 v5, v53, v5, s51
	v_bfe_u32 v45, v55, 16, 1
	v_lshrrev_b32_e32 v5, 16, v5
	v_add3_u32 v45, v55, v45, s51
	v_and_or_b32 v45, v45, s33, v5
	v_bfe_u32 v5, v57, 16, 1
	v_add3_u32 v5, v57, v5, s51
	v_bfe_u32 v46, v121, 16, 1
	v_lshrrev_b32_e32 v5, 16, v5
	v_add3_u32 v46, v121, v46, s51
	v_and_or_b32 v46, v46, s33, v5
	v_bfe_u32 v5, v123, 16, 1
	v_add3_u32 v5, v123, v5, s51
	v_bfe_u32 v47, v125, 16, 1
	v_lshrrev_b32_e32 v5, 16, v5
	v_add3_u32 v47, v125, v47, s51
	v_and_or_b32 v47, v47, s33, v5
	v_or_b32_e32 v5, v4, v115
	v_mul_u32_u24_e32 v5, 0xb00, v5
	v_lshlrev_b32_e32 v48, 1, v5
	v_mov_b32_e32 v49, v0
	v_lshl_add_u64 v[48:49], v[2:3], 0, v[48:49]
	global_store_dwordx4 v[48:49], v[44:47], off
	ds_read2_b32 v[48:49], v114 offset0:16 offset1:24
	ds_read2_b32 v[50:51], v114 offset0:49 offset1:57
	ds_read2_b32 v[52:53], v114 offset0:82 offset1:90
	ds_read2_b32 v[54:55], v114 offset0:115 offset1:123
	ds_read2_b32 v[56:57], v114 offset0:148 offset1:156
	ds_read2_b32 v[120:121], v114 offset0:181 offset1:189
	ds_read2_b32 v[122:123], v114 offset0:214 offset1:222
	ds_read2_b32 v[124:125], v114 offset0:247 offset1:255
	s_waitcnt lgkmcnt(7)
	v_bfe_u32 v5, v48, 16, 1
	v_add3_u32 v5, v48, v5, s51
	s_waitcnt lgkmcnt(6)
	v_bfe_u32 v44, v50, 16, 1
	v_lshrrev_b32_e32 v5, 16, v5
	v_add3_u32 v44, v50, v44, s51
	v_and_or_b32 v44, v44, s33, v5
	s_waitcnt lgkmcnt(5)
	v_bfe_u32 v5, v52, 16, 1
	v_add3_u32 v5, v52, v5, s51
	s_waitcnt lgkmcnt(4)
	v_bfe_u32 v45, v54, 16, 1
	v_lshrrev_b32_e32 v5, 16, v5
	v_add3_u32 v45, v54, v45, s51
	v_and_or_b32 v45, v45, s33, v5
	s_waitcnt lgkmcnt(3)
	v_bfe_u32 v5, v56, 16, 1
	v_add3_u32 v5, v56, v5, s51
	s_waitcnt lgkmcnt(2)
	v_bfe_u32 v46, v120, 16, 1
	v_lshrrev_b32_e32 v5, 16, v5
	v_add3_u32 v46, v120, v46, s51
	v_and_or_b32 v46, v46, s33, v5
	s_waitcnt lgkmcnt(1)
	v_bfe_u32 v5, v122, 16, 1
	v_add3_u32 v5, v122, v5, s51
	s_waitcnt lgkmcnt(0)
	v_bfe_u32 v47, v124, 16, 1
	v_lshrrev_b32_e32 v5, 16, v5
	v_add3_u32 v47, v124, v47, s51
	v_and_or_b32 v47, v47, s33, v5
	v_or_b32_e32 v5, v4, v116
	v_mul_u32_u24_e32 v5, 0xb00, v5
	v_lshlrev_b32_e32 v126, 1, v5
	v_mov_b32_e32 v127, v0
	v_lshl_add_u64 v[126:127], v[2:3], 0, v[126:127]
	v_bfe_u32 v5, v49, 16, 1
	global_store_dwordx4 v[126:127], v[44:47], off
	v_add3_u32 v5, v49, v5, s51
	v_lshrrev_b32_e32 v5, 16, v5
	v_bfe_u32 v44, v51, 16, 1
	v_add3_u32 v44, v51, v44, s51
	v_and_or_b32 v44, v44, s33, v5
	v_bfe_u32 v5, v53, 16, 1
	v_add3_u32 v5, v53, v5, s51
	v_bfe_u32 v45, v55, 16, 1
	v_lshrrev_b32_e32 v5, 16, v5
	v_add3_u32 v45, v55, v45, s51
	v_and_or_b32 v45, v45, s33, v5
	v_bfe_u32 v5, v57, 16, 1
	v_add3_u32 v5, v57, v5, s51
	v_bfe_u32 v46, v121, 16, 1
	v_lshrrev_b32_e32 v5, 16, v5
	v_add3_u32 v46, v121, v46, s51
	v_and_or_b32 v46, v46, s33, v5
	v_bfe_u32 v5, v123, 16, 1
	v_add3_u32 v5, v123, v5, s51
	v_bfe_u32 v47, v125, 16, 1
	v_or_b32_e32 v4, v4, v117
	v_lshrrev_b32_e32 v5, 16, v5
	v_add3_u32 v47, v125, v47, s51
	v_mul_u32_u24_e32 v4, 0xb00, v4
	v_and_or_b32 v47, v47, s33, v5
	v_lshlrev_b32_e32 v4, 1, v4
	v_mov_b32_e32 v5, v0
	v_lshl_add_u64 v[2:3], v[2:3], 0, v[4:5]
	global_store_dwordx4 v[2:3], v[44:47], off
	s_waitcnt lgkmcnt(0)

.LBB0_203:
	v_mul_lo_u16_e32 v3, 0xb0, v3
	v_sub_u16_e32 v44, v2, v3
	v_lshlrev_b16_e32 v5, 5, v44
	v_lshlrev_b32_e32 v2, 2, v5
	v_mov_b32_e32 v3, v0
	v_lshl_add_u64 v[2:3], v[38:39], 0, v[2:3]
	v_mad_u64_u32 v[48:49], s[8:9], v45, s48, v[2:3]
	global_load_dword v45, v[48:49], off
	v_add_u32_e32 v48, v7, v13
	s_and_b64 vcc, exec, s[0:1]
	v_or_b32_e32 v170, v58, v4
	v_mad_u64_u32 v[168:169], s[8:9], v170, s48, v[2:3]
	global_load_dword v168, v[168:169], off
	v_or_b32_e32 v208, v60, v4
	v_mad_u64_u32 v[208:209], s[8:9], v208, s48, v[2:3]
	global_load_dword v208, v[208:209], off
	s_waitcnt vmcnt(2)
	v_mul_f32_e32 v45, v47, v45
	ds_write_b32 v48, v45
	v_add_lshl_u32 v45, v8, v4, 2
	s_cbranch_vccnz .LBB0_205
	global_load_dword v176, v45, s[76:77] offset:16
	global_load_dword v177, v45, s[76:77] offset:24
	global_load_dword v178, v45, s[76:77] offset:32
	global_load_dword v179, v45, s[76:77] offset:40
	global_load_dword v180, v45, s[76:77] offset:48
	global_load_dword v181, v45, s[76:77] offset:56
	global_load_dword v182, v45, s[76:77] offset:64
	global_load_dword v183, v45, s[76:77] offset:72
	global_load_dword v184, v45, s[76:77] offset:80
	global_load_dword v185, v45, s[76:77] offset:88
	global_load_dword v186, v45, s[76:77] offset:96
	global_load_dword v187, v45, s[76:77] offset:104
	global_load_dword v188, v45, s[76:77] offset:112
	global_load_dword v189, v45, s[76:77] offset:120
	global_load_dword v190, v45, s[76:77] offset:128
	global_load_dword v191, v45, s[76:77] offset:136
	global_load_dword v192, v45, s[76:77] offset:144
	global_load_dword v193, v45, s[76:77] offset:152
	global_load_dword v194, v45, s[76:77] offset:160
	global_load_dword v195, v45, s[76:77] offset:168
	global_load_dword v196, v45, s[76:77] offset:176
	global_load_dword v197, v45, s[76:77] offset:184
	global_load_dword v198, v45, s[76:77] offset:192
	global_load_dword v199, v45, s[76:77] offset:200
	global_load_dword v200, v45, s[76:77] offset:208
	global_load_dword v201, v45, s[76:77] offset:216
	global_load_dword v202, v45, s[76:77] offset:224
	global_load_dword v203, v45, s[76:77] offset:232
	global_load_dword v204, v45, s[76:77] offset:240
	global_load_dword v205, v45, s[76:77] offset:248
	global_load_dword v46, v45, s[76:77] offset:8
.LBB0_205:
	v_add_u32_e32 v49, v7, v59
	v_mov_b32_e32 v47, 1.0
	s_and_b64 vcc, exec, s[0:1]
	v_or_b32_e32 v162, v62, v4
	v_mad_u64_u32 v[160:161], s[8:9], v162, s48, v[2:3]
	global_load_dword v160, v[160:161], off
	s_waitcnt vmcnt(1)
	v_mul_f32_e32 v46, v46, v168
	ds_write_b32 v49, v46
	v_mov_b32_e32 v46, 1.0
	s_cbranch_vccnz .LBB0_207
	v_mov_b32_e32 v46, v176
.LBB0_207:
	v_add_u32_e32 v49, v7, v61
	s_and_b64 vcc, exec, s[0:1]
	v_or_b32_e32 v168, v64, v4
	v_mad_u64_u32 v[168:169], s[8:9], v168, s48, v[2:3]
	global_load_dword v168, v[168:169], off
	s_waitcnt vmcnt(2)
	v_mul_f32_e32 v46, v46, v208
	ds_write_b32 v49, v46
	s_cbranch_vccnz .LBB0_209
	v_mov_b32_e32 v47, v177
.LBB0_209:
	v_add_u32_e32 v49, v7, v63
	v_mov_b32_e32 v46, 1.0
	s_and_b64 vcc, exec, s[0:1]
	v_or_b32_e32 v210, v66, v4
	v_mad_u64_u32 v[208:209], s[8:9], v210, s48, v[2:3]
	global_load_dword v208, v[208:209], off
	s_waitcnt vmcnt(2)
	v_mul_f32_e32 v47, v47, v160
	ds_write_b32 v49, v47
	v_mov_b32_e32 v47, 1.0
	s_cbranch_vccnz .LBB0_211
	v_mov_b32_e32 v47, v178
.LBB0_211:
	v_add_u32_e32 v49, v7, v65
	s_and_b64 vcc, exec, s[0:1]
	v_or_b32_e32 v160, v68, v4
	v_mad_u64_u32 v[160:161], s[8:9], v160, s48, v[2:3]
	global_load_dword v160, v[160:161], off
	s_waitcnt vmcnt(2)
	v_mul_f32_e32 v47, v47, v168
	ds_write_b32 v49, v47
	s_cbranch_vccnz .LBB0_213
	v_mov_b32_e32 v46, v179
.LBB0_213:
	v_add_u32_e32 v49, v7, v67
	v_mov_b32_e32 v47, 1.0
	s_and_b64 vcc, exec, s[0:1]
	v_or_b32_e32 v170, v70, v4
	v_mad_u64_u32 v[168:169], s[8:9], v170, s48, v[2:3]
	global_load_dword v168, v[168:169], off
	s_waitcnt vmcnt(2)
	v_mul_f32_e32 v46, v46, v208
	ds_write_b32 v49, v46
	v_mov_b32_e32 v46, 1.0
	s_cbranch_vccnz .LBB0_215
	v_mov_b32_e32 v46, v180
.LBB0_215:
	v_add_u32_e32 v49, v7, v69
	s_and_b64 vcc, exec, s[0:1]
	v_or_b32_e32 v208, v72, v4
	v_mad_u64_u32 v[208:209], s[8:9], v208, s48, v[2:3]
	global_load_dword v208, v[208:209], off
	s_waitcnt vmcnt(2)
	v_mul_f32_e32 v46, v46, v160
	ds_write_b32 v49, v46
	s_cbranch_vccnz .LBB0_217
	v_mov_b32_e32 v47, v181
.LBB0_217:
	v_add_u32_e32 v49, v7, v71
	v_mov_b32_e32 v46, 1.0
	s_and_b64 vcc, exec, s[0:1]
	v_or_b32_e32 v162, v74, v4
	v_mad_u64_u32 v[160:161], s[8:9], v162, s48, v[2:3]
	global_load_dword v160, v[160:161], off
	s_waitcnt vmcnt(2)
	v_mul_f32_e32 v47, v47, v168
	ds_write_b32 v49, v47
	v_mov_b32_e32 v47, 1.0
	s_cbranch_vccnz .LBB0_219
	v_mov_b32_e32 v47, v182
.LBB0_219:
	v_add_u32_e32 v49, v7, v73
	s_and_b64 vcc, exec, s[0:1]
	v_or_b32_e32 v168, v76, v4
	v_mad_u64_u32 v[168:169], s[8:9], v168, s48, v[2:3]
	global_load_dword v168, v[168:169], off
	s_waitcnt vmcnt(2)
	v_mul_f32_e32 v47, v47, v208
	ds_write_b32 v49, v47
	s_cbranch_vccnz .LBB0_221
	v_mov_b32_e32 v46, v183
.LBB0_221:
	v_add_u32_e32 v49, v7, v75
	v_mov_b32_e32 v47, 1.0
	s_and_b64 vcc, exec, s[0:1]
	v_or_b32_e32 v210, v78, v4
	v_mad_u64_u32 v[208:209], s[8:9], v210, s48, v[2:3]
	global_load_dword v208, v[208:209], off
	s_waitcnt vmcnt(2)
	v_mul_f32_e32 v46, v46, v160
	ds_write_b32 v49, v46
	v_mov_b32_e32 v46, 1.0
	s_cbranch_vccnz .LBB0_223
	v_mov_b32_e32 v46, v184
.LBB0_223:
	v_add_u32_e32 v49, v7, v77
	s_and_b64 vcc, exec, s[0:1]
	v_or_b32_e32 v160, v80, v4
	v_mad_u64_u32 v[160:161], s[8:9], v160, s48, v[2:3]
	global_load_dword v160, v[160:161], off
	s_waitcnt vmcnt(2)
	v_mul_f32_e32 v46, v46, v168
	ds_write_b32 v49, v46
	s_cbranch_vccnz .LBB0_225
	v_mov_b32_e32 v47, v185
.LBB0_225:
	v_add_u32_e32 v49, v7, v79
	v_mov_b32_e32 v46, 1.0
	s_and_b64 vcc, exec, s[0:1]
	v_or_b32_e32 v170, v82, v4
	v_mad_u64_u32 v[168:169], s[8:9], v170, s48, v[2:3]
	global_load_dword v168, v[168:169], off
	s_waitcnt vmcnt(2)
	v_mul_f32_e32 v47, v47, v208
	ds_write_b32 v49, v47
	v_mov_b32_e32 v47, 1.0
	s_cbranch_vccnz .LBB0_227
	v_mov_b32_e32 v47, v186
.LBB0_227:
	v_add_u32_e32 v49, v7, v81
	s_and_b64 vcc, exec, s[0:1]
	v_or_b32_e32 v208, v84, v4
	v_mad_u64_u32 v[208:209], s[8:9], v208, s48, v[2:3]
	global_load_dword v208, v[208:209], off
	s_waitcnt vmcnt(2)
	v_mul_f32_e32 v47, v47, v160
	ds_write_b32 v49, v47
	s_cbranch_vccnz .LBB0_229
	v_mov_b32_e32 v46, v187
.LBB0_229:
	v_add_u32_e32 v49, v7, v83
	v_mov_b32_e32 v47, 1.0
	s_and_b64 vcc, exec, s[0:1]
	v_or_b32_e32 v162, v86, v4
	v_mad_u64_u32 v[160:161], s[8:9], v162, s48, v[2:3]
	global_load_dword v160, v[160:161], off
	s_waitcnt vmcnt(2)
	v_mul_f32_e32 v46, v46, v168
	ds_write_b32 v49, v46
	v_mov_b32_e32 v46, 1.0
	s_cbranch_vccnz .LBB0_231
	v_mov_b32_e32 v46, v188
.LBB0_231:
	v_add_u32_e32 v49, v7, v85
	s_and_b64 vcc, exec, s[0:1]
	v_or_b32_e32 v168, v88, v4
	v_mad_u64_u32 v[168:169], s[8:9], v168, s48, v[2:3]
	global_load_dword v168, v[168:169], off
	s_waitcnt vmcnt(2)
	v_mul_f32_e32 v46, v46, v208
	ds_write_b32 v49, v46
	s_cbranch_vccnz .LBB0_233
	v_mov_b32_e32 v47, v189
.LBB0_233:
	v_add_u32_e32 v49, v7, v87
	v_mov_b32_e32 v46, 1.0
	s_and_b64 vcc, exec, s[0:1]
	v_or_b32_e32 v210, v90, v4
	v_mad_u64_u32 v[208:209], s[8:9], v210, s48, v[2:3]
	global_load_dword v208, v[208:209], off
	s_waitcnt vmcnt(2)
	v_mul_f32_e32 v47, v47, v160
	ds_write_b32 v49, v47
	v_mov_b32_e32 v47, 1.0
	s_cbranch_vccnz .LBB0_235
	v_mov_b32_e32 v47, v190
.LBB0_235:
	v_add_u32_e32 v49, v7, v89
	s_and_b64 vcc, exec, s[0:1]
	v_or_b32_e32 v160, v92, v4
	v_mad_u64_u32 v[160:161], s[8:9], v160, s48, v[2:3]
	global_load_dword v160, v[160:161], off
	s_waitcnt vmcnt(2)
	v_mul_f32_e32 v47, v47, v168
	ds_write_b32 v49, v47
	s_cbranch_vccnz .LBB0_237
	v_mov_b32_e32 v46, v191
.LBB0_237:
	v_add_u32_e32 v49, v7, v91
	v_mov_b32_e32 v47, 1.0
	s_and_b64 vcc, exec, s[0:1]
	v_or_b32_e32 v170, v94, v4
	v_mad_u64_u32 v[168:169], s[8:9], v170, s48, v[2:3]
	global_load_dword v168, v[168:169], off
	s_waitcnt vmcnt(2)
	v_mul_f32_e32 v46, v46, v208
	ds_write_b32 v49, v46
	v_mov_b32_e32 v46, 1.0
	s_cbranch_vccnz .LBB0_239
	v_mov_b32_e32 v46, v192
.LBB0_239:
	v_add_u32_e32 v49, v7, v93
	s_and_b64 vcc, exec, s[0:1]
	v_or_b32_e32 v208, v96, v4
	v_mad_u64_u32 v[208:209], s[8:9], v208, s48, v[2:3]
	global_load_dword v208, v[208:209], off
	s_waitcnt vmcnt(2)
	v_mul_f32_e32 v46, v46, v160
	ds_write_b32 v49, v46
	s_cbranch_vccnz .LBB0_241
	v_mov_b32_e32 v47, v193
.LBB0_241:
	v_add_u32_e32 v49, v7, v95
	v_mov_b32_e32 v46, 1.0
	s_and_b64 vcc, exec, s[0:1]
	v_or_b32_e32 v162, v98, v4
	v_mad_u64_u32 v[160:161], s[8:9], v162, s48, v[2:3]
	global_load_dword v160, v[160:161], off
	s_waitcnt vmcnt(2)
	v_mul_f32_e32 v47, v47, v168
	ds_write_b32 v49, v47
	v_mov_b32_e32 v47, 1.0
	s_cbranch_vccnz .LBB0_243
	v_mov_b32_e32 v47, v194
.LBB0_243:
	v_add_u32_e32 v49, v7, v97
	s_and_b64 vcc, exec, s[0:1]
	v_or_b32_e32 v168, v100, v4
	v_mad_u64_u32 v[168:169], s[8:9], v168, s48, v[2:3]
	global_load_dword v168, v[168:169], off
	s_waitcnt vmcnt(2)
	v_mul_f32_e32 v47, v47, v208
	ds_write_b32 v49, v47
	s_cbranch_vccnz .LBB0_245
	v_mov_b32_e32 v46, v195
.LBB0_245:
	v_add_u32_e32 v49, v7, v99
	v_mov_b32_e32 v47, 1.0
	s_and_b64 vcc, exec, s[0:1]
	v_or_b32_e32 v210, v102, v4
	v_mad_u64_u32 v[208:209], s[8:9], v210, s48, v[2:3]
	global_load_dword v210, v[208:209], off
	s_waitcnt vmcnt(2)
	v_mul_f32_e32 v46, v46, v160
	ds_write_b32 v49, v46
	v_mov_b32_e32 v46, 1.0
	s_cbranch_vccnz .LBB0_247
	v_mov_b32_e32 v46, v196
.LBB0_247:
	v_add_u32_e32 v49, v7, v101
	s_and_b64 vcc, exec, s[0:1]
	v_or_b32_e32 v162, v104, v4
	v_mad_u64_u32 v[160:161], s[8:9], v162, s48, v[2:3]
	global_load_dword v163, v[160:161], off
	s_waitcnt vmcnt(2)
	v_mul_f32_e32 v46, v46, v168
	ds_write_b32 v49, v46
	s_cbranch_vccnz .LBB0_249
	v_mov_b32_e32 v47, v197
.LBB0_249:
	v_add_u32_e32 v49, v7, v103
	v_mov_b32_e32 v48, 1.0
	s_and_b64 vcc, exec, s[0:1]
	v_or_b32_e32 v170, v106, v4
	v_mad_u64_u32 v[168:169], s[8:9], v170, s48, v[2:3]
	global_load_dword v171, v[168:169], off
	s_waitcnt vmcnt(2)
	v_mul_f32_e32 v46, v47, v210
	v_mov_b32_e32 v47, 1.0
	ds_write_b32 v49, v46
	s_cbranch_vccnz .LBB0_251
	v_mov_b32_e32 v47, v198
.LBB0_251:
	v_add_u32_e32 v46, v7, v105
	s_and_b64 vcc, exec, s[0:1]
	v_or_b32_e32 v210, v107, v4
	v_mad_u64_u32 v[208:209], s[8:9], v210, s48, v[2:3]
	global_load_dword v210, v[208:209], off
	s_waitcnt vmcnt(2)
	v_mul_f32_e32 v47, v47, v163
	ds_write_b32 v46, v47
	s_cbranch_vccnz .LBB0_253
	v_mov_b32_e32 v48, v199
.LBB0_253:
	v_mov_b32_e32 v47, 1.0
	s_and_b64 vcc, exec, s[0:1]
	v_or_b32_e32 v160, v108, v4
	v_mad_u64_u32 v[160:161], s[8:9], v160, s48, v[2:3]
	global_load_dword v161, v[160:161], off
	s_waitcnt vmcnt(2)
	v_mul_f32_e32 v48, v48, v171
	ds_write_b32 v46, v48 offset:264
	v_mov_b32_e32 v48, 1.0
	s_cbranch_vccnz .LBB0_255
	v_mov_b32_e32 v48, v200
.LBB0_255:
	s_and_b64 vcc, exec, s[0:1]
	v_or_b32_e32 v170, v109, v4
	v_mad_u64_u32 v[168:169], s[8:9], v170, s48, v[2:3]
	global_load_dword v170, v[168:169], off
	s_waitcnt vmcnt(2)
	v_mul_f32_e32 v48, v48, v210
	ds_write_b32 v46, v48 offset:528
	s_cbranch_vccnz .LBB0_257
	v_mov_b32_e32 v47, v201
.LBB0_257:
	v_mov_b32_e32 v48, 1.0
	s_and_b64 vcc, exec, s[0:1]
	v_or_b32_e32 v210, v110, v4
	v_mad_u64_u32 v[208:209], s[8:9], v210, s48, v[2:3]
	global_load_dword v211, v[208:209], off
	s_waitcnt vmcnt(2)
	v_mul_f32_e32 v47, v47, v161
	ds_write_b32 v46, v47 offset:792
	v_mov_b32_e32 v47, 1.0
	s_cbranch_vccnz .LBB0_259
	v_mov_b32_e32 v47, v202
.LBB0_259:
	s_and_b64 vcc, exec, s[0:1]
	v_or_b32_e32 v162, v111, v4
	v_mad_u64_u32 v[160:161], s[8:9], v162, s48, v[2:3]
	global_load_dword v162, v[160:161], off
	s_waitcnt vmcnt(2)
	v_mul_f32_e32 v47, v47, v170
	ds_write_b32 v46, v47 offset:1056
	s_cbranch_vccnz .LBB0_261
	v_mov_b32_e32 v48, v203
.LBB0_261:
	v_mov_b32_e32 v47, 1.0
	s_and_b64 vcc, exec, s[0:1]
	s_waitcnt vmcnt(1)
	v_mul_f32_e32 v48, v48, v211
	ds_write_b32 v46, v48 offset:1320
	v_mov_b32_e32 v48, 1.0
	s_cbranch_vccnz .LBB0_263
	v_mov_b32_e32 v48, v204
.LBB0_263:
	s_and_b64 vcc, exec, s[0:1]
	s_waitcnt vmcnt(0)
	v_mul_f32_e32 v48, v48, v162
	ds_write_b32 v46, v48 offset:1584
	s_cbranch_vccnz .LBB0_265
	v_mov_b32_e32 v47, v205

.LBB0_270:
	s_movk_i32 s8, 0xea00
	v_mad_u64_u32 v[44:45], s[8:9], v48, s8, v[42:43]
	v_ashrrev_i32_e32 v45, 31, v44
	v_lshl_add_u64 v[4:5], v[44:45], 2, v[40:41]
	v_mad_i64_i32 v[46:47], s[8:9], v46, s48, v[4:5]
	global_load_dword v45, v[46:47], off
	v_add_u32_e32 v46, v7, v13
	s_and_b64 vcc, exec, s[0:1]
	v_or_b32_e32 v162, v2, v58
	v_mad_i64_i32 v[160:161], s[8:9], v162, s48, v[4:5]
	global_load_dword v160, v[160:161], off
	v_or_b32_e32 v170, v2, v60
	v_mad_i64_i32 v[168:169], s[8:9], v170, s48, v[4:5]
	global_load_dword v170, v[168:169], off
	s_waitcnt vmcnt(2)
	v_mul_f32_e32 v3, v3, v45
	ds_write_b32 v46, v3
	v_ashrrev_i32_e32 v3, 31, v2
	s_cbranch_vccnz .LBB0_272
	v_readlane_b32 s52, v252, 14
	v_lshl_add_u64 v[46:47], v[2:3], 0, v[8:9]
	v_readlane_b32 s56, v252, 18
	v_readlane_b32 s57, v252, 19
	v_readlane_b32 s53, v252, 15
	v_readlane_b32 s54, v252, 16
	v_lshl_add_u64 v[46:47], v[46:47], 2, s[56:57]
	global_load_dword v176, v[46:47], off offset:16
	global_load_dword v177, v[46:47], off offset:24
	global_load_dword v178, v[46:47], off offset:32
	global_load_dword v179, v[46:47], off offset:40
	global_load_dword v180, v[46:47], off offset:48
	global_load_dword v181, v[46:47], off offset:56
	global_load_dword v182, v[46:47], off offset:64
	global_load_dword v183, v[46:47], off offset:72
	global_load_dword v184, v[46:47], off offset:80
	global_load_dword v185, v[46:47], off offset:88
	global_load_dword v186, v[46:47], off offset:96
	global_load_dword v187, v[46:47], off offset:104
	global_load_dword v188, v[46:47], off offset:112
	global_load_dword v189, v[46:47], off offset:120
	global_load_dword v190, v[46:47], off offset:128
	global_load_dword v191, v[46:47], off offset:136
	global_load_dword v192, v[46:47], off offset:144
	global_load_dword v193, v[46:47], off offset:152
	global_load_dword v194, v[46:47], off offset:160
	global_load_dword v195, v[46:47], off offset:168
	global_load_dword v196, v[46:47], off offset:176
	global_load_dword v197, v[46:47], off offset:184
	global_load_dword v198, v[46:47], off offset:192
	global_load_dword v199, v[46:47], off offset:200
	global_load_dword v200, v[46:47], off offset:208
	global_load_dword v201, v[46:47], off offset:216
	global_load_dword v202, v[46:47], off offset:224
	global_load_dword v203, v[46:47], off offset:232
	global_load_dword v49, v[46:47], off offset:8
	v_readlane_b32 s55, v252, 17
	v_readlane_b32 s58, v252, 20
	v_readlane_b32 s59, v252, 21
	v_readlane_b32 s60, v252, 22
	v_readlane_b32 s61, v252, 23
	v_readlane_b32 s62, v252, 24
	v_readlane_b32 s63, v252, 25
	v_readlane_b32 s64, v252, 26
	v_readlane_b32 s65, v252, 27
	v_readlane_b32 s66, v252, 28
	v_readlane_b32 s67, v252, 29
.LBB0_272:
	v_add_u32_e32 v47, v7, v59
	v_mov_b32_e32 v45, 1.0
	s_and_b64 vcc, exec, s[0:1]
	v_or_b32_e32 v208, v2, v62
	v_mad_i64_i32 v[208:209], s[8:9], v208, s48, v[4:5]
	global_load_dword v209, v[208:209], off
	s_waitcnt vmcnt(1)
	v_mul_f32_e32 v46, v49, v160
	ds_write_b32 v47, v46
	v_mov_b32_e32 v46, 1.0
	s_cbranch_vccnz .LBB0_274
	v_readlane_b32 s52, v252, 14
	v_lshl_add_u64 v[46:47], v[2:3], 0, v[8:9]
	v_readlane_b32 s56, v252, 18
	v_readlane_b32 s57, v252, 19
	v_readlane_b32 s53, v252, 15
	v_readlane_b32 s54, v252, 16
	v_lshl_add_u64 v[46:47], v[46:47], 2, s[56:57]
	v_mov_b32_e32 v46, v176
	v_readlane_b32 s55, v252, 17
	v_readlane_b32 s58, v252, 20
	v_readlane_b32 s59, v252, 21
	v_readlane_b32 s60, v252, 22
	v_readlane_b32 s61, v252, 23
	v_readlane_b32 s62, v252, 24
	v_readlane_b32 s63, v252, 25
	v_readlane_b32 s64, v252, 26
	v_readlane_b32 s65, v252, 27
	v_readlane_b32 s66, v252, 28
	v_readlane_b32 s67, v252, 29
.LBB0_274:
	v_add_u32_e32 v49, v7, v61
	s_and_b64 vcc, exec, s[0:1]
	v_or_b32_e32 v162, v2, v64
	v_mad_i64_i32 v[160:161], s[8:9], v162, s48, v[4:5]
	global_load_dword v162, v[160:161], off
	s_waitcnt vmcnt(2)
	v_mul_f32_e32 v46, v46, v170
	ds_write_b32 v49, v46
	s_cbranch_vccnz .LBB0_276
	v_readlane_b32 s52, v252, 14
	v_lshl_add_u64 v[46:47], v[2:3], 0, v[8:9]
	v_readlane_b32 s56, v252, 18
	v_readlane_b32 s57, v252, 19
	v_readlane_b32 s53, v252, 15
	v_readlane_b32 s54, v252, 16
	v_lshl_add_u64 v[46:47], v[46:47], 2, s[56:57]
	v_mov_b32_e32 v45, v177
	v_readlane_b32 s55, v252, 17
	v_readlane_b32 s58, v252, 20
	v_readlane_b32 s59, v252, 21
	v_readlane_b32 s60, v252, 22
	v_readlane_b32 s61, v252, 23
	v_readlane_b32 s62, v252, 24
	v_readlane_b32 s63, v252, 25
	v_readlane_b32 s64, v252, 26
	v_readlane_b32 s65, v252, 27
	v_readlane_b32 s66, v252, 28
	v_readlane_b32 s67, v252, 29
.LBB0_276:
	v_add_u32_e32 v49, v7, v63
	v_mov_b32_e32 v46, 1.0
	s_and_b64 vcc, exec, s[0:1]
	v_or_b32_e32 v170, v2, v66
	v_mad_i64_i32 v[168:169], s[8:9], v170, s48, v[4:5]
	global_load_dword v171, v[168:169], off
	s_waitcnt vmcnt(2)
	v_mul_f32_e32 v45, v45, v209
	ds_write_b32 v49, v45
	v_mov_b32_e32 v45, 1.0
	s_cbranch_vccnz .LBB0_278
	v_readlane_b32 s52, v252, 14
	v_lshl_add_u64 v[50:51], v[2:3], 0, v[8:9]
	v_readlane_b32 s56, v252, 18
	v_readlane_b32 s57, v252, 19
	v_readlane_b32 s53, v252, 15
	v_readlane_b32 s54, v252, 16
	v_lshl_add_u64 v[50:51], v[50:51], 2, s[56:57]
	v_mov_b32_e32 v45, v178
	v_readlane_b32 s55, v252, 17
	v_readlane_b32 s58, v252, 20
	v_readlane_b32 s59, v252, 21
	v_readlane_b32 s60, v252, 22
	v_readlane_b32 s61, v252, 23
	v_readlane_b32 s62, v252, 24
	v_readlane_b32 s63, v252, 25
	v_readlane_b32 s64, v252, 26
	v_readlane_b32 s65, v252, 27
	v_readlane_b32 s66, v252, 28
	v_readlane_b32 s67, v252, 29
.LBB0_278:
	v_add_u32_e32 v49, v7, v65
	s_and_b64 vcc, exec, s[0:1]
	v_or_b32_e32 v210, v2, v68
	v_mad_i64_i32 v[208:209], s[8:9], v210, s48, v[4:5]
	global_load_dword v210, v[208:209], off
	s_waitcnt vmcnt(2)
	v_mul_f32_e32 v45, v45, v162
	ds_write_b32 v49, v45
	s_cbranch_vccnz .LBB0_280
	v_readlane_b32 s52, v252, 14
	v_lshl_add_u64 v[46:47], v[2:3], 0, v[8:9]
	v_readlane_b32 s56, v252, 18
	v_readlane_b32 s57, v252, 19
	v_readlane_b32 s53, v252, 15
	v_readlane_b32 s54, v252, 16
	v_lshl_add_u64 v[46:47], v[46:47], 2, s[56:57]
	v_mov_b32_e32 v46, v179
	v_readlane_b32 s55, v252, 17
	v_readlane_b32 s58, v252, 20
	v_readlane_b32 s59, v252, 21
	v_readlane_b32 s60, v252, 22
	v_readlane_b32 s61, v252, 23
	v_readlane_b32 s62, v252, 24
	v_readlane_b32 s63, v252, 25
	v_readlane_b32 s64, v252, 26
	v_readlane_b32 s65, v252, 27
	v_readlane_b32 s66, v252, 28
	v_readlane_b32 s67, v252, 29
.LBB0_280:
	v_add_u32_e32 v49, v7, v67
	v_mov_b32_e32 v45, 1.0
	s_and_b64 vcc, exec, s[0:1]
	v_or_b32_e32 v160, v2, v70
	v_mad_i64_i32 v[160:161], s[8:9], v160, s48, v[4:5]
	global_load_dword v161, v[160:161], off
	s_waitcnt vmcnt(2)
	v_mul_f32_e32 v46, v46, v171
	ds_write_b32 v49, v46
	v_mov_b32_e32 v46, 1.0
	s_cbranch_vccnz .LBB0_282
	v_readlane_b32 s52, v252, 14
	v_lshl_add_u64 v[46:47], v[2:3], 0, v[8:9]
	v_readlane_b32 s56, v252, 18
	v_readlane_b32 s57, v252, 19
	v_readlane_b32 s53, v252, 15
	v_readlane_b32 s54, v252, 16
	v_lshl_add_u64 v[46:47], v[46:47], 2, s[56:57]
	v_mov_b32_e32 v46, v180
	v_readlane_b32 s55, v252, 17
	v_readlane_b32 s58, v252, 20
	v_readlane_b32 s59, v252, 21
	v_readlane_b32 s60, v252, 22
	v_readlane_b32 s61, v252, 23
	v_readlane_b32 s62, v252, 24
	v_readlane_b32 s63, v252, 25
	v_readlane_b32 s64, v252, 26
	v_readlane_b32 s65, v252, 27
	v_readlane_b32 s66, v252, 28
	v_readlane_b32 s67, v252, 29
.LBB0_282:
	v_add_u32_e32 v49, v7, v69
	s_and_b64 vcc, exec, s[0:1]
	v_or_b32_e32 v170, v2, v72
	v_mad_i64_i32 v[168:169], s[8:9], v170, s48, v[4:5]
	global_load_dword v170, v[168:169], off
	s_waitcnt vmcnt(2)
	v_mul_f32_e32 v46, v46, v210
	ds_write_b32 v49, v46
	s_cbranch_vccnz .LBB0_284
	v_readlane_b32 s52, v252, 14
	v_lshl_add_u64 v[46:47], v[2:3], 0, v[8:9]
	v_readlane_b32 s56, v252, 18
	v_readlane_b32 s57, v252, 19
	v_readlane_b32 s53, v252, 15
	v_readlane_b32 s54, v252, 16
	v_lshl_add_u64 v[46:47], v[46:47], 2, s[56:57]
	v_mov_b32_e32 v45, v181
	v_readlane_b32 s55, v252, 17
	v_readlane_b32 s58, v252, 20
	v_readlane_b32 s59, v252, 21
	v_readlane_b32 s60, v252, 22
	v_readlane_b32 s61, v252, 23
	v_readlane_b32 s62, v252, 24
	v_readlane_b32 s63, v252, 25
	v_readlane_b32 s64, v252, 26
	v_readlane_b32 s65, v252, 27
	v_readlane_b32 s66, v252, 28
	v_readlane_b32 s67, v252, 29
.LBB0_284:
	v_add_u32_e32 v49, v7, v71
	v_mov_b32_e32 v46, 1.0
	s_and_b64 vcc, exec, s[0:1]
	v_or_b32_e32 v210, v2, v74
	v_mad_i64_i32 v[208:209], s[8:9], v210, s48, v[4:5]
	global_load_dword v211, v[208:209], off
	s_waitcnt vmcnt(2)
	v_mul_f32_e32 v45, v45, v161
	ds_write_b32 v49, v45
	v_mov_b32_e32 v45, 1.0
	s_cbranch_vccnz .LBB0_286
	v_readlane_b32 s52, v252, 14
	v_lshl_add_u64 v[50:51], v[2:3], 0, v[8:9]
	v_readlane_b32 s56, v252, 18
	v_readlane_b32 s57, v252, 19
	v_readlane_b32 s53, v252, 15
	v_readlane_b32 s54, v252, 16
	v_lshl_add_u64 v[50:51], v[50:51], 2, s[56:57]
	v_mov_b32_e32 v45, v182
	v_readlane_b32 s55, v252, 17
	v_readlane_b32 s58, v252, 20
	v_readlane_b32 s59, v252, 21
	v_readlane_b32 s60, v252, 22
	v_readlane_b32 s61, v252, 23
	v_readlane_b32 s62, v252, 24
	v_readlane_b32 s63, v252, 25
	v_readlane_b32 s64, v252, 26
	v_readlane_b32 s65, v252, 27
	v_readlane_b32 s66, v252, 28
	v_readlane_b32 s67, v252, 29
.LBB0_286:
	v_add_u32_e32 v49, v7, v73
	s_and_b64 vcc, exec, s[0:1]
	v_or_b32_e32 v162, v2, v76
	v_mad_i64_i32 v[160:161], s[8:9], v162, s48, v[4:5]
	global_load_dword v162, v[160:161], off
	s_waitcnt vmcnt(2)
	v_mul_f32_e32 v45, v45, v170
	ds_write_b32 v49, v45
	s_cbranch_vccnz .LBB0_288
	v_readlane_b32 s52, v252, 14
	v_lshl_add_u64 v[46:47], v[2:3], 0, v[8:9]
	v_readlane_b32 s56, v252, 18
	v_readlane_b32 s57, v252, 19
	v_readlane_b32 s53, v252, 15
	v_readlane_b32 s54, v252, 16
	v_lshl_add_u64 v[46:47], v[46:47], 2, s[56:57]
	v_mov_b32_e32 v46, v183
	v_readlane_b32 s55, v252, 17
	v_readlane_b32 s58, v252, 20
	v_readlane_b32 s59, v252, 21
	v_readlane_b32 s60, v252, 22
	v_readlane_b32 s61, v252, 23
	v_readlane_b32 s62, v252, 24
	v_readlane_b32 s63, v252, 25
	v_readlane_b32 s64, v252, 26
	v_readlane_b32 s65, v252, 27
	v_readlane_b32 s66, v252, 28
	v_readlane_b32 s67, v252, 29
.LBB0_288:
	v_add_u32_e32 v49, v7, v75
	v_mov_b32_e32 v45, 1.0
	s_and_b64 vcc, exec, s[0:1]
	v_or_b32_e32 v168, v2, v78
	v_mad_i64_i32 v[168:169], s[8:9], v168, s48, v[4:5]
	global_load_dword v169, v[168:169], off
	s_waitcnt vmcnt(2)
	v_mul_f32_e32 v46, v46, v211
	ds_write_b32 v49, v46
	v_mov_b32_e32 v46, 1.0
	s_cbranch_vccnz .LBB0_290
	v_readlane_b32 s52, v252, 14
	v_lshl_add_u64 v[46:47], v[2:3], 0, v[8:9]
	v_readlane_b32 s56, v252, 18
	v_readlane_b32 s57, v252, 19
	v_readlane_b32 s53, v252, 15
	v_readlane_b32 s54, v252, 16
	v_lshl_add_u64 v[46:47], v[46:47], 2, s[56:57]
	v_mov_b32_e32 v46, v184
	v_readlane_b32 s55, v252, 17
	v_readlane_b32 s58, v252, 20
	v_readlane_b32 s59, v252, 21
	v_readlane_b32 s60, v252, 22
	v_readlane_b32 s61, v252, 23
	v_readlane_b32 s62, v252, 24
	v_readlane_b32 s63, v252, 25
	v_readlane_b32 s64, v252, 26
	v_readlane_b32 s65, v252, 27
	v_readlane_b32 s66, v252, 28
	v_readlane_b32 s67, v252, 29
.LBB0_290:
	v_add_u32_e32 v49, v7, v77
	s_and_b64 vcc, exec, s[0:1]
	v_or_b32_e32 v210, v2, v80
	v_mad_i64_i32 v[208:209], s[8:9], v210, s48, v[4:5]
	global_load_dword v210, v[208:209], off
	s_waitcnt vmcnt(2)
	v_mul_f32_e32 v46, v46, v162
	ds_write_b32 v49, v46
	s_cbranch_vccnz .LBB0_292
	v_readlane_b32 s52, v252, 14
	v_lshl_add_u64 v[46:47], v[2:3], 0, v[8:9]
	v_readlane_b32 s56, v252, 18
	v_readlane_b32 s57, v252, 19
	v_readlane_b32 s53, v252, 15
	v_readlane_b32 s54, v252, 16
	v_lshl_add_u64 v[46:47], v[46:47], 2, s[56:57]
	v_mov_b32_e32 v45, v185
	v_readlane_b32 s55, v252, 17
	v_readlane_b32 s58, v252, 20
	v_readlane_b32 s59, v252, 21
	v_readlane_b32 s60, v252, 22
	v_readlane_b32 s61, v252, 23
	v_readlane_b32 s62, v252, 24
	v_readlane_b32 s63, v252, 25
	v_readlane_b32 s64, v252, 26
	v_readlane_b32 s65, v252, 27
	v_readlane_b32 s66, v252, 28
	v_readlane_b32 s67, v252, 29
.LBB0_292:
	v_add_u32_e32 v49, v7, v79
	v_mov_b32_e32 v46, 1.0
	s_and_b64 vcc, exec, s[0:1]
	v_or_b32_e32 v162, v2, v82
	v_mad_i64_i32 v[160:161], s[8:9], v162, s48, v[4:5]
	global_load_dword v163, v[160:161], off
	s_waitcnt vmcnt(2)
	v_mul_f32_e32 v45, v45, v169
	ds_write_b32 v49, v45
	v_mov_b32_e32 v45, 1.0
	s_cbranch_vccnz .LBB0_294
	v_readlane_b32 s52, v252, 14
	v_lshl_add_u64 v[50:51], v[2:3], 0, v[8:9]
	v_readlane_b32 s56, v252, 18
	v_readlane_b32 s57, v252, 19
	v_readlane_b32 s53, v252, 15
	v_readlane_b32 s54, v252, 16
	v_lshl_add_u64 v[50:51], v[50:51], 2, s[56:57]
	v_mov_b32_e32 v45, v186
	v_readlane_b32 s55, v252, 17
	v_readlane_b32 s58, v252, 20
	v_readlane_b32 s59, v252, 21
	v_readlane_b32 s60, v252, 22
	v_readlane_b32 s61, v252, 23
	v_readlane_b32 s62, v252, 24
	v_readlane_b32 s63, v252, 25
	v_readlane_b32 s64, v252, 26
	v_readlane_b32 s65, v252, 27
	v_readlane_b32 s66, v252, 28
	v_readlane_b32 s67, v252, 29
.LBB0_294:
	v_add_u32_e32 v49, v7, v81
	s_and_b64 vcc, exec, s[0:1]
	v_or_b32_e32 v170, v2, v84
	v_mad_i64_i32 v[168:169], s[8:9], v170, s48, v[4:5]
	global_load_dword v170, v[168:169], off
	s_waitcnt vmcnt(2)
	v_mul_f32_e32 v45, v45, v210
	ds_write_b32 v49, v45
	s_cbranch_vccnz .LBB0_296
	v_readlane_b32 s52, v252, 14
	v_lshl_add_u64 v[46:47], v[2:3], 0, v[8:9]
	v_readlane_b32 s56, v252, 18
	v_readlane_b32 s57, v252, 19
	v_readlane_b32 s53, v252, 15
	v_readlane_b32 s54, v252, 16
	v_lshl_add_u64 v[46:47], v[46:47], 2, s[56:57]
	v_mov_b32_e32 v46, v187
	v_readlane_b32 s55, v252, 17
	v_readlane_b32 s58, v252, 20
	v_readlane_b32 s59, v252, 21
	v_readlane_b32 s60, v252, 22
	v_readlane_b32 s61, v252, 23
	v_readlane_b32 s62, v252, 24
	v_readlane_b32 s63, v252, 25
	v_readlane_b32 s64, v252, 26
	v_readlane_b32 s65, v252, 27
	v_readlane_b32 s66, v252, 28
	v_readlane_b32 s67, v252, 29
.LBB0_296:
	v_add_u32_e32 v49, v7, v83
	v_mov_b32_e32 v45, 1.0
	s_and_b64 vcc, exec, s[0:1]
	v_or_b32_e32 v208, v2, v86
	v_mad_i64_i32 v[208:209], s[8:9], v208, s48, v[4:5]
	global_load_dword v209, v[208:209], off
	s_waitcnt vmcnt(2)
	v_mul_f32_e32 v46, v46, v163
	ds_write_b32 v49, v46
	v_mov_b32_e32 v46, 1.0
	s_cbranch_vccnz .LBB0_298
	v_readlane_b32 s52, v252, 14
	v_lshl_add_u64 v[46:47], v[2:3], 0, v[8:9]
	v_readlane_b32 s56, v252, 18
	v_readlane_b32 s57, v252, 19
	v_readlane_b32 s53, v252, 15
	v_readlane_b32 s54, v252, 16
	v_lshl_add_u64 v[46:47], v[46:47], 2, s[56:57]
	v_mov_b32_e32 v46, v188
	v_readlane_b32 s55, v252, 17
	v_readlane_b32 s58, v252, 20
	v_readlane_b32 s59, v252, 21
	v_readlane_b32 s60, v252, 22
	v_readlane_b32 s61, v252, 23
	v_readlane_b32 s62, v252, 24
	v_readlane_b32 s63, v252, 25
	v_readlane_b32 s64, v252, 26
	v_readlane_b32 s65, v252, 27
	v_readlane_b32 s66, v252, 28
	v_readlane_b32 s67, v252, 29
.LBB0_298:
	v_add_u32_e32 v49, v7, v85
	s_and_b64 vcc, exec, s[0:1]
	v_or_b32_e32 v162, v2, v88
	v_mad_i64_i32 v[160:161], s[8:9], v162, s48, v[4:5]
	global_load_dword v162, v[160:161], off
	s_waitcnt vmcnt(2)
	v_mul_f32_e32 v46, v46, v170
	ds_write_b32 v49, v46
	s_cbranch_vccnz .LBB0_300
	v_readlane_b32 s52, v252, 14
	v_lshl_add_u64 v[46:47], v[2:3], 0, v[8:9]
	v_readlane_b32 s56, v252, 18
	v_readlane_b32 s57, v252, 19
	v_readlane_b32 s53, v252, 15
	v_readlane_b32 s54, v252, 16
	v_lshl_add_u64 v[46:47], v[46:47], 2, s[56:57]
	v_mov_b32_e32 v45, v189
	v_readlane_b32 s55, v252, 17
	v_readlane_b32 s58, v252, 20
	v_readlane_b32 s59, v252, 21
	v_readlane_b32 s60, v252, 22
	v_readlane_b32 s61, v252, 23
	v_readlane_b32 s62, v252, 24
	v_readlane_b32 s63, v252, 25
	v_readlane_b32 s64, v252, 26
	v_readlane_b32 s65, v252, 27
	v_readlane_b32 s66, v252, 28
	v_readlane_b32 s67, v252, 29
.LBB0_300:
	v_add_u32_e32 v49, v7, v87
	v_mov_b32_e32 v46, 1.0
	s_and_b64 vcc, exec, s[0:1]
	v_or_b32_e32 v170, v2, v90
	v_mad_i64_i32 v[168:169], s[8:9], v170, s48, v[4:5]
	global_load_dword v171, v[168:169], off
	s_waitcnt vmcnt(2)
	v_mul_f32_e32 v45, v45, v209
	ds_write_b32 v49, v45
	v_mov_b32_e32 v45, 1.0
	s_cbranch_vccnz .LBB0_302
	v_readlane_b32 s52, v252, 14
	v_lshl_add_u64 v[50:51], v[2:3], 0, v[8:9]
	v_readlane_b32 s56, v252, 18
	v_readlane_b32 s57, v252, 19
	v_readlane_b32 s53, v252, 15
	v_readlane_b32 s54, v252, 16
	v_lshl_add_u64 v[50:51], v[50:51], 2, s[56:57]
	v_mov_b32_e32 v45, v190
	v_readlane_b32 s55, v252, 17
	v_readlane_b32 s58, v252, 20
	v_readlane_b32 s59, v252, 21
	v_readlane_b32 s60, v252, 22
	v_readlane_b32 s61, v252, 23
	v_readlane_b32 s62, v252, 24
	v_readlane_b32 s63, v252, 25
	v_readlane_b32 s64, v252, 26
	v_readlane_b32 s65, v252, 27
	v_readlane_b32 s66, v252, 28
	v_readlane_b32 s67, v252, 29
.LBB0_302:
	v_add_u32_e32 v49, v7, v89
	s_and_b64 vcc, exec, s[0:1]
	v_or_b32_e32 v210, v2, v92
	v_mad_i64_i32 v[208:209], s[8:9], v210, s48, v[4:5]
	global_load_dword v210, v[208:209], off
	s_waitcnt vmcnt(2)
	v_mul_f32_e32 v45, v45, v162
	ds_write_b32 v49, v45
	s_cbranch_vccnz .LBB0_304
	v_readlane_b32 s52, v252, 14
	v_lshl_add_u64 v[46:47], v[2:3], 0, v[8:9]
	v_readlane_b32 s56, v252, 18
	v_readlane_b32 s57, v252, 19
	v_readlane_b32 s53, v252, 15
	v_readlane_b32 s54, v252, 16
	v_lshl_add_u64 v[46:47], v[46:47], 2, s[56:57]
	v_mov_b32_e32 v46, v191
	v_readlane_b32 s55, v252, 17
	v_readlane_b32 s58, v252, 20
	v_readlane_b32 s59, v252, 21
	v_readlane_b32 s60, v252, 22
	v_readlane_b32 s61, v252, 23
	v_readlane_b32 s62, v252, 24
	v_readlane_b32 s63, v252, 25
	v_readlane_b32 s64, v252, 26
	v_readlane_b32 s65, v252, 27
	v_readlane_b32 s66, v252, 28
	v_readlane_b32 s67, v252, 29
.LBB0_304:
	v_add_u32_e32 v49, v7, v91
	v_mov_b32_e32 v45, 1.0
	s_and_b64 vcc, exec, s[0:1]
	v_or_b32_e32 v160, v2, v94
	v_mad_i64_i32 v[160:161], s[8:9], v160, s48, v[4:5]
	global_load_dword v161, v[160:161], off
	s_waitcnt vmcnt(2)
	v_mul_f32_e32 v46, v46, v171
	ds_write_b32 v49, v46
	v_mov_b32_e32 v46, 1.0
	s_cbranch_vccnz .LBB0_306
	v_readlane_b32 s52, v252, 14
	v_lshl_add_u64 v[46:47], v[2:3], 0, v[8:9]
	v_readlane_b32 s56, v252, 18
	v_readlane_b32 s57, v252, 19
	v_readlane_b32 s53, v252, 15
	v_readlane_b32 s54, v252, 16
	v_lshl_add_u64 v[46:47], v[46:47], 2, s[56:57]
	v_mov_b32_e32 v46, v192
	v_readlane_b32 s55, v252, 17
	v_readlane_b32 s58, v252, 20
	v_readlane_b32 s59, v252, 21
	v_readlane_b32 s60, v252, 22
	v_readlane_b32 s61, v252, 23
	v_readlane_b32 s62, v252, 24
	v_readlane_b32 s63, v252, 25
	v_readlane_b32 s64, v252, 26
	v_readlane_b32 s65, v252, 27
	v_readlane_b32 s66, v252, 28
	v_readlane_b32 s67, v252, 29
.LBB0_306:
	v_add_u32_e32 v49, v7, v93
	s_and_b64 vcc, exec, s[0:1]
	v_or_b32_e32 v170, v2, v96
	v_mad_i64_i32 v[168:169], s[8:9], v170, s48, v[4:5]
	global_load_dword v170, v[168:169], off
	s_waitcnt vmcnt(2)
	v_mul_f32_e32 v46, v46, v210
	ds_write_b32 v49, v46
	s_cbranch_vccnz .LBB0_308
	v_readlane_b32 s52, v252, 14
	v_lshl_add_u64 v[46:47], v[2:3], 0, v[8:9]
	v_readlane_b32 s56, v252, 18
	v_readlane_b32 s57, v252, 19
	v_readlane_b32 s53, v252, 15
	v_readlane_b32 s54, v252, 16
	v_lshl_add_u64 v[46:47], v[46:47], 2, s[56:57]
	v_mov_b32_e32 v45, v193
	v_readlane_b32 s55, v252, 17
	v_readlane_b32 s58, v252, 20
	v_readlane_b32 s59, v252, 21
	v_readlane_b32 s60, v252, 22
	v_readlane_b32 s61, v252, 23
	v_readlane_b32 s62, v252, 24
	v_readlane_b32 s63, v252, 25
	v_readlane_b32 s64, v252, 26
	v_readlane_b32 s65, v252, 27
	v_readlane_b32 s66, v252, 28
	v_readlane_b32 s67, v252, 29
.LBB0_308:
	v_add_u32_e32 v49, v7, v95
	v_mov_b32_e32 v46, 1.0
	s_and_b64 vcc, exec, s[0:1]
	v_or_b32_e32 v210, v2, v98
	v_mad_i64_i32 v[208:209], s[8:9], v210, s48, v[4:5]
	global_load_dword v211, v[208:209], off
	s_waitcnt vmcnt(2)
	v_mul_f32_e32 v45, v45, v161
	ds_write_b32 v49, v45
	v_mov_b32_e32 v45, 1.0
	s_cbranch_vccnz .LBB0_310
	v_readlane_b32 s52, v252, 14
	v_lshl_add_u64 v[50:51], v[2:3], 0, v[8:9]
	v_readlane_b32 s56, v252, 18
	v_readlane_b32 s57, v252, 19
	v_readlane_b32 s53, v252, 15
	v_readlane_b32 s54, v252, 16
	v_lshl_add_u64 v[50:51], v[50:51], 2, s[56:57]
	v_mov_b32_e32 v45, v194
	v_readlane_b32 s55, v252, 17
	v_readlane_b32 s58, v252, 20
	v_readlane_b32 s59, v252, 21
	v_readlane_b32 s60, v252, 22
	v_readlane_b32 s61, v252, 23
	v_readlane_b32 s62, v252, 24
	v_readlane_b32 s63, v252, 25
	v_readlane_b32 s64, v252, 26
	v_readlane_b32 s65, v252, 27
	v_readlane_b32 s66, v252, 28
	v_readlane_b32 s67, v252, 29
.LBB0_310:
	v_add_u32_e32 v49, v7, v97
	s_and_b64 vcc, exec, s[0:1]
	v_or_b32_e32 v162, v2, v100
	v_mad_i64_i32 v[160:161], s[8:9], v162, s48, v[4:5]
	global_load_dword v162, v[160:161], off
	s_waitcnt vmcnt(2)
	v_mul_f32_e32 v45, v45, v170
	ds_write_b32 v49, v45
	s_cbranch_vccnz .LBB0_312
	v_readlane_b32 s52, v252, 14
	v_lshl_add_u64 v[46:47], v[2:3], 0, v[8:9]
	v_readlane_b32 s56, v252, 18
	v_readlane_b32 s57, v252, 19
	v_readlane_b32 s53, v252, 15
	v_readlane_b32 s54, v252, 16
	v_lshl_add_u64 v[46:47], v[46:47], 2, s[56:57]
	v_mov_b32_e32 v46, v195
	v_readlane_b32 s55, v252, 17
	v_readlane_b32 s58, v252, 20
	v_readlane_b32 s59, v252, 21
	v_readlane_b32 s60, v252, 22
	v_readlane_b32 s61, v252, 23
	v_readlane_b32 s62, v252, 24
	v_readlane_b32 s63, v252, 25
	v_readlane_b32 s64, v252, 26
	v_readlane_b32 s65, v252, 27
	v_readlane_b32 s66, v252, 28
	v_readlane_b32 s67, v252, 29
.LBB0_312:
	v_add_u32_e32 v49, v7, v99
	v_mov_b32_e32 v45, 1.0
	s_and_b64 vcc, exec, s[0:1]
	v_or_b32_e32 v168, v2, v102
	v_mad_i64_i32 v[168:169], s[8:9], v168, s48, v[4:5]
	global_load_dword v169, v[168:169], off
	s_waitcnt vmcnt(2)
	v_mul_f32_e32 v46, v46, v211
	ds_write_b32 v49, v46
	v_mov_b32_e32 v46, 1.0
	s_cbranch_vccnz .LBB0_314
	v_readlane_b32 s52, v252, 14
	v_lshl_add_u64 v[46:47], v[2:3], 0, v[8:9]
	v_readlane_b32 s56, v252, 18
	v_readlane_b32 s57, v252, 19
	v_readlane_b32 s53, v252, 15
	v_readlane_b32 s54, v252, 16
	v_lshl_add_u64 v[46:47], v[46:47], 2, s[56:57]
	v_mov_b32_e32 v46, v196
	v_readlane_b32 s55, v252, 17
	v_readlane_b32 s58, v252, 20
	v_readlane_b32 s59, v252, 21
	v_readlane_b32 s60, v252, 22
	v_readlane_b32 s61, v252, 23
	v_readlane_b32 s62, v252, 24
	v_readlane_b32 s63, v252, 25
	v_readlane_b32 s64, v252, 26
	v_readlane_b32 s65, v252, 27
	v_readlane_b32 s66, v252, 28
	v_readlane_b32 s67, v252, 29
.LBB0_314:
	v_add_u32_e32 v49, v7, v101
	s_and_b64 vcc, exec, s[0:1]
	v_or_b32_e32 v210, v2, v104
	v_mad_i64_i32 v[208:209], s[8:9], v210, s48, v[4:5]
	global_load_dword v211, v[208:209], off
	s_waitcnt vmcnt(2)
	v_mul_f32_e32 v46, v46, v162
	ds_write_b32 v49, v46
	s_cbranch_vccnz .LBB0_316
	v_readlane_b32 s52, v252, 14
	v_lshl_add_u64 v[46:47], v[2:3], 0, v[8:9]
	v_readlane_b32 s56, v252, 18
	v_readlane_b32 s57, v252, 19
	v_readlane_b32 s53, v252, 15
	v_readlane_b32 s54, v252, 16
	v_lshl_add_u64 v[46:47], v[46:47], 2, s[56:57]
	v_mov_b32_e32 v45, v197
	v_readlane_b32 s55, v252, 17
	v_readlane_b32 s58, v252, 20
	v_readlane_b32 s59, v252, 21
	v_readlane_b32 s60, v252, 22
	v_readlane_b32 s61, v252, 23
	v_readlane_b32 s62, v252, 24
	v_readlane_b32 s63, v252, 25
	v_readlane_b32 s64, v252, 26
	v_readlane_b32 s65, v252, 27
	v_readlane_b32 s66, v252, 28
	v_readlane_b32 s67, v252, 29
.LBB0_316:
	v_add_u32_e32 v49, v7, v103
	v_mov_b32_e32 v46, 1.0
	s_and_b64 vcc, exec, s[0:1]
	v_or_b32_e32 v162, v2, v106
	v_mad_i64_i32 v[160:161], s[8:9], v162, s48, v[4:5]
	global_load_dword v163, v[160:161], off
	s_waitcnt vmcnt(2)
	v_mul_f32_e32 v45, v45, v169
	v_mov_b32_e32 v47, 1.0
	ds_write_b32 v49, v45
	s_cbranch_vccnz .LBB0_318
	v_readlane_b32 s52, v252, 14
	v_lshl_add_u64 v[50:51], v[2:3], 0, v[8:9]
	v_readlane_b32 s56, v252, 18
	v_readlane_b32 s57, v252, 19
	v_readlane_b32 s53, v252, 15
	v_readlane_b32 s54, v252, 16
	v_lshl_add_u64 v[50:51], v[50:51], 2, s[56:57]
	v_mov_b32_e32 v47, v198
	v_readlane_b32 s55, v252, 17
	v_readlane_b32 s58, v252, 20
	v_readlane_b32 s59, v252, 21
	v_readlane_b32 s60, v252, 22
	v_readlane_b32 s61, v252, 23
	v_readlane_b32 s62, v252, 24
	v_readlane_b32 s63, v252, 25
	v_readlane_b32 s64, v252, 26
	v_readlane_b32 s65, v252, 27
	v_readlane_b32 s66, v252, 28
	v_readlane_b32 s67, v252, 29
.LBB0_318:
	v_add_u32_e32 v45, v7, v105
	s_and_b64 vcc, exec, s[0:1]
	v_or_b32_e32 v170, v2, v107
	v_mad_i64_i32 v[168:169], s[8:9], v170, s48, v[4:5]
	global_load_dword v170, v[168:169], off
	s_waitcnt vmcnt(2)
	v_mul_f32_e32 v47, v47, v211
	ds_write_b32 v45, v47
	s_cbranch_vccnz .LBB0_320
	v_readlane_b32 s52, v252, 14
	v_lshl_add_u64 v[46:47], v[2:3], 0, v[8:9]
	v_readlane_b32 s56, v252, 18
	v_readlane_b32 s57, v252, 19
	v_readlane_b32 s53, v252, 15
	v_readlane_b32 s54, v252, 16
	v_lshl_add_u64 v[46:47], v[46:47], 2, s[56:57]
	v_mov_b32_e32 v46, v199
	v_readlane_b32 s55, v252, 17
	v_readlane_b32 s58, v252, 20
	v_readlane_b32 s59, v252, 21
	v_readlane_b32 s60, v252, 22
	v_readlane_b32 s61, v252, 23
	v_readlane_b32 s62, v252, 24
	v_readlane_b32 s63, v252, 25
	v_readlane_b32 s64, v252, 26
	v_readlane_b32 s65, v252, 27
	v_readlane_b32 s66, v252, 28
	v_readlane_b32 s67, v252, 29
.LBB0_320:
	v_mov_b32_e32 v47, 1.0
	s_and_b64 vcc, exec, s[0:1]
	v_or_b32_e32 v210, v2, v108
	v_mad_i64_i32 v[208:209], s[8:9], v210, s48, v[4:5]
	global_load_dword v211, v[208:209], off
	s_waitcnt vmcnt(2)
	v_mul_f32_e32 v46, v46, v163
	ds_write_b32 v45, v46 offset:264
	v_mov_b32_e32 v46, 1.0
	s_cbranch_vccnz .LBB0_322
	v_readlane_b32 s52, v252, 14
	v_lshl_add_u64 v[50:51], v[2:3], 0, v[8:9]
	v_readlane_b32 s56, v252, 18
	v_readlane_b32 s57, v252, 19
	v_readlane_b32 s53, v252, 15
	v_readlane_b32 s54, v252, 16
	v_lshl_add_u64 v[50:51], v[50:51], 2, s[56:57]
	v_mov_b32_e32 v46, v200
	v_readlane_b32 s55, v252, 17
	v_readlane_b32 s58, v252, 20
	v_readlane_b32 s59, v252, 21
	v_readlane_b32 s60, v252, 22
	v_readlane_b32 s61, v252, 23
	v_readlane_b32 s62, v252, 24
	v_readlane_b32 s63, v252, 25
	v_readlane_b32 s64, v252, 26
	v_readlane_b32 s65, v252, 27
	v_readlane_b32 s66, v252, 28
	v_readlane_b32 s67, v252, 29
.LBB0_322:
	s_and_b64 vcc, exec, s[0:1]
	v_or_b32_e32 v162, v2, v109
	v_mad_i64_i32 v[160:161], s[8:9], v162, s48, v[4:5]
	global_load_dword v162, v[160:161], off
	s_waitcnt vmcnt(2)
	v_mul_f32_e32 v46, v46, v170
	ds_write_b32 v45, v46 offset:528
	s_cbranch_vccnz .LBB0_324
	v_readlane_b32 s52, v252, 14
	v_lshl_add_u64 v[46:47], v[2:3], 0, v[8:9]
	v_readlane_b32 s56, v252, 18
	v_readlane_b32 s57, v252, 19
	v_readlane_b32 s53, v252, 15
	v_readlane_b32 s54, v252, 16
	v_lshl_add_u64 v[46:47], v[46:47], 2, s[56:57]
	v_mov_b32_e32 v47, v201
	v_readlane_b32 s55, v252, 17
	v_readlane_b32 s58, v252, 20
	v_readlane_b32 s59, v252, 21
	v_readlane_b32 s60, v252, 22
	v_readlane_b32 s61, v252, 23
	v_readlane_b32 s62, v252, 24
	v_readlane_b32 s63, v252, 25
	v_readlane_b32 s64, v252, 26
	v_readlane_b32 s65, v252, 27
	v_readlane_b32 s66, v252, 28
	v_readlane_b32 s67, v252, 29
.LBB0_324:
	v_mov_b32_e32 v46, 1.0
	s_and_b64 vcc, exec, s[0:1]
	v_or_b32_e32 v170, v2, v110
	v_mad_i64_i32 v[168:169], s[8:9], v170, s48, v[4:5]
	global_load_dword v170, v[168:169], off
	s_waitcnt vmcnt(2)
	v_mul_f32_e32 v47, v47, v211
	ds_write_b32 v45, v47 offset:792
	v_mov_b32_e32 v47, 1.0
	s_cbranch_vccnz .LBB0_326
	v_readlane_b32 s52, v252, 14
	v_lshl_add_u64 v[50:51], v[2:3], 0, v[8:9]
	v_readlane_b32 s56, v252, 18
	v_readlane_b32 s57, v252, 19
	v_readlane_b32 s53, v252, 15
	v_readlane_b32 s54, v252, 16
	v_lshl_add_u64 v[50:51], v[50:51], 2, s[56:57]
	v_mov_b32_e32 v47, v202
	v_readlane_b32 s55, v252, 17
	v_readlane_b32 s58, v252, 20
	v_readlane_b32 s59, v252, 21
	v_readlane_b32 s60, v252, 22
	v_readlane_b32 s61, v252, 23
	v_readlane_b32 s62, v252, 24
	v_readlane_b32 s63, v252, 25
	v_readlane_b32 s64, v252, 26
	v_readlane_b32 s65, v252, 27
	v_readlane_b32 s66, v252, 28
	v_readlane_b32 s67, v252, 29
.LBB0_326:
	s_and_b64 vcc, exec, s[0:1]
	s_waitcnt vmcnt(1)
	v_mul_f32_e32 v47, v47, v162
	ds_write_b32 v45, v47 offset:1056
	s_cbranch_vccnz .LBB0_328
	v_readlane_b32 s52, v252, 14
	v_lshl_add_u64 v[46:47], v[2:3], 0, v[8:9]
	v_readlane_b32 s56, v252, 18
	v_readlane_b32 s57, v252, 19
	v_readlane_b32 s53, v252, 15
	v_readlane_b32 s54, v252, 16
	v_lshl_add_u64 v[46:47], v[46:47], 2, s[56:57]
	v_mov_b32_e32 v46, v203
	v_readlane_b32 s55, v252, 17
	v_readlane_b32 s58, v252, 20
	v_readlane_b32 s59, v252, 21
	v_readlane_b32 s60, v252, 22
	v_readlane_b32 s61, v252, 23
	v_readlane_b32 s62, v252, 24
	v_readlane_b32 s63, v252, 25
	v_readlane_b32 s64, v252, 26
	v_readlane_b32 s65, v252, 27
	v_readlane_b32 s66, v252, 28
	v_readlane_b32 s67, v252, 29
.LBB0_328:
	s_and_b64 vcc, exec, s[0:1]
	v_or_b32_e32 v210, v2, v111
	v_mad_i64_i32 v[208:209], s[0:1], v210, s48, v[4:5]
	global_load_dword v210, v[208:209], off
	s_waitcnt vmcnt(1)
	v_mul_f32_e32 v46, v46, v170
	ds_write_b32 v45, v46 offset:1320
	s_cbranch_vccnz .LBB0_330
	v_readlane_b32 s52, v252, 14
	v_lshl_add_u64 v[46:47], v[2:3], 0, v[8:9]
	v_readlane_b32 s56, v252, 18
	v_readlane_b32 s57, v252, 19
	v_readlane_b32 s53, v252, 15
	v_readlane_b32 s54, v252, 16
	v_lshl_add_u64 v[46:47], v[46:47], 2, s[56:57]
	global_load_dword v46, v[46:47], off offset:240
	v_readlane_b32 s55, v252, 17
	v_readlane_b32 s58, v252, 20
	v_readlane_b32 s59, v252, 21
	v_readlane_b32 s60, v252, 22
	v_readlane_b32 s61, v252, 23
	v_readlane_b32 s62, v252, 24
	v_readlane_b32 s63, v252, 25
	v_readlane_b32 s64, v252, 26
	v_readlane_b32 s65, v252, 27
	v_readlane_b32 s66, v252, 28
	v_readlane_b32 s67, v252, 29
	s_branch .LBB0_331

.LBB0_331:
	v_readlane_b32 s0, v250, 38
	v_readlane_b32 s1, v250, 39
	s_and_b64 vcc, exec, s[0:1]
	s_waitcnt vmcnt(0)
	v_mul_f32_e32 v46, v46, v210
	ds_write_b32 v45, v46 offset:1584
	s_cbranch_vccz .LBB0_333
	v_readlane_b32 s52, v252, 14
	v_lshl_add_u64 v[46:47], v[2:3], 0, v[8:9]
	v_readlane_b32 s56, v252, 18
	v_readlane_b32 s57, v252, 19
	v_readlane_b32 s53, v252, 15
	v_readlane_b32 s54, v252, 16
	v_lshl_add_u64 v[46:47], v[46:47], 2, s[56:57]
	global_load_dword v46, v[46:47], off offset:248
	v_readlane_b32 s55, v252, 17
	v_readlane_b32 s58, v252, 20
	v_readlane_b32 s59, v252, 21
	v_readlane_b32 s60, v252, 22
	v_readlane_b32 s61, v252, 23
	v_readlane_b32 s62, v252, 24
	v_readlane_b32 s63, v252, 25
	v_readlane_b32 s64, v252, 26
	v_readlane_b32 s65, v252, 27
	v_readlane_b32 s66, v252, 28
	v_readlane_b32 s67, v252, 29
	s_cbranch_execnz .LBB0_115
	s_branch .LBB0_114

.LBB0_360:
	v_lshlrev_b16_e32 v8, 6, v8
	v_ashrrev_i32_e32 v15, 31, v14
	v_sub_u16_e32 v5, v5, v8
	v_mov_b32_e32 v8, 5
	v_lshlrev_b64 v[16:17], 23, v[14:15]
	v_lshlrev_b32_sdwa v8, v8, sext(v5) dst_sel:DWORD dst_unused:UNUSED_PAD src0_sel:DWORD src1_sel:WORD_0
	v_lshl_add_u64 v[16:17], s[72:73], 0, v[16:17]
	v_ashrrev_i32_e32 v9, 31, v8
	v_lshl_add_u64 v[16:17], v[8:9], 2, v[16:17]
	v_mov_b32_e32 v5, v0
	v_lshl_add_u64 v[16:17], v[16:17], 0, v[4:5]
	v_lshlrev_b64 v[20:21], 13, v[20:21]
	v_lshl_add_u64 v[20:21], v[16:17], 0, v[20:21]
	global_load_dword v5, v[20:21], off
	s_and_b64 vcc, exec, s[38:39]
	v_or_b32_e32 v208, v12, v11
	v_ashrrev_i32_e32 v209, 31, v208
	v_lshlrev_b64 v[208:209], 13, v[208:209]
	v_lshl_add_u64 v[208:209], v[16:17], 0, v[208:209]
	global_load_dword v210, v[208:209], off
	v_or_b32_e32 v160, v12, v22
	v_ashrrev_i32_e32 v161, 31, v160
	v_lshlrev_b64 v[160:161], 13, v[160:161]
	v_lshl_add_u64 v[160:161], v[16:17], 0, v[160:161]
	global_load_dword v162, v[160:161], off
	s_waitcnt vmcnt(2)
	v_mul_f32_e32 v5, v13, v5
	v_ashrrev_i32_e32 v13, 31, v12
	ds_write_b32 v56, v5
	s_cbranch_vccnz .LBB0_362
	v_lshl_add_u64 v[20:21], v[12:13], 0, v[2:3]
	v_lshl_add_u64 v[20:21], v[20:21], 2, v[18:19]
	global_load_dword v176, v[20:21], off offset:16
	global_load_dword v177, v[20:21], off offset:24
	global_load_dword v178, v[20:21], off offset:32
	global_load_dword v179, v[20:21], off offset:40
	global_load_dword v180, v[20:21], off offset:48
	global_load_dword v181, v[20:21], off offset:56
	global_load_dword v182, v[20:21], off offset:64
	global_load_dword v183, v[20:21], off offset:72
	global_load_dword v184, v[20:21], off offset:80
	global_load_dword v185, v[20:21], off offset:88
	global_load_dword v186, v[20:21], off offset:96
	global_load_dword v187, v[20:21], off offset:104
	global_load_dword v188, v[20:21], off offset:112
	global_load_dword v189, v[20:21], off offset:120
	global_load_dword v190, v[20:21], off offset:128
	global_load_dword v191, v[20:21], off offset:136
	global_load_dword v192, v[20:21], off offset:144
	global_load_dword v193, v[20:21], off offset:152
	global_load_dword v194, v[20:21], off offset:160
	global_load_dword v195, v[20:21], off offset:168
	global_load_dword v196, v[20:21], off offset:176
	global_load_dword v197, v[20:21], off offset:184
	global_load_dword v198, v[20:21], off offset:192
	global_load_dword v199, v[20:21], off offset:200
	global_load_dword v200, v[20:21], off offset:208
	global_load_dword v201, v[20:21], off offset:216
	global_load_dword v202, v[20:21], off offset:224
	global_load_dword v203, v[20:21], off offset:232
	global_load_dword v7, v[20:21], off offset:8
.LBB0_362:
	v_mov_b32_e32 v5, 1.0
	s_and_b64 vcc, exec, s[38:39]
	v_or_b32_e32 v168, v12, v23
	v_ashrrev_i32_e32 v169, 31, v168
	v_lshlrev_b64 v[168:169], 13, v[168:169]
	v_lshl_add_u64 v[168:169], v[16:17], 0, v[168:169]
	global_load_dword v170, v[168:169], off
	s_waitcnt vmcnt(1)
	v_mul_f32_e32 v7, v7, v210
	ds_write_b32 v56, v7 offset:264
	v_mov_b32_e32 v7, 1.0
	s_cbranch_vccnz .LBB0_364
	v_lshl_add_u64 v[20:21], v[12:13], 0, v[2:3]
	v_lshl_add_u64 v[20:21], v[20:21], 2, v[18:19]
	v_mov_b32_e32 v7, v176
.LBB0_364:
	s_and_b64 vcc, exec, s[38:39]
	v_or_b32_e32 v208, v12, v24
	v_ashrrev_i32_e32 v209, 31, v208
	v_lshlrev_b64 v[208:209], 13, v[208:209]
	v_lshl_add_u64 v[208:209], v[16:17], 0, v[208:209]
	global_load_dword v210, v[208:209], off
	s_waitcnt vmcnt(2)
	v_mul_f32_e32 v7, v7, v162
	ds_write_b32 v56, v7 offset:528
	s_cbranch_vccnz .LBB0_366
	v_lshl_add_u64 v[20:21], v[12:13], 0, v[2:3]
	v_lshl_add_u64 v[20:21], v[20:21], 2, v[18:19]
	v_mov_b32_e32 v5, v177
.LBB0_366:
	v_mov_b32_e32 v7, 1.0
	s_and_b64 vcc, exec, s[38:39]
	v_or_b32_e32 v160, v12, v25
	v_ashrrev_i32_e32 v161, 31, v160
	v_lshlrev_b64 v[160:161], 13, v[160:161]
	v_lshl_add_u64 v[160:161], v[16:17], 0, v[160:161]
	global_load_dword v162, v[160:161], off
	s_waitcnt vmcnt(2)
	v_mul_f32_e32 v5, v5, v170
	ds_write_b32 v56, v5 offset:792
	v_mov_b32_e32 v5, 1.0
	s_cbranch_vccnz .LBB0_368
	v_lshl_add_u64 v[20:21], v[12:13], 0, v[2:3]
	v_lshl_add_u64 v[20:21], v[20:21], 2, v[18:19]
	v_mov_b32_e32 v5, v178
.LBB0_368:
	s_and_b64 vcc, exec, s[38:39]
	v_or_b32_e32 v168, v12, v26
	v_ashrrev_i32_e32 v169, 31, v168
	v_lshlrev_b64 v[168:169], 13, v[168:169]
	v_lshl_add_u64 v[168:169], v[16:17], 0, v[168:169]
	global_load_dword v170, v[168:169], off
	s_waitcnt vmcnt(2)
	v_mul_f32_e32 v5, v5, v210
	ds_write_b32 v56, v5 offset:1056
	s_cbranch_vccnz .LBB0_370
	v_lshl_add_u64 v[20:21], v[12:13], 0, v[2:3]
	v_lshl_add_u64 v[20:21], v[20:21], 2, v[18:19]
	v_mov_b32_e32 v7, v179
.LBB0_370:
	v_mov_b32_e32 v5, 1.0
	s_and_b64 vcc, exec, s[38:39]
	v_or_b32_e32 v208, v12, v27
	v_ashrrev_i32_e32 v209, 31, v208
	v_lshlrev_b64 v[208:209], 13, v[208:209]
	v_lshl_add_u64 v[208:209], v[16:17], 0, v[208:209]
	global_load_dword v210, v[208:209], off
	s_waitcnt vmcnt(2)
	v_mul_f32_e32 v7, v7, v162
	ds_write_b32 v56, v7 offset:1320
	v_mov_b32_e32 v7, 1.0
	s_cbranch_vccnz .LBB0_372
	v_lshl_add_u64 v[20:21], v[12:13], 0, v[2:3]
	v_lshl_add_u64 v[20:21], v[20:21], 2, v[18:19]
	v_mov_b32_e32 v7, v180
.LBB0_372:
	s_and_b64 vcc, exec, s[38:39]
	v_or_b32_e32 v160, v12, v28
	v_ashrrev_i32_e32 v161, 31, v160
	v_lshlrev_b64 v[160:161], 13, v[160:161]
	v_lshl_add_u64 v[160:161], v[16:17], 0, v[160:161]
	global_load_dword v162, v[160:161], off
	s_waitcnt vmcnt(2)
	v_mul_f32_e32 v7, v7, v170
	ds_write_b32 v56, v7 offset:1584
	s_cbranch_vccnz .LBB0_374
	v_lshl_add_u64 v[20:21], v[12:13], 0, v[2:3]
	v_lshl_add_u64 v[20:21], v[20:21], 2, v[18:19]
	v_mov_b32_e32 v5, v181
.LBB0_374:
	v_mov_b32_e32 v7, 1.0
	s_and_b64 vcc, exec, s[38:39]
	v_or_b32_e32 v168, v12, v29
	v_ashrrev_i32_e32 v169, 31, v168
	v_lshlrev_b64 v[168:169], 13, v[168:169]
	v_lshl_add_u64 v[168:169], v[16:17], 0, v[168:169]
	global_load_dword v170, v[168:169], off
	s_waitcnt vmcnt(2)
	v_mul_f32_e32 v5, v5, v210
	ds_write_b32 v56, v5 offset:1848
	v_mov_b32_e32 v5, 1.0
	s_cbranch_vccnz .LBB0_376
	v_lshl_add_u64 v[20:21], v[12:13], 0, v[2:3]
	v_lshl_add_u64 v[20:21], v[20:21], 2, v[18:19]
	v_mov_b32_e32 v5, v182
.LBB0_376:
	s_and_b64 vcc, exec, s[38:39]
	v_or_b32_e32 v208, v12, v30
	v_ashrrev_i32_e32 v209, 31, v208
	v_lshlrev_b64 v[208:209], 13, v[208:209]
	v_lshl_add_u64 v[208:209], v[16:17], 0, v[208:209]
	global_load_dword v210, v[208:209], off
	s_waitcnt vmcnt(2)
	v_mul_f32_e32 v5, v5, v162
	ds_write_b32 v56, v5 offset:2112
	s_cbranch_vccnz .LBB0_378
	v_lshl_add_u64 v[20:21], v[12:13], 0, v[2:3]
	v_lshl_add_u64 v[20:21], v[20:21], 2, v[18:19]
	v_mov_b32_e32 v7, v183
.LBB0_378:
	v_mov_b32_e32 v5, 1.0
	s_and_b64 vcc, exec, s[38:39]
	v_or_b32_e32 v160, v12, v31
	v_ashrrev_i32_e32 v161, 31, v160
	v_lshlrev_b64 v[160:161], 13, v[160:161]
	v_lshl_add_u64 v[160:161], v[16:17], 0, v[160:161]
	global_load_dword v162, v[160:161], off
	s_waitcnt vmcnt(2)
	v_mul_f32_e32 v7, v7, v170
	ds_write_b32 v56, v7 offset:2376
	v_mov_b32_e32 v7, 1.0
	s_cbranch_vccnz .LBB0_380
	v_lshl_add_u64 v[20:21], v[12:13], 0, v[2:3]
	v_lshl_add_u64 v[20:21], v[20:21], 2, v[18:19]
	v_mov_b32_e32 v7, v184
.LBB0_380:
	s_and_b64 vcc, exec, s[38:39]
	v_or_b32_e32 v168, v12, v32
	v_ashrrev_i32_e32 v169, 31, v168
	v_lshlrev_b64 v[168:169], 13, v[168:169]
	v_lshl_add_u64 v[168:169], v[16:17], 0, v[168:169]
	global_load_dword v170, v[168:169], off
	s_waitcnt vmcnt(2)
	v_mul_f32_e32 v7, v7, v210
	ds_write_b32 v56, v7 offset:2640
	s_cbranch_vccnz .LBB0_382
	v_lshl_add_u64 v[20:21], v[12:13], 0, v[2:3]
	v_lshl_add_u64 v[20:21], v[20:21], 2, v[18:19]
	v_mov_b32_e32 v5, v185
.LBB0_382:
	v_mov_b32_e32 v7, 1.0
	s_and_b64 vcc, exec, s[38:39]
	v_or_b32_e32 v208, v12, v33
	v_ashrrev_i32_e32 v209, 31, v208
	v_lshlrev_b64 v[208:209], 13, v[208:209]
	v_lshl_add_u64 v[208:209], v[16:17], 0, v[208:209]
	global_load_dword v210, v[208:209], off
	s_waitcnt vmcnt(2)
	v_mul_f32_e32 v5, v5, v162
	ds_write_b32 v56, v5 offset:2904
	v_mov_b32_e32 v5, 1.0
	s_cbranch_vccnz .LBB0_384
	v_lshl_add_u64 v[20:21], v[12:13], 0, v[2:3]
	v_lshl_add_u64 v[20:21], v[20:21], 2, v[18:19]
	v_mov_b32_e32 v5, v186
.LBB0_384:
	s_and_b64 vcc, exec, s[38:39]
	v_or_b32_e32 v160, v12, v34
	v_ashrrev_i32_e32 v161, 31, v160
	v_lshlrev_b64 v[160:161], 13, v[160:161]
	v_lshl_add_u64 v[160:161], v[16:17], 0, v[160:161]
	global_load_dword v162, v[160:161], off
	s_waitcnt vmcnt(2)
	v_mul_f32_e32 v5, v5, v170
	ds_write_b32 v56, v5 offset:3168
	s_cbranch_vccnz .LBB0_386
	v_lshl_add_u64 v[20:21], v[12:13], 0, v[2:3]
	v_lshl_add_u64 v[20:21], v[20:21], 2, v[18:19]
	v_mov_b32_e32 v7, v187
.LBB0_386:
	v_mov_b32_e32 v5, 1.0
	s_and_b64 vcc, exec, s[38:39]
	v_or_b32_e32 v168, v12, v35
	v_ashrrev_i32_e32 v169, 31, v168
	v_lshlrev_b64 v[168:169], 13, v[168:169]
	v_lshl_add_u64 v[168:169], v[16:17], 0, v[168:169]
	global_load_dword v170, v[168:169], off
	s_waitcnt vmcnt(2)
	v_mul_f32_e32 v7, v7, v210
	ds_write_b32 v56, v7 offset:3432
	v_mov_b32_e32 v7, 1.0
	s_cbranch_vccnz .LBB0_388
	v_lshl_add_u64 v[20:21], v[12:13], 0, v[2:3]
	v_lshl_add_u64 v[20:21], v[20:21], 2, v[18:19]
	v_mov_b32_e32 v7, v188
.LBB0_388:
	s_and_b64 vcc, exec, s[38:39]
	v_or_b32_e32 v208, v12, v36
	v_ashrrev_i32_e32 v209, 31, v208
	v_lshlrev_b64 v[208:209], 13, v[208:209]
	v_lshl_add_u64 v[208:209], v[16:17], 0, v[208:209]
	global_load_dword v210, v[208:209], off
	s_waitcnt vmcnt(2)
	v_mul_f32_e32 v7, v7, v162
	ds_write_b32 v56, v7 offset:3696
	s_cbranch_vccnz .LBB0_390
	v_lshl_add_u64 v[20:21], v[12:13], 0, v[2:3]
	v_lshl_add_u64 v[20:21], v[20:21], 2, v[18:19]
	v_mov_b32_e32 v5, v189
.LBB0_390:
	v_mov_b32_e32 v7, 1.0
	s_and_b64 vcc, exec, s[38:39]
	v_or_b32_e32 v160, v12, v37
	v_ashrrev_i32_e32 v161, 31, v160
	v_lshlrev_b64 v[160:161], 13, v[160:161]
	v_lshl_add_u64 v[160:161], v[16:17], 0, v[160:161]
	global_load_dword v162, v[160:161], off
	s_waitcnt vmcnt(2)
	v_mul_f32_e32 v5, v5, v170
	ds_write_b32 v56, v5 offset:3960
	v_mov_b32_e32 v5, 1.0
	s_cbranch_vccnz .LBB0_392
	v_lshl_add_u64 v[20:21], v[12:13], 0, v[2:3]
	v_lshl_add_u64 v[20:21], v[20:21], 2, v[18:19]
	v_mov_b32_e32 v5, v190
.LBB0_392:
	s_and_b64 vcc, exec, s[38:39]
	v_or_b32_e32 v168, v12, v38
	v_ashrrev_i32_e32 v169, 31, v168
	v_lshlrev_b64 v[168:169], 13, v[168:169]
	v_lshl_add_u64 v[168:169], v[16:17], 0, v[168:169]
	global_load_dword v170, v[168:169], off
	s_waitcnt vmcnt(2)
	v_mul_f32_e32 v5, v5, v210
	ds_write_b32 v56, v5 offset:4224
	s_cbranch_vccnz .LBB0_394
	v_lshl_add_u64 v[20:21], v[12:13], 0, v[2:3]
	v_lshl_add_u64 v[20:21], v[20:21], 2, v[18:19]
	v_mov_b32_e32 v7, v191
.LBB0_394:
	v_mov_b32_e32 v5, 1.0
	s_and_b64 vcc, exec, s[38:39]
	v_or_b32_e32 v208, v12, v39
	v_ashrrev_i32_e32 v209, 31, v208
	v_lshlrev_b64 v[208:209], 13, v[208:209]
	v_lshl_add_u64 v[208:209], v[16:17], 0, v[208:209]
	global_load_dword v210, v[208:209], off
	s_waitcnt vmcnt(2)
	v_mul_f32_e32 v7, v7, v162
	ds_write_b32 v56, v7 offset:4488
	v_mov_b32_e32 v7, 1.0
	s_cbranch_vccnz .LBB0_396
	v_lshl_add_u64 v[20:21], v[12:13], 0, v[2:3]
	v_lshl_add_u64 v[20:21], v[20:21], 2, v[18:19]
	v_mov_b32_e32 v7, v192
.LBB0_396:
	s_and_b64 vcc, exec, s[38:39]
	v_or_b32_e32 v160, v12, v40
	v_ashrrev_i32_e32 v161, 31, v160
	v_lshlrev_b64 v[160:161], 13, v[160:161]
	v_lshl_add_u64 v[160:161], v[16:17], 0, v[160:161]
	global_load_dword v162, v[160:161], off
	s_waitcnt vmcnt(2)
	v_mul_f32_e32 v7, v7, v170
	ds_write_b32 v56, v7 offset:4752
	s_cbranch_vccnz .LBB0_398
	v_lshl_add_u64 v[20:21], v[12:13], 0, v[2:3]
	v_lshl_add_u64 v[20:21], v[20:21], 2, v[18:19]
	v_mov_b32_e32 v5, v193
.LBB0_398:
	v_mov_b32_e32 v7, 1.0
	s_and_b64 vcc, exec, s[38:39]
	v_or_b32_e32 v168, v12, v41
	v_ashrrev_i32_e32 v169, 31, v168
	v_lshlrev_b64 v[168:169], 13, v[168:169]
	v_lshl_add_u64 v[168:169], v[16:17], 0, v[168:169]
	global_load_dword v170, v[168:169], off
	s_waitcnt vmcnt(2)
	v_mul_f32_e32 v5, v5, v210
	ds_write_b32 v56, v5 offset:5016
	v_mov_b32_e32 v5, 1.0
	s_cbranch_vccnz .LBB0_400
	v_lshl_add_u64 v[20:21], v[12:13], 0, v[2:3]
	v_lshl_add_u64 v[20:21], v[20:21], 2, v[18:19]
	v_mov_b32_e32 v5, v194
.LBB0_400:
	s_and_b64 vcc, exec, s[38:39]
	v_or_b32_e32 v208, v12, v42
	v_ashrrev_i32_e32 v209, 31, v208
	v_lshlrev_b64 v[208:209], 13, v[208:209]
	v_lshl_add_u64 v[208:209], v[16:17], 0, v[208:209]
	global_load_dword v210, v[208:209], off
	s_waitcnt vmcnt(2)
	v_mul_f32_e32 v5, v5, v162
	ds_write_b32 v56, v5 offset:5280
	s_cbranch_vccnz .LBB0_402
	v_lshl_add_u64 v[20:21], v[12:13], 0, v[2:3]
	v_lshl_add_u64 v[20:21], v[20:21], 2, v[18:19]
	v_mov_b32_e32 v7, v195
.LBB0_402:
	v_mov_b32_e32 v5, 1.0
	s_and_b64 vcc, exec, s[38:39]
	v_or_b32_e32 v160, v12, v43
	v_ashrrev_i32_e32 v161, 31, v160
	v_lshlrev_b64 v[160:161], 13, v[160:161]
	v_lshl_add_u64 v[160:161], v[16:17], 0, v[160:161]
	global_load_dword v162, v[160:161], off
	s_waitcnt vmcnt(2)
	v_mul_f32_e32 v7, v7, v170
	ds_write_b32 v56, v7 offset:5544
	v_mov_b32_e32 v7, 1.0
	s_cbranch_vccnz .LBB0_404
	v_lshl_add_u64 v[20:21], v[12:13], 0, v[2:3]
	v_lshl_add_u64 v[20:21], v[20:21], 2, v[18:19]
	v_mov_b32_e32 v7, v196
.LBB0_404:
	s_and_b64 vcc, exec, s[38:39]
	v_or_b32_e32 v168, v12, v44
	v_ashrrev_i32_e32 v169, 31, v168
	v_lshlrev_b64 v[168:169], 13, v[168:169]
	v_lshl_add_u64 v[168:169], v[16:17], 0, v[168:169]
	global_load_dword v170, v[168:169], off
	s_waitcnt vmcnt(2)
	v_mul_f32_e32 v7, v7, v210
	ds_write_b32 v56, v7 offset:5808
	s_cbranch_vccnz .LBB0_406
	v_lshl_add_u64 v[20:21], v[12:13], 0, v[2:3]
	v_lshl_add_u64 v[20:21], v[20:21], 2, v[18:19]
	v_mov_b32_e32 v5, v197
.LBB0_406:
	v_mov_b32_e32 v7, 1.0
	s_and_b64 vcc, exec, s[38:39]
	v_or_b32_e32 v208, v12, v45
	v_ashrrev_i32_e32 v209, 31, v208
	v_lshlrev_b64 v[208:209], 13, v[208:209]
	v_lshl_add_u64 v[208:209], v[16:17], 0, v[208:209]
	global_load_dword v210, v[208:209], off
	s_waitcnt vmcnt(2)
	v_mul_f32_e32 v5, v5, v162
	ds_write_b32 v56, v5 offset:6072
	v_mov_b32_e32 v5, 1.0
	s_cbranch_vccnz .LBB0_408
	v_lshl_add_u64 v[20:21], v[12:13], 0, v[2:3]
	v_lshl_add_u64 v[20:21], v[20:21], 2, v[18:19]
	v_mov_b32_e32 v5, v198
.LBB0_408:
	s_and_b64 vcc, exec, s[38:39]
	v_or_b32_e32 v160, v12, v46
	v_ashrrev_i32_e32 v161, 31, v160
	v_lshlrev_b64 v[160:161], 13, v[160:161]
	v_lshl_add_u64 v[160:161], v[16:17], 0, v[160:161]
	global_load_dword v162, v[160:161], off
	s_waitcnt vmcnt(2)
	v_mul_f32_e32 v5, v5, v170
	ds_write_b32 v56, v5 offset:6336
	s_cbranch_vccnz .LBB0_410
	v_lshl_add_u64 v[20:21], v[12:13], 0, v[2:3]
	v_lshl_add_u64 v[20:21], v[20:21], 2, v[18:19]
	v_mov_b32_e32 v7, v199
.LBB0_410:
	v_mov_b32_e32 v5, 1.0
	s_and_b64 vcc, exec, s[38:39]
	v_or_b32_e32 v168, v12, v47
	v_ashrrev_i32_e32 v169, 31, v168
	v_lshlrev_b64 v[168:169], 13, v[168:169]
	v_lshl_add_u64 v[168:169], v[16:17], 0, v[168:169]
	global_load_dword v170, v[168:169], off
	s_waitcnt vmcnt(2)
	v_mul_f32_e32 v7, v7, v210
	ds_write_b32 v56, v7 offset:6600
	v_mov_b32_e32 v7, 1.0
	s_cbranch_vccnz .LBB0_412
	v_lshl_add_u64 v[20:21], v[12:13], 0, v[2:3]
	v_lshl_add_u64 v[20:21], v[20:21], 2, v[18:19]
	v_mov_b32_e32 v7, v200
.LBB0_412:
	s_and_b64 vcc, exec, s[38:39]
	v_or_b32_e32 v208, v12, v48
	v_ashrrev_i32_e32 v209, 31, v208
	v_lshlrev_b64 v[208:209], 13, v[208:209]
	v_lshl_add_u64 v[208:209], v[16:17], 0, v[208:209]
	global_load_dword v210, v[208:209], off
	s_waitcnt vmcnt(2)
	v_mul_f32_e32 v7, v7, v162
	ds_write_b32 v56, v7 offset:6864
	s_cbranch_vccnz .LBB0_414
	v_lshl_add_u64 v[20:21], v[12:13], 0, v[2:3]
	v_lshl_add_u64 v[20:21], v[20:21], 2, v[18:19]
	v_mov_b32_e32 v5, v201
.LBB0_414:
	v_mov_b32_e32 v7, 1.0
	s_and_b64 vcc, exec, s[38:39]
	v_or_b32_e32 v160, v12, v49
	v_ashrrev_i32_e32 v161, 31, v160
	v_lshlrev_b64 v[160:161], 13, v[160:161]
	v_lshl_add_u64 v[160:161], v[16:17], 0, v[160:161]
	global_load_dword v162, v[160:161], off
	s_waitcnt vmcnt(2)
	v_mul_f32_e32 v5, v5, v170
	ds_write_b32 v56, v5 offset:7128
	v_mov_b32_e32 v5, 1.0
	s_cbranch_vccnz .LBB0_416
	v_lshl_add_u64 v[20:21], v[12:13], 0, v[2:3]
	v_lshl_add_u64 v[20:21], v[20:21], 2, v[18:19]
	v_mov_b32_e32 v5, v202
.LBB0_416:
	s_and_b64 vcc, exec, s[38:39]
	v_or_b32_e32 v168, v12, v50
	v_ashrrev_i32_e32 v169, 31, v168
	v_lshlrev_b64 v[168:169], 13, v[168:169]
	v_lshl_add_u64 v[168:169], v[16:17], 0, v[168:169]
	global_load_dword v170, v[168:169], off
	s_waitcnt vmcnt(2)
	v_mul_f32_e32 v5, v5, v210
	ds_write_b32 v56, v5 offset:7392
	s_cbranch_vccnz .LBB0_418
	v_lshl_add_u64 v[20:21], v[12:13], 0, v[2:3]
	v_lshl_add_u64 v[20:21], v[20:21], 2, v[18:19]
	v_mov_b32_e32 v7, v203
.LBB0_418:
	s_and_b64 vcc, exec, s[38:39]
	s_waitcnt vmcnt(1)
	v_mul_f32_e32 v5, v7, v162
	ds_write_b32 v56, v5 offset:7656
	s_cbranch_vccnz .LBB0_420
	v_lshl_add_u64 v[20:21], v[12:13], 0, v[2:3]
	v_lshl_add_u64 v[20:21], v[20:21], 2, v[18:19]
	global_load_dword v5, v[20:21], off offset:240
	s_branch .LBB0_421

.LBB0_421:
	s_and_b64 vcc, exec, s[92:93]
	s_waitcnt vmcnt(0)
	v_mul_f32_e32 v5, v5, v170
	ds_write_b32 v56, v5 offset:7920
	s_cbranch_vccz .LBB0_423
	v_lshl_add_u64 v[20:21], v[12:13], 0, v[2:3]
	v_lshl_add_u64 v[18:19], v[20:21], 2, v[18:19]
	global_load_dword v5, v[18:19], off offset:248
	s_cbranch_execnz .LBB0_357
	s_branch .LBB0_356
